# v4: v3 + P9 epilogue base-tile loads issued together (12+4) + fused P12 K-loop rebalance
# speedup vs baseline: 1.0142x; 1.0041x over previous
; #define PG8_STAGE(bufoff, gbase, voff) do { _Pragma("unroll") for (int _i = 0; _i < 2; ++_i) \
;         __builtin_amdgcn_global_load_lds((const unsigned*)((const char*)(gbase) + (voff)[_i]), (PG8_LAS unsigned*)(lds + (bufoff) + ldsw + _i * 8192), 16, 0, 0); } while (0)
; #define PG8_LDA(dst, b, h) do { _Pragma("unroll") for (int m = 0; m < 4; ++m) _Pragma("unroll") for (int k = 0; k < 2; ++k) dst[m][k] = *(const PG8_LAS bf16x8*)(lds + PG8_SA(b, h) + aoff + m * 2048 + k * 1024); } while (0)
; #define PG8_LDB(dst, b, h) do { _Pragma("unroll") for (int n = 0; n < 2; ++n) _Pragma("unroll") for (int k = 0; k < 2; ++k) dst[n][k] = *(const PG8_LAS bf16x8*)(lds + PG8_SB(b, h) + boff + n * 2048 + k * 1024); } while (0)
; template <class Epi, class Sched, bool ALIGN_EPI = false, bool SP2 = false>
; __device__ __forceinline__ void gemm_phase(PG8_LAS unsigned char* lds, const Gemm g, const Sched& S, const Epi& E) {
;     ...
;         for (; t < tend; t += 2) {
;             const bool last = (t == nt - 2);
;             const char* a1 = cA + (size_t)(t + 1) * kstep;
;             const char* a2 = last ? nA : cA + (size_t)(t + 2) * kstep; const char* b2 = last ? nB : cB + (size_t)(t + 2) * kstep;
;             const char* a3 = a2 + kstep; const char* b3 = b2 + kstep;
;             if (last && has_next) S.a_ready(nxt);
;             if constexpr (SP2) {
;             PG8_LDB(B0, 0, 0); PG8_LDB(B1, 0, 1); PG8_SCHED; PG8_LDA(At, 0, 0); PG8_STAGE(PG8_SA(1, 1), a1 + hstep, voffA);
;             PG8_WAIT_V(8); PG8_WAIT_L(0); PG8_BAR; PG8_MMA(0, 0, At, B0); PG8_MMA(0, 1, At, B1); PG8_BAR; PG8_SCHED;
;             PG8_LDA(At, 0, 1); PG8_STAGE(PG8_SB(0, 0), b2, voffB); PG8_STAGE(PG8_SB(0, 1), b2 + hstep, voffB); PG8_STAGE(PG8_SA(0, 0), a2, voffA);
;             PG8_WAIT_V(8); PG8_WAIT_L(0); PG8_BAR; PG8_MMA(1, 0, At, B0); PG8_MMA(1, 1, At, B1); PG8_BAR; PG8_SCHED;
;             PG8_LDB(B0, 1, 0); PG8_LDB(B1, 1, 1); PG8_SCHED; PG8_LDA(At, 1, 0); PG8_STAGE(PG8_SA(0, 1), a2 + hstep, voffA);
;             PG8_WAIT_V(8); PG8_WAIT_L(0); PG8_BAR; PG8_MMA(0, 0, At, B0); PG8_MMA(0, 1, At, B1); PG8_BAR; PG8_SCHED;
;             PG8_LDA(At, 1, 1); PG8_STAGE(PG8_SB(1, 0), b3, voffB); PG8_STAGE(PG8_SB(1, 1), b3 + hstep, voffB); PG8_STAGE(PG8_SA(1, 0), a3, voffA);
;             PG8_WAIT_V(8); PG8_WAIT_L(0); PG8_BAR; PG8_MMA(1, 0, At, B0); PG8_MMA(1, 1, At, B1); PG8_BAR; PG8_SCHED;
.LBB0_115:
	ds_read_b128 v[154:157], v150
	ds_read_b128 v[158:161], v150 offset:1024
	ds_read_b128 v[162:165], v150 offset:2048
	ds_read_b128 v[166:169], v150 offset:3072
	ds_read_b128 v[170:173], v151
	ds_read_b128 v[174:177], v151 offset:1024
	ds_read_b128 v[180:183], v151 offset:2048
	ds_read_b128 v[184:187], v151 offset:3072
	s_add_u32 s50, s48, 0x4000
	s_addc_u32 s51, s49, 0
	s_cmp_eq_u32 s76, 60
	s_cselect_b32 s74, s64, s50
	s_cselect_b32 s75, s25, s51
	s_cselect_b32 s72, s65, s68
	s_cselect_b32 s73, s19, s69
	s_add_u32 s50, s74, 0x8000
	s_addc_u32 s51, s75, 0
	s_sub_u32 s50, s48, 0x4000
	s_subb_u32 s51, s49, 0
	v_lshl_add_u64 v[224:225], s[50:51], 0, v[130:131]
	s_mov_b32 m0, s58
	s_nop 0
	global_load_lds_dwordx4 v[224:225], off
	v_lshl_add_u64 v[224:225], s[50:51], 0, v[134:135]
	s_mov_b32 m0, s59
	s_nop 0
	global_load_lds_dwordx4 v[224:225], off
	v_lshl_add_u64 v[224:225], s[48:49], 0, v[140:141]
	s_add_i32 m0, s28, 0xc000
	ds_read_b128 v[188:191], v152
	ds_read_b128 v[196:199], v152 offset:1024
	ds_read_b128 v[200:203], v152 offset:2048
	ds_read_b128 v[204:207], v152 offset:3072
	ds_read_b128 v[208:211], v152 offset:4096
	ds_read_b128 v[212:215], v152 offset:5120
	ds_read_b128 v[216:219], v152 offset:6144
	ds_read_b128 v[220:223], v152 offset:7168
	global_load_lds_dwordx4 v[224:225], off
	v_lshl_add_u64 v[224:225], s[48:49], 0, v[142:143]
	s_add_i32 m0, s28, 0xe000
	s_nop 0
	global_load_lds_dwordx4 v[224:225], off
	s_waitcnt vmcnt(8)
	s_waitcnt lgkmcnt(0)
	s_barrier
	s_setprio 1
	s_waitcnt lgkmcnt(0)
	v_mfma_f32_16x16x32_bf16 v[126:129], v[154:157], v[188:191], v[126:129]
	v_mfma_f32_16x16x32_bf16 v[118:121], v[162:165], v[188:191], v[118:121]
	v_mfma_f32_16x16x32_bf16 v[110:113], v[154:157], v[200:203], v[110:113]
	v_mfma_f32_16x16x32_bf16 v[102:105], v[162:165], v[200:203], v[102:105]
	v_mfma_f32_16x16x32_bf16 v[94:97], v[154:157], v[208:211], v[94:97]
	v_mfma_f32_16x16x32_bf16 v[86:89], v[162:165], v[208:211], v[86:89]
	v_mfma_f32_16x16x32_bf16 v[78:81], v[154:157], v[216:219], v[78:81]
	v_mfma_f32_16x16x32_bf16 v[70:73], v[162:165], v[216:219], v[70:73]
	v_mfma_f32_16x16x32_bf16 v[126:129], v[158:161], v[196:199], v[126:129]
	v_mfma_f32_16x16x32_bf16 v[118:121], v[166:169], v[196:199], v[118:121]
	v_mfma_f32_16x16x32_bf16 v[110:113], v[158:161], v[204:207], v[110:113]
	v_mfma_f32_16x16x32_bf16 v[102:105], v[166:169], v[204:207], v[102:105]
	v_mfma_f32_16x16x32_bf16 v[94:97], v[158:161], v[212:215], v[94:97]
	v_mfma_f32_16x16x32_bf16 v[86:89], v[166:169], v[212:215], v[86:89]
	v_mfma_f32_16x16x32_bf16 v[78:81], v[158:161], v[220:223], v[78:81]
	v_mfma_f32_16x16x32_bf16 v[70:73], v[166:169], v[220:223], v[70:73]
	s_setprio 0
	s_setprio 1
	v_mfma_f32_16x16x32_bf16 v[122:125], v[170:173], v[188:191], v[122:125]
	v_mfma_f32_16x16x32_bf16 v[114:117], v[180:183], v[188:191], v[114:117]
	v_mfma_f32_16x16x32_bf16 v[106:109], v[170:173], v[200:203], v[106:109]
	v_mfma_f32_16x16x32_bf16 v[98:101], v[180:183], v[200:203], v[98:101]
	v_mfma_f32_16x16x32_bf16 v[90:93], v[170:173], v[208:211], v[90:93]
	v_mfma_f32_16x16x32_bf16 v[82:85], v[180:183], v[208:211], v[82:85]
	v_mfma_f32_16x16x32_bf16 v[74:77], v[170:173], v[216:219], v[74:77]
	v_mfma_f32_16x16x32_bf16 v[66:69], v[180:183], v[216:219], v[66:69]
	v_mfma_f32_16x16x32_bf16 v[122:125], v[174:177], v[196:199], v[122:125]
	v_mfma_f32_16x16x32_bf16 v[114:117], v[184:187], v[196:199], v[114:117]
	v_mfma_f32_16x16x32_bf16 v[106:109], v[174:177], v[204:207], v[106:109]
	v_mfma_f32_16x16x32_bf16 v[98:101], v[184:187], v[204:207], v[98:101]
	v_mfma_f32_16x16x32_bf16 v[90:93], v[174:177], v[212:215], v[90:93]
	v_mfma_f32_16x16x32_bf16 v[82:85], v[184:187], v[212:215], v[82:85]
	v_mfma_f32_16x16x32_bf16 v[74:77], v[174:177], v[220:223], v[74:77]
	v_mfma_f32_16x16x32_bf16 v[66:69], v[184:187], v[220:223], v[66:69]
	s_setprio 0
	s_barrier
	s_add_i32 s77, s61, s3
	v_lshl_add_u64 v[224:225], s[72:73], 0, v[132:133]
	s_mov_b32 m0, s77
	ds_read_b128 v[188:191], v152 offset:16384
	ds_read_b128 v[196:199], v152 offset:17408
	ds_read_b128 v[200:203], v152 offset:18432
	ds_read_b128 v[204:207], v152 offset:19456
	ds_read_b128 v[208:211], v152 offset:20480
	ds_read_b128 v[212:215], v152 offset:21504
	ds_read_b128 v[216:219], v152 offset:22528
	ds_read_b128 v[220:223], v152 offset:23552
	global_load_lds_dwordx4 v[224:225], off
	s_add_i32 m0, s77, 0x2000
	s_add_u32 s78, s72, 0x4000
	v_lshl_add_u64 v[224:225], s[72:73], 0, v[136:137]
	s_addc_u32 s79, s73, 0
	s_add_i32 s77, s62, s3
	global_load_lds_dwordx4 v[224:225], off
	v_lshl_add_u64 v[224:225], s[78:79], 0, v[132:133]
	s_mov_b32 m0, s77
	s_nop 0
	global_load_lds_dwordx4 v[224:225], off
	v_lshl_add_u64 v[224:225], s[78:79], 0, v[136:137]
	s_add_i32 m0, s77, 0x2000
	s_nop 0
	global_load_lds_dwordx4 v[224:225], off
	s_waitcnt vmcnt(6)
	s_waitcnt lgkmcnt(0)
	s_barrier
; #define PG8_STAGE(bufoff, gbase, voff) do { _Pragma("unroll") for (int _i = 0; _i < 2; ++_i) \
;         __builtin_amdgcn_global_load_lds((const unsigned*)((const char*)(gbase) + (voff)[_i]), (PG8_LAS unsigned*)(lds + (bufoff) + ldsw + _i * 8192), 16, 0, 0); } while (0)
; #define PG8_LDA(dst, b, h) do { _Pragma("unroll") for (int m = 0; m < 4; ++m) _Pragma("unroll") for (int k = 0; k < 2; ++k) dst[m][k] = *(const PG8_LAS bf16x8*)(lds + PG8_SA(b, h) + aoff + m * 2048 + k * 1024); } while (0)
; #define PG8_LDB(dst, b, h) do { _Pragma("unroll") for (int n = 0; n < 2; ++n) _Pragma("unroll") for (int k = 0; k < 2; ++k) dst[n][k] = *(const PG8_LAS bf16x8*)(lds + PG8_SB(b, h) + boff + n * 2048 + k * 1024); } while (0)
; #define PG8_MMA(ai, bj, At, Bt) do { __builtin_amdgcn_s_setprio(1); _Pragma("unroll") for (int m = 0; m < 4; ++m) _Pragma("unroll") for (int n = 0; n < 2; ++n) _Pragma("unroll") for (int k = 0; k < 2; ++k) \
;         acc[ai][bj][m][n] = __builtin_amdgcn_mfma_f32_16x16x32_bf16(Bt[n][k], At[m][k], acc[ai][bj][m][n], 0, 0, 0); __builtin_amdgcn_s_setprio(0); } while (0)
; #define PG8_WAIT_V(n) asm volatile("s_waitcnt vmcnt(" #n ")" ::: "memory")
; #define PG8_WAIT_L(n) asm volatile("s_waitcnt lgkmcnt(" #n ")" ::: "memory")
; #define PG8_BAR __builtin_amdgcn_s_barrier()
; #define PG8_SCHED __builtin_amdgcn_sched_barrier(0)
; template <class Epi, class Sched, bool ALIGN_EPI = false, bool SP2 = false>
; __device__ __forceinline__ void gemm_phase(PG8_LAS unsigned char* lds, const Gemm g, const Sched& S, const Epi& E) {
;     ...
;             PG8_LDB(B0, 0, 0); PG8_LDB(B1, 0, 1); PG8_SCHED; PG8_LDA(At, 0, 0); PG8_STAGE(PG8_SA(1, 1), a1 + hstep, voffA);
;             PG8_WAIT_V(8); PG8_WAIT_L(0); PG8_BAR; PG8_MMA(0, 0, At, B0); PG8_MMA(0, 1, At, B1); PG8_BAR; PG8_SCHED;
;             PG8_LDA(At, 0, 1); PG8_STAGE(PG8_SB(0, 0), b2, voffB); PG8_STAGE(PG8_SB(0, 1), b2 + hstep, voffB); PG8_STAGE(PG8_SA(0, 0), a2, voffA);
;             PG8_WAIT_V(8); PG8_WAIT_L(0); PG8_BAR; PG8_MMA(1, 0, At, B0); PG8_MMA(1, 1, At, B1); PG8_BAR; PG8_SCHED;
;             PG8_LDB(B0, 1, 0); PG8_LDB(B1, 1, 1); PG8_SCHED; PG8_LDA(At, 1, 0); PG8_STAGE(PG8_SA(0, 1), a2 + hstep, voffA);
;             PG8_WAIT_V(8); PG8_WAIT_L(0); PG8_BAR; PG8_MMA(0, 0, At, B0); PG8_MMA(0, 1, At, B1); PG8_BAR; PG8_SCHED;
	s_setprio 1
	s_waitcnt lgkmcnt(0)
	v_mfma_f32_16x16x32_bf16 v[62:65], v[154:157], v[188:191], v[62:65]
	v_mfma_f32_16x16x32_bf16 v[54:57], v[162:165], v[188:191], v[54:57]
	v_mfma_f32_16x16x32_bf16 v[46:49], v[154:157], v[200:203], v[46:49]
	v_mfma_f32_16x16x32_bf16 v[38:41], v[162:165], v[200:203], v[38:41]
	v_mfma_f32_16x16x32_bf16 v[30:33], v[154:157], v[208:211], v[30:33]
	v_mfma_f32_16x16x32_bf16 v[22:25], v[162:165], v[208:211], v[22:25]
	v_mfma_f32_16x16x32_bf16 v[14:17], v[154:157], v[216:219], v[14:17]
	v_mfma_f32_16x16x32_bf16 v[6:9], v[162:165], v[216:219], v[6:9]
	v_mfma_f32_16x16x32_bf16 v[62:65], v[158:161], v[196:199], v[62:65]
	v_mfma_f32_16x16x32_bf16 v[54:57], v[166:169], v[196:199], v[54:57]
	v_mfma_f32_16x16x32_bf16 v[46:49], v[158:161], v[204:207], v[46:49]
	v_mfma_f32_16x16x32_bf16 v[38:41], v[166:169], v[204:207], v[38:41]
	v_mfma_f32_16x16x32_bf16 v[30:33], v[158:161], v[212:215], v[30:33]
	v_mfma_f32_16x16x32_bf16 v[22:25], v[166:169], v[212:215], v[22:25]
	v_mfma_f32_16x16x32_bf16 v[14:17], v[158:161], v[220:223], v[14:17]
	v_mfma_f32_16x16x32_bf16 v[6:9], v[166:169], v[220:223], v[6:9]
	s_setprio 0
	s_setprio 1
	v_mfma_f32_16x16x32_bf16 v[58:61], v[170:173], v[188:191], v[58:61]
	v_mfma_f32_16x16x32_bf16 v[50:53], v[180:183], v[188:191], v[50:53]
	v_mfma_f32_16x16x32_bf16 v[42:45], v[170:173], v[200:203], v[42:45]
	v_mfma_f32_16x16x32_bf16 v[34:37], v[180:183], v[200:203], v[34:37]
	v_mfma_f32_16x16x32_bf16 v[26:29], v[170:173], v[208:211], v[26:29]
	v_mfma_f32_16x16x32_bf16 v[18:21], v[180:183], v[208:211], v[18:21]
	v_mfma_f32_16x16x32_bf16 v[10:13], v[170:173], v[216:219], v[10:13]
	v_mfma_f32_16x16x32_bf16 v[2:5], v[180:183], v[216:219], v[2:5]
	v_mfma_f32_16x16x32_bf16 v[58:61], v[174:177], v[196:199], v[58:61]
	v_mfma_f32_16x16x32_bf16 v[50:53], v[184:187], v[196:199], v[50:53]
	v_mfma_f32_16x16x32_bf16 v[42:45], v[174:177], v[204:207], v[42:45]
	v_mfma_f32_16x16x32_bf16 v[34:37], v[184:187], v[204:207], v[34:37]
	v_mfma_f32_16x16x32_bf16 v[26:29], v[174:177], v[212:215], v[26:29]
	v_mfma_f32_16x16x32_bf16 v[18:21], v[184:187], v[212:215], v[18:21]
	v_mfma_f32_16x16x32_bf16 v[10:13], v[174:177], v[220:223], v[10:13]
	v_mfma_f32_16x16x32_bf16 v[2:5], v[184:187], v[220:223], v[2:5]
	s_setprio 0
	s_barrier
	s_add_i32 s77, 0, 0x18000
	v_add_u32_e32 v138, s77, v148
	s_add_i32 s78, 0, 0x1c000
	ds_read_b128 v[154:157], v138
	ds_read_b128 v[158:161], v138 offset:1024
	ds_read_b128 v[162:165], v138 offset:2048
	ds_read_b128 v[166:169], v138 offset:3072
	v_add_u32_e32 v138, s78, v148
	ds_read_b128 v[170:173], v138
	ds_read_b128 v[174:177], v138 offset:1024
	ds_read_b128 v[180:183], v138 offset:2048
	ds_read_b128 v[184:187], v138 offset:3072
	v_lshl_add_u64 v[224:225], s[74:75], 0, v[130:131]
	s_mov_b32 m0, s28
	s_nop 0
	global_load_lds_dwordx4 v[224:225], off
	v_lshl_add_u64 v[224:225], s[74:75], 0, v[134:135]
	s_mov_b32 m0, s29
	s_nop 0
	global_load_lds_dwordx4 v[224:225], off
	s_add_u32 s74, s74, 0x4000
	s_addc_u32 s75, s75, 0
	s_mov_b32 m0, s30
	v_lshl_add_u64 v[224:225], s[74:75], 0, v[130:131]
	ds_read_b128 v[188:191], v152 offset:32768
	ds_read_b128 v[196:199], v152 offset:33792
	ds_read_b128 v[200:203], v152 offset:34816
	ds_read_b128 v[204:207], v152 offset:35840
	ds_read_b128 v[208:211], v152 offset:36864
	ds_read_b128 v[212:215], v152 offset:37888
	ds_read_b128 v[216:219], v152 offset:38912
	ds_read_b128 v[220:223], v152 offset:39936
	global_load_lds_dwordx4 v[224:225], off
	v_lshl_add_u64 v[224:225], s[74:75], 0, v[134:135]
	s_mov_b32 m0, s31
	s_nop 0
	global_load_lds_dwordx4 v[224:225], off
	s_waitcnt vmcnt(8)
	s_waitcnt lgkmcnt(0)
	s_barrier
; #define PG8_STAGE(bufoff, gbase, voff) do { _Pragma("unroll") for (int _i = 0; _i < 2; ++_i) \
;         __builtin_amdgcn_global_load_lds((const unsigned*)((const char*)(gbase) + (voff)[_i]), (PG8_LAS unsigned*)(lds + (bufoff) + ldsw + _i * 8192), 16, 0, 0); } while (0)
; #define PG8_LDA(dst, b, h) do { _Pragma("unroll") for (int m = 0; m < 4; ++m) _Pragma("unroll") for (int k = 0; k < 2; ++k) dst[m][k] = *(const PG8_LAS bf16x8*)(lds + PG8_SA(b, h) + aoff + m * 2048 + k * 1024); } while (0)
; #define PG8_LDB(dst, b, h) do { _Pragma("unroll") for (int n = 0; n < 2; ++n) _Pragma("unroll") for (int k = 0; k < 2; ++k) dst[n][k] = *(const PG8_LAS bf16x8*)(lds + PG8_SB(b, h) + boff + n * 2048 + k * 1024); } while (0)
; #define PG8_MMA(ai, bj, At, Bt) do { __builtin_amdgcn_s_setprio(1); _Pragma("unroll") for (int m = 0; m < 4; ++m) _Pragma("unroll") for (int n = 0; n < 2; ++n) _Pragma("unroll") for (int k = 0; k < 2; ++k) \
;         acc[ai][bj][m][n] = __builtin_amdgcn_mfma_f32_16x16x32_bf16(Bt[n][k], At[m][k], acc[ai][bj][m][n], 0, 0, 0); __builtin_amdgcn_s_setprio(0); } while (0)
; #define PG8_WAIT_V(n) asm volatile("s_waitcnt vmcnt(" #n ")" ::: "memory")
; #define PG8_WAIT_L(n) asm volatile("s_waitcnt lgkmcnt(" #n ")" ::: "memory")
; #define PG8_BAR __builtin_amdgcn_s_barrier()
; #define PG8_SCHED __builtin_amdgcn_sched_barrier(0)
; template <class Epi, class Sched, bool ALIGN_EPI = false, bool SP2 = false>
; __device__ __forceinline__ void gemm_phase(PG8_LAS unsigned char* lds, const Gemm g, const Sched& S, const Epi& E) {
;     ...
;             PG8_LDB(B0, 1, 0); PG8_LDB(B1, 1, 1); PG8_SCHED; PG8_LDA(At, 1, 0); PG8_STAGE(PG8_SA(0, 1), a2 + hstep, voffA);
;             PG8_WAIT_V(8); PG8_WAIT_L(0); PG8_BAR; PG8_MMA(0, 0, At, B0); PG8_MMA(0, 1, At, B1); PG8_BAR; PG8_SCHED;
;             PG8_LDA(At, 1, 1); PG8_STAGE(PG8_SB(1, 0), b3, voffB); PG8_STAGE(PG8_SB(1, 1), b3 + hstep, voffB); PG8_STAGE(PG8_SA(1, 0), a3, voffA);
;             PG8_WAIT_V(8); PG8_WAIT_L(0); PG8_BAR; PG8_MMA(1, 0, At, B0); PG8_MMA(1, 1, At, B1); PG8_BAR; PG8_SCHED;
	s_setprio 1
	s_waitcnt lgkmcnt(0)
	v_mfma_f32_16x16x32_bf16 v[126:129], v[154:157], v[188:191], v[126:129]
	v_mfma_f32_16x16x32_bf16 v[118:121], v[162:165], v[188:191], v[118:121]
	v_mfma_f32_16x16x32_bf16 v[110:113], v[154:157], v[200:203], v[110:113]
	v_mfma_f32_16x16x32_bf16 v[102:105], v[162:165], v[200:203], v[102:105]
	v_mfma_f32_16x16x32_bf16 v[94:97], v[154:157], v[208:211], v[94:97]
	v_mfma_f32_16x16x32_bf16 v[86:89], v[162:165], v[208:211], v[86:89]
	v_mfma_f32_16x16x32_bf16 v[78:81], v[154:157], v[216:219], v[78:81]
	v_mfma_f32_16x16x32_bf16 v[70:73], v[162:165], v[216:219], v[70:73]
	v_mfma_f32_16x16x32_bf16 v[126:129], v[158:161], v[196:199], v[126:129]
	v_mfma_f32_16x16x32_bf16 v[118:121], v[166:169], v[196:199], v[118:121]
	v_mfma_f32_16x16x32_bf16 v[110:113], v[158:161], v[204:207], v[110:113]
	v_mfma_f32_16x16x32_bf16 v[102:105], v[166:169], v[204:207], v[102:105]
	v_mfma_f32_16x16x32_bf16 v[94:97], v[158:161], v[212:215], v[94:97]
	v_mfma_f32_16x16x32_bf16 v[86:89], v[166:169], v[212:215], v[86:89]
	v_mfma_f32_16x16x32_bf16 v[78:81], v[158:161], v[220:223], v[78:81]
	v_mfma_f32_16x16x32_bf16 v[70:73], v[166:169], v[220:223], v[70:73]
	s_setprio 0
	s_setprio 1
	v_mfma_f32_16x16x32_bf16 v[122:125], v[170:173], v[188:191], v[122:125]
	v_mfma_f32_16x16x32_bf16 v[114:117], v[180:183], v[188:191], v[114:117]
	v_mfma_f32_16x16x32_bf16 v[106:109], v[170:173], v[200:203], v[106:109]
	v_mfma_f32_16x16x32_bf16 v[98:101], v[180:183], v[200:203], v[98:101]
	v_mfma_f32_16x16x32_bf16 v[90:93], v[170:173], v[208:211], v[90:93]
	v_mfma_f32_16x16x32_bf16 v[82:85], v[180:183], v[208:211], v[82:85]
	v_mfma_f32_16x16x32_bf16 v[74:77], v[170:173], v[216:219], v[74:77]
	v_mfma_f32_16x16x32_bf16 v[66:69], v[180:183], v[216:219], v[66:69]
	v_mfma_f32_16x16x32_bf16 v[122:125], v[174:177], v[196:199], v[122:125]
	v_mfma_f32_16x16x32_bf16 v[114:117], v[184:187], v[196:199], v[114:117]
	v_mfma_f32_16x16x32_bf16 v[106:109], v[174:177], v[204:207], v[106:109]
	v_mfma_f32_16x16x32_bf16 v[98:101], v[184:187], v[204:207], v[98:101]
	v_mfma_f32_16x16x32_bf16 v[90:93], v[174:177], v[212:215], v[90:93]
	v_mfma_f32_16x16x32_bf16 v[82:85], v[184:187], v[212:215], v[82:85]
	v_mfma_f32_16x16x32_bf16 v[74:77], v[174:177], v[220:223], v[74:77]
	v_mfma_f32_16x16x32_bf16 v[66:69], v[184:187], v[220:223], v[66:69]
	s_setprio 0
	s_barrier
	s_add_u32 s74, s72, 0x8000
	s_addc_u32 s75, s73, 0
	s_add_i32 s77, s77, s3
	v_lshl_add_u64 v[224:225], s[74:75], 0, v[132:133]
	s_mov_b32 m0, s77
	ds_read_b128 v[188:191], v152 offset:49152
	ds_read_b128 v[196:199], v152 offset:50176
	ds_read_b128 v[200:203], v152 offset:51200
	ds_read_b128 v[204:207], v152 offset:52224
	ds_read_b128 v[208:211], v152 offset:53248
	ds_read_b128 v[212:215], v152 offset:54272
	ds_read_b128 v[216:219], v152 offset:55296
	ds_read_b128 v[220:223], v152 offset:56320
	global_load_lds_dwordx4 v[224:225], off
	s_add_i32 m0, s77, 0x2000
	s_add_u32 s72, s72, 0xc000
	v_lshl_add_u64 v[224:225], s[74:75], 0, v[136:137]
	s_addc_u32 s73, s73, 0
	s_add_i32 s74, s78, s3
	global_load_lds_dwordx4 v[224:225], off
	v_lshl_add_u64 v[224:225], s[72:73], 0, v[132:133]
	s_mov_b32 m0, s74
	s_nop 0
	global_load_lds_dwordx4 v[224:225], off
	v_lshl_add_u64 v[224:225], s[72:73], 0, v[136:137]
	s_add_i32 m0, s74, 0x2000
	s_nop 0
	global_load_lds_dwordx4 v[224:225], off
	s_waitcnt vmcnt(6)
	s_waitcnt lgkmcnt(0)
	s_barrier
	s_setprio 1
	s_waitcnt lgkmcnt(0)
	v_mfma_f32_16x16x32_bf16 v[62:65], v[154:157], v[188:191], v[62:65]
	v_mfma_f32_16x16x32_bf16 v[54:57], v[162:165], v[188:191], v[54:57]
	v_mfma_f32_16x16x32_bf16 v[46:49], v[154:157], v[200:203], v[46:49]
	v_mfma_f32_16x16x32_bf16 v[38:41], v[162:165], v[200:203], v[38:41]
	v_mfma_f32_16x16x32_bf16 v[30:33], v[154:157], v[208:211], v[30:33]
	v_mfma_f32_16x16x32_bf16 v[22:25], v[162:165], v[208:211], v[22:25]
	v_mfma_f32_16x16x32_bf16 v[14:17], v[154:157], v[216:219], v[14:17]
	v_mfma_f32_16x16x32_bf16 v[6:9], v[162:165], v[216:219], v[6:9]
	v_mfma_f32_16x16x32_bf16 v[62:65], v[158:161], v[196:199], v[62:65]
	v_mfma_f32_16x16x32_bf16 v[54:57], v[166:169], v[196:199], v[54:57]
	v_mfma_f32_16x16x32_bf16 v[46:49], v[158:161], v[204:207], v[46:49]
	v_mfma_f32_16x16x32_bf16 v[38:41], v[166:169], v[204:207], v[38:41]
	v_mfma_f32_16x16x32_bf16 v[30:33], v[158:161], v[212:215], v[30:33]
	v_mfma_f32_16x16x32_bf16 v[22:25], v[166:169], v[212:215], v[22:25]
	v_mfma_f32_16x16x32_bf16 v[14:17], v[158:161], v[220:223], v[14:17]
	v_mfma_f32_16x16x32_bf16 v[6:9], v[166:169], v[220:223], v[6:9]
	s_setprio 0
	s_setprio 1
	v_mfma_f32_16x16x32_bf16 v[58:61], v[170:173], v[188:191], v[58:61]
	v_mfma_f32_16x16x32_bf16 v[50:53], v[180:183], v[188:191], v[50:53]
	v_mfma_f32_16x16x32_bf16 v[42:45], v[170:173], v[200:203], v[42:45]
	v_mfma_f32_16x16x32_bf16 v[34:37], v[180:183], v[200:203], v[34:37]
	v_mfma_f32_16x16x32_bf16 v[26:29], v[170:173], v[208:211], v[26:29]
	v_mfma_f32_16x16x32_bf16 v[18:21], v[180:183], v[208:211], v[18:21]
	v_mfma_f32_16x16x32_bf16 v[10:13], v[170:173], v[216:219], v[10:13]
	v_mfma_f32_16x16x32_bf16 v[2:5], v[180:183], v[216:219], v[2:5]
	v_mfma_f32_16x16x32_bf16 v[58:61], v[174:177], v[196:199], v[58:61]
	v_mfma_f32_16x16x32_bf16 v[50:53], v[184:187], v[196:199], v[50:53]
	v_mfma_f32_16x16x32_bf16 v[42:45], v[174:177], v[204:207], v[42:45]
	v_mfma_f32_16x16x32_bf16 v[34:37], v[184:187], v[204:207], v[34:37]
	v_mfma_f32_16x16x32_bf16 v[26:29], v[174:177], v[212:215], v[26:29]
	v_mfma_f32_16x16x32_bf16 v[18:21], v[184:187], v[212:215], v[18:21]
	v_mfma_f32_16x16x32_bf16 v[10:13], v[174:177], v[220:223], v[10:13]
	v_mfma_f32_16x16x32_bf16 v[2:5], v[184:187], v[220:223], v[2:5]
	s_setprio 0
	s_barrier
	s_add_i32 s76, s76, 2
	s_add_u32 s48, s48, 0x10000
	s_addc_u32 s49, s49, 0
	s_add_u32 s68, s68, 0x10000
	s_addc_u32 s69, s69, 0
	s_cmp_gt_u32 s76, 61
	s_cbranch_scc0 .LBB0_115
	s_and_b64 vcc, exec, s[14:15]
	s_cbranch_vccz .LBB0_118
	s_barrier

; #define PG8_STAGE(bufoff, gbase, voff) do { _Pragma("unroll") for (int _i = 0; _i < 2; ++_i) \
;         __builtin_amdgcn_global_load_lds((const unsigned*)((const char*)(gbase) + (voff)[_i]), (PG8_LAS unsigned*)(lds + (bufoff) + ldsw + _i * 8192), 16, 0, 0); } while (0)
; #define PG8_LDA(dst, b, h) do { _Pragma("unroll") for (int m = 0; m < 4; ++m) _Pragma("unroll") for (int k = 0; k < 2; ++k) dst[m][k] = *(const PG8_LAS bf16x8*)(lds + PG8_SA(b, h) + aoff + m * 2048 + k * 1024); } while (0)
; #define PG8_LDB(dst, b, h) do { _Pragma("unroll") for (int n = 0; n < 2; ++n) _Pragma("unroll") for (int k = 0; k < 2; ++k) dst[n][k] = *(const PG8_LAS bf16x8*)(lds + PG8_SB(b, h) + boff + n * 2048 + k * 1024); } while (0)
; template <class Epi, class Sched, bool ALIGN_EPI = false, bool SP2 = false>
; __device__ __forceinline__ void gemm_phase(PG8_LAS unsigned char* lds, const Gemm g, const Sched& S, const Epi& E) {
;     ...
;         for (; t < tend; t += 2) {
;             const bool last = (t == nt - 2);
;             const char* a1 = cA + (size_t)(t + 1) * kstep;
;             const char* a2 = last ? nA : cA + (size_t)(t + 2) * kstep; const char* b2 = last ? nB : cB + (size_t)(t + 2) * kstep;
;             const char* a3 = a2 + kstep; const char* b3 = b2 + kstep;
;             if (last && has_next) S.a_ready(nxt);
;             if constexpr (SP2) {
;             PG8_LDB(B0, 0, 0); PG8_LDB(B1, 0, 1); PG8_SCHED; PG8_LDA(At, 0, 0); PG8_STAGE(PG8_SA(1, 1), a1 + hstep, voffA);
;             PG8_WAIT_V(8); PG8_WAIT_L(0); PG8_BAR; PG8_MMA(0, 0, At, B0); PG8_MMA(0, 1, At, B1); PG8_BAR; PG8_SCHED;
;             PG8_LDA(At, 0, 1); PG8_STAGE(PG8_SB(0, 0), b2, voffB); PG8_STAGE(PG8_SB(0, 1), b2 + hstep, voffB); PG8_STAGE(PG8_SA(0, 0), a2, voffA);
;             PG8_WAIT_V(8); PG8_WAIT_L(0); PG8_BAR; PG8_MMA(1, 0, At, B0); PG8_MMA(1, 1, At, B1); PG8_BAR; PG8_SCHED;
;             PG8_LDB(B0, 1, 0); PG8_LDB(B1, 1, 1); PG8_SCHED; PG8_LDA(At, 1, 0); PG8_STAGE(PG8_SA(0, 1), a2 + hstep, voffA);
;             PG8_WAIT_V(8); PG8_WAIT_L(0); PG8_BAR; PG8_MMA(0, 0, At, B0); PG8_MMA(0, 1, At, B1); PG8_BAR; PG8_SCHED;
;             PG8_LDA(At, 1, 1); PG8_STAGE(PG8_SB(1, 0), b3, voffB); PG8_STAGE(PG8_SB(1, 1), b3 + hstep, voffB); PG8_STAGE(PG8_SA(1, 0), a3, voffA);
;             PG8_WAIT_V(8); PG8_WAIT_L(0); PG8_BAR; PG8_MMA(1, 0, At, B0); PG8_MMA(1, 1, At, B1); PG8_BAR; PG8_SCHED;
.LBB0_200:
	ds_read_b128 v[148:151], v154
	ds_read_b128 v[158:161], v154 offset:1024
	ds_read_b128 v[162:165], v154 offset:2048
	ds_read_b128 v[166:169], v154 offset:3072
	ds_read_b128 v[170:173], v155
	ds_read_b128 v[174:177], v155 offset:1024
	ds_read_b128 v[180:183], v155 offset:2048
	ds_read_b128 v[184:187], v155 offset:3072
	s_add_u32 s46, s44, 0x4000
	s_addc_u32 s47, s45, 0
	s_cmpk_eq_i32 s76, 0xa8
	s_cselect_b32 s50, s6, s46
	s_cselect_b32 s51, s7, s47
	s_cselect_b32 s48, s24, s74
	s_cselect_b32 s49, s25, s75
	s_add_u32 s46, s50, 0x8000
	s_addc_u32 s47, s51, 0
	s_sub_u32 s46, s44, 0x4000
	s_subb_u32 s47, s45, 0
	v_lshl_add_u64 v[224:225], s[46:47], 0, v[130:131]
	s_mov_b32 m0, s57
	s_nop 0
	global_load_lds_dwordx4 v[224:225], off
	v_lshl_add_u64 v[224:225], s[46:47], 0, v[134:135]
	s_mov_b32 m0, s58
	s_nop 0
	global_load_lds_dwordx4 v[224:225], off
	v_lshl_add_u64 v[224:225], s[44:45], 0, v[140:141]
	s_add_i32 m0, s26, 0xc000
	ds_read_b128 v[188:191], v156
	ds_read_b128 v[196:199], v156 offset:1024
	ds_read_b128 v[200:203], v156 offset:2048
	ds_read_b128 v[204:207], v156 offset:3072
	ds_read_b128 v[208:211], v156 offset:4096
	ds_read_b128 v[212:215], v156 offset:5120
	ds_read_b128 v[216:219], v156 offset:6144
	ds_read_b128 v[220:223], v156 offset:7168
	global_load_lds_dwordx4 v[224:225], off
	v_lshl_add_u64 v[224:225], s[44:45], 0, v[142:143]
	s_add_i32 m0, s26, 0xe000
	s_nop 0
	global_load_lds_dwordx4 v[224:225], off
	s_waitcnt vmcnt(8)
	s_waitcnt lgkmcnt(0)
	s_barrier
	s_setprio 1
	s_waitcnt lgkmcnt(0)
	v_mfma_f32_16x16x32_bf16 v[126:129], v[148:151], v[188:191], v[126:129]
	v_mfma_f32_16x16x32_bf16 v[122:125], v[162:165], v[188:191], v[122:125]
	v_mfma_f32_16x16x32_bf16 v[110:113], v[148:151], v[200:203], v[110:113]
	v_mfma_f32_16x16x32_bf16 v[106:109], v[162:165], v[200:203], v[106:109]
	v_mfma_f32_16x16x32_bf16 v[94:97], v[148:151], v[208:211], v[94:97]
	v_mfma_f32_16x16x32_bf16 v[90:93], v[162:165], v[208:211], v[90:93]
	v_mfma_f32_16x16x32_bf16 v[78:81], v[148:151], v[216:219], v[78:81]
	v_mfma_f32_16x16x32_bf16 v[74:77], v[162:165], v[216:219], v[74:77]
	v_mfma_f32_16x16x32_bf16 v[126:129], v[158:161], v[196:199], v[126:129]
	v_mfma_f32_16x16x32_bf16 v[122:125], v[166:169], v[196:199], v[122:125]
	v_mfma_f32_16x16x32_bf16 v[110:113], v[158:161], v[204:207], v[110:113]
	v_mfma_f32_16x16x32_bf16 v[106:109], v[166:169], v[204:207], v[106:109]
	v_mfma_f32_16x16x32_bf16 v[94:97], v[158:161], v[212:215], v[94:97]
	v_mfma_f32_16x16x32_bf16 v[90:93], v[166:169], v[212:215], v[90:93]
	v_mfma_f32_16x16x32_bf16 v[78:81], v[158:161], v[220:223], v[78:81]
	v_mfma_f32_16x16x32_bf16 v[74:77], v[166:169], v[220:223], v[74:77]
	s_setprio 0
	s_setprio 1
	v_mfma_f32_16x16x32_bf16 v[118:121], v[170:173], v[188:191], v[118:121]
	v_mfma_f32_16x16x32_bf16 v[114:117], v[180:183], v[188:191], v[114:117]
	v_mfma_f32_16x16x32_bf16 v[102:105], v[170:173], v[200:203], v[102:105]
	v_mfma_f32_16x16x32_bf16 v[98:101], v[180:183], v[200:203], v[98:101]
	v_mfma_f32_16x16x32_bf16 v[86:89], v[170:173], v[208:211], v[86:89]
	v_mfma_f32_16x16x32_bf16 v[82:85], v[180:183], v[208:211], v[82:85]
	v_mfma_f32_16x16x32_bf16 v[70:73], v[170:173], v[216:219], v[70:73]
	v_mfma_f32_16x16x32_bf16 v[66:69], v[180:183], v[216:219], v[66:69]
	v_mfma_f32_16x16x32_bf16 v[118:121], v[174:177], v[196:199], v[118:121]
	v_mfma_f32_16x16x32_bf16 v[114:117], v[184:187], v[196:199], v[114:117]
	v_mfma_f32_16x16x32_bf16 v[102:105], v[174:177], v[204:207], v[102:105]
	v_mfma_f32_16x16x32_bf16 v[98:101], v[184:187], v[204:207], v[98:101]
	v_mfma_f32_16x16x32_bf16 v[86:89], v[174:177], v[212:215], v[86:89]
	v_mfma_f32_16x16x32_bf16 v[82:85], v[184:187], v[212:215], v[82:85]
	v_mfma_f32_16x16x32_bf16 v[70:73], v[174:177], v[220:223], v[70:73]
	v_mfma_f32_16x16x32_bf16 v[66:69], v[184:187], v[220:223], v[66:69]
	s_setprio 0
	s_barrier
	s_add_i32 s77, s59, s3
	v_lshl_add_u64 v[224:225], s[48:49], 0, v[132:133]
	s_mov_b32 m0, s77
	ds_read_b128 v[188:191], v156 offset:16384
	ds_read_b128 v[196:199], v156 offset:17408
	ds_read_b128 v[200:203], v156 offset:18432
	ds_read_b128 v[204:207], v156 offset:19456
	ds_read_b128 v[208:211], v156 offset:20480
	ds_read_b128 v[212:215], v156 offset:21504
	ds_read_b128 v[216:219], v156 offset:22528
	ds_read_b128 v[220:223], v156 offset:23552
	global_load_lds_dwordx4 v[224:225], off
	s_add_i32 m0, s77, 0x2000
	s_add_u32 s78, s48, 0x4000
	v_lshl_add_u64 v[224:225], s[48:49], 0, v[136:137]
	s_addc_u32 s79, s49, 0
	s_add_i32 s77, s61, s3
	global_load_lds_dwordx4 v[224:225], off
	v_lshl_add_u64 v[224:225], s[78:79], 0, v[132:133]
	s_mov_b32 m0, s77
	s_nop 0
	global_load_lds_dwordx4 v[224:225], off
	v_lshl_add_u64 v[224:225], s[78:79], 0, v[136:137]
	s_add_i32 m0, s77, 0x2000
	s_nop 0
	global_load_lds_dwordx4 v[224:225], off
	s_waitcnt vmcnt(6)
	s_waitcnt lgkmcnt(0)
	s_barrier
; #define PG8_STAGE(bufoff, gbase, voff) do { _Pragma("unroll") for (int _i = 0; _i < 2; ++_i) \
;         __builtin_amdgcn_global_load_lds((const unsigned*)((const char*)(gbase) + (voff)[_i]), (PG8_LAS unsigned*)(lds + (bufoff) + ldsw + _i * 8192), 16, 0, 0); } while (0)
; #define PG8_LDA(dst, b, h) do { _Pragma("unroll") for (int m = 0; m < 4; ++m) _Pragma("unroll") for (int k = 0; k < 2; ++k) dst[m][k] = *(const PG8_LAS bf16x8*)(lds + PG8_SA(b, h) + aoff + m * 2048 + k * 1024); } while (0)
; #define PG8_LDB(dst, b, h) do { _Pragma("unroll") for (int n = 0; n < 2; ++n) _Pragma("unroll") for (int k = 0; k < 2; ++k) dst[n][k] = *(const PG8_LAS bf16x8*)(lds + PG8_SB(b, h) + boff + n * 2048 + k * 1024); } while (0)
; #define PG8_MMA(ai, bj, At, Bt) do { __builtin_amdgcn_s_setprio(1); _Pragma("unroll") for (int m = 0; m < 4; ++m) _Pragma("unroll") for (int n = 0; n < 2; ++n) _Pragma("unroll") for (int k = 0; k < 2; ++k) \
;         acc[ai][bj][m][n] = __builtin_amdgcn_mfma_f32_16x16x32_bf16(Bt[n][k], At[m][k], acc[ai][bj][m][n], 0, 0, 0); __builtin_amdgcn_s_setprio(0); } while (0)
; #define PG8_WAIT_V(n) asm volatile("s_waitcnt vmcnt(" #n ")" ::: "memory")
; #define PG8_WAIT_L(n) asm volatile("s_waitcnt lgkmcnt(" #n ")" ::: "memory")
; #define PG8_BAR __builtin_amdgcn_s_barrier()
; #define PG8_SCHED __builtin_amdgcn_sched_barrier(0)
; template <class Epi, class Sched, bool ALIGN_EPI = false, bool SP2 = false>
; __device__ __forceinline__ void gemm_phase(PG8_LAS unsigned char* lds, const Gemm g, const Sched& S, const Epi& E) {
;     ...
;             PG8_LDB(B0, 0, 0); PG8_LDB(B1, 0, 1); PG8_SCHED; PG8_LDA(At, 0, 0); PG8_STAGE(PG8_SA(1, 1), a1 + hstep, voffA);
;             PG8_WAIT_V(8); PG8_WAIT_L(0); PG8_BAR; PG8_MMA(0, 0, At, B0); PG8_MMA(0, 1, At, B1); PG8_BAR; PG8_SCHED;
;             PG8_LDA(At, 0, 1); PG8_STAGE(PG8_SB(0, 0), b2, voffB); PG8_STAGE(PG8_SB(0, 1), b2 + hstep, voffB); PG8_STAGE(PG8_SA(0, 0), a2, voffA);
;             PG8_WAIT_V(8); PG8_WAIT_L(0); PG8_BAR; PG8_MMA(1, 0, At, B0); PG8_MMA(1, 1, At, B1); PG8_BAR; PG8_SCHED;
;             PG8_LDB(B0, 1, 0); PG8_LDB(B1, 1, 1); PG8_SCHED; PG8_LDA(At, 1, 0); PG8_STAGE(PG8_SA(0, 1), a2 + hstep, voffA);
;             PG8_WAIT_V(8); PG8_WAIT_L(0); PG8_BAR; PG8_MMA(0, 0, At, B0); PG8_MMA(0, 1, At, B1); PG8_BAR; PG8_SCHED;
	s_setprio 1
	s_waitcnt lgkmcnt(0)
	v_mfma_f32_16x16x32_bf16 v[62:65], v[148:151], v[188:191], v[62:65]
	v_mfma_f32_16x16x32_bf16 v[58:61], v[162:165], v[188:191], v[58:61]
	v_mfma_f32_16x16x32_bf16 v[46:49], v[148:151], v[200:203], v[46:49]
	v_mfma_f32_16x16x32_bf16 v[42:45], v[162:165], v[200:203], v[42:45]
	v_mfma_f32_16x16x32_bf16 v[30:33], v[148:151], v[208:211], v[30:33]
	v_mfma_f32_16x16x32_bf16 v[26:29], v[162:165], v[208:211], v[26:29]
	v_mfma_f32_16x16x32_bf16 v[14:17], v[148:151], v[216:219], v[14:17]
	v_mfma_f32_16x16x32_bf16 v[10:13], v[162:165], v[216:219], v[10:13]
	v_mfma_f32_16x16x32_bf16 v[62:65], v[158:161], v[196:199], v[62:65]
	v_mfma_f32_16x16x32_bf16 v[58:61], v[166:169], v[196:199], v[58:61]
	v_mfma_f32_16x16x32_bf16 v[46:49], v[158:161], v[204:207], v[46:49]
	v_mfma_f32_16x16x32_bf16 v[42:45], v[166:169], v[204:207], v[42:45]
	v_mfma_f32_16x16x32_bf16 v[30:33], v[158:161], v[212:215], v[30:33]
	v_mfma_f32_16x16x32_bf16 v[26:29], v[166:169], v[212:215], v[26:29]
	v_mfma_f32_16x16x32_bf16 v[14:17], v[158:161], v[220:223], v[14:17]
	v_mfma_f32_16x16x32_bf16 v[10:13], v[166:169], v[220:223], v[10:13]
	s_setprio 0
	s_setprio 1
	v_mfma_f32_16x16x32_bf16 v[54:57], v[170:173], v[188:191], v[54:57]
	v_mfma_f32_16x16x32_bf16 v[50:53], v[180:183], v[188:191], v[50:53]
	v_mfma_f32_16x16x32_bf16 v[38:41], v[170:173], v[200:203], v[38:41]
	v_mfma_f32_16x16x32_bf16 v[34:37], v[180:183], v[200:203], v[34:37]
	v_mfma_f32_16x16x32_bf16 v[22:25], v[170:173], v[208:211], v[22:25]
	v_mfma_f32_16x16x32_bf16 v[18:21], v[180:183], v[208:211], v[18:21]
	v_mfma_f32_16x16x32_bf16 v[6:9], v[170:173], v[216:219], v[6:9]
	v_mfma_f32_16x16x32_bf16 v[2:5], v[180:183], v[216:219], v[2:5]
	v_mfma_f32_16x16x32_bf16 v[54:57], v[174:177], v[196:199], v[54:57]
	v_mfma_f32_16x16x32_bf16 v[50:53], v[184:187], v[196:199], v[50:53]
	v_mfma_f32_16x16x32_bf16 v[38:41], v[174:177], v[204:207], v[38:41]
	v_mfma_f32_16x16x32_bf16 v[34:37], v[184:187], v[204:207], v[34:37]
	v_mfma_f32_16x16x32_bf16 v[22:25], v[174:177], v[212:215], v[22:25]
	v_mfma_f32_16x16x32_bf16 v[18:21], v[184:187], v[212:215], v[18:21]
	v_mfma_f32_16x16x32_bf16 v[6:9], v[174:177], v[220:223], v[6:9]
	v_mfma_f32_16x16x32_bf16 v[2:5], v[184:187], v[220:223], v[2:5]
	s_setprio 0
	s_barrier
	s_add_i32 s77, 0, 0x18000
	v_add_u32_e32 v138, s77, v153
	s_add_i32 s78, 0, 0x1c000
	ds_read_b128 v[148:151], v138
	ds_read_b128 v[158:161], v138 offset:1024
	ds_read_b128 v[162:165], v138 offset:2048
	ds_read_b128 v[166:169], v138 offset:3072
	v_add_u32_e32 v138, s78, v153
	ds_read_b128 v[170:173], v138
	ds_read_b128 v[174:177], v138 offset:1024
	ds_read_b128 v[180:183], v138 offset:2048
	ds_read_b128 v[184:187], v138 offset:3072
	v_lshl_add_u64 v[224:225], s[50:51], 0, v[130:131]
	s_mov_b32 m0, s26
	s_nop 0
	global_load_lds_dwordx4 v[224:225], off
	v_lshl_add_u64 v[224:225], s[50:51], 0, v[134:135]
	s_mov_b32 m0, s27
	s_nop 0
	global_load_lds_dwordx4 v[224:225], off
	s_add_u32 s50, s50, 0x4000
	s_addc_u32 s51, s51, 0
	s_mov_b32 m0, s28
	v_lshl_add_u64 v[224:225], s[50:51], 0, v[130:131]
	ds_read_b128 v[188:191], v156 offset:32768
	ds_read_b128 v[196:199], v156 offset:33792
	ds_read_b128 v[200:203], v156 offset:34816
	ds_read_b128 v[204:207], v156 offset:35840
	ds_read_b128 v[208:211], v156 offset:36864
	ds_read_b128 v[212:215], v156 offset:37888
	ds_read_b128 v[216:219], v156 offset:38912
	ds_read_b128 v[220:223], v156 offset:39936
	global_load_lds_dwordx4 v[224:225], off
	v_lshl_add_u64 v[224:225], s[50:51], 0, v[134:135]
	s_mov_b32 m0, s29
	s_nop 0
	global_load_lds_dwordx4 v[224:225], off
	s_waitcnt vmcnt(8)
	s_waitcnt lgkmcnt(0)
	s_barrier
; #define PG8_STAGE(bufoff, gbase, voff) do { _Pragma("unroll") for (int _i = 0; _i < 2; ++_i) \
;         __builtin_amdgcn_global_load_lds((const unsigned*)((const char*)(gbase) + (voff)[_i]), (PG8_LAS unsigned*)(lds + (bufoff) + ldsw + _i * 8192), 16, 0, 0); } while (0)
; #define PG8_LDA(dst, b, h) do { _Pragma("unroll") for (int m = 0; m < 4; ++m) _Pragma("unroll") for (int k = 0; k < 2; ++k) dst[m][k] = *(const PG8_LAS bf16x8*)(lds + PG8_SA(b, h) + aoff + m * 2048 + k * 1024); } while (0)
; #define PG8_LDB(dst, b, h) do { _Pragma("unroll") for (int n = 0; n < 2; ++n) _Pragma("unroll") for (int k = 0; k < 2; ++k) dst[n][k] = *(const PG8_LAS bf16x8*)(lds + PG8_SB(b, h) + boff + n * 2048 + k * 1024); } while (0)
; #define PG8_MMA(ai, bj, At, Bt) do { __builtin_amdgcn_s_setprio(1); _Pragma("unroll") for (int m = 0; m < 4; ++m) _Pragma("unroll") for (int n = 0; n < 2; ++n) _Pragma("unroll") for (int k = 0; k < 2; ++k) \
;         acc[ai][bj][m][n] = __builtin_amdgcn_mfma_f32_16x16x32_bf16(Bt[n][k], At[m][k], acc[ai][bj][m][n], 0, 0, 0); __builtin_amdgcn_s_setprio(0); } while (0)
; #define PG8_WAIT_V(n) asm volatile("s_waitcnt vmcnt(" #n ")" ::: "memory")
; #define PG8_WAIT_L(n) asm volatile("s_waitcnt lgkmcnt(" #n ")" ::: "memory")
; #define PG8_BAR __builtin_amdgcn_s_barrier()
; #define PG8_SCHED __builtin_amdgcn_sched_barrier(0)
; template <class Epi, class Sched, bool ALIGN_EPI = false, bool SP2 = false>
; __device__ __forceinline__ void gemm_phase(PG8_LAS unsigned char* lds, const Gemm g, const Sched& S, const Epi& E) {
;     ...
;             PG8_LDB(B0, 1, 0); PG8_LDB(B1, 1, 1); PG8_SCHED; PG8_LDA(At, 1, 0); PG8_STAGE(PG8_SA(0, 1), a2 + hstep, voffA);
;             PG8_WAIT_V(8); PG8_WAIT_L(0); PG8_BAR; PG8_MMA(0, 0, At, B0); PG8_MMA(0, 1, At, B1); PG8_BAR; PG8_SCHED;
;             PG8_LDA(At, 1, 1); PG8_STAGE(PG8_SB(1, 0), b3, voffB); PG8_STAGE(PG8_SB(1, 1), b3 + hstep, voffB); PG8_STAGE(PG8_SA(1, 0), a3, voffA);
;             PG8_WAIT_V(8); PG8_WAIT_L(0); PG8_BAR; PG8_MMA(1, 0, At, B0); PG8_MMA(1, 1, At, B1); PG8_BAR; PG8_SCHED;
	s_setprio 1
	s_waitcnt lgkmcnt(0)
	v_mfma_f32_16x16x32_bf16 v[126:129], v[148:151], v[188:191], v[126:129]
	v_mfma_f32_16x16x32_bf16 v[122:125], v[162:165], v[188:191], v[122:125]
	v_mfma_f32_16x16x32_bf16 v[110:113], v[148:151], v[200:203], v[110:113]
	v_mfma_f32_16x16x32_bf16 v[106:109], v[162:165], v[200:203], v[106:109]
	v_mfma_f32_16x16x32_bf16 v[94:97], v[148:151], v[208:211], v[94:97]
	v_mfma_f32_16x16x32_bf16 v[90:93], v[162:165], v[208:211], v[90:93]
	v_mfma_f32_16x16x32_bf16 v[78:81], v[148:151], v[216:219], v[78:81]
	v_mfma_f32_16x16x32_bf16 v[74:77], v[162:165], v[216:219], v[74:77]
	v_mfma_f32_16x16x32_bf16 v[126:129], v[158:161], v[196:199], v[126:129]
	v_mfma_f32_16x16x32_bf16 v[122:125], v[166:169], v[196:199], v[122:125]
	v_mfma_f32_16x16x32_bf16 v[110:113], v[158:161], v[204:207], v[110:113]
	v_mfma_f32_16x16x32_bf16 v[106:109], v[166:169], v[204:207], v[106:109]
	v_mfma_f32_16x16x32_bf16 v[94:97], v[158:161], v[212:215], v[94:97]
	v_mfma_f32_16x16x32_bf16 v[90:93], v[166:169], v[212:215], v[90:93]
	v_mfma_f32_16x16x32_bf16 v[78:81], v[158:161], v[220:223], v[78:81]
	v_mfma_f32_16x16x32_bf16 v[74:77], v[166:169], v[220:223], v[74:77]
	s_setprio 0
	s_setprio 1
	v_mfma_f32_16x16x32_bf16 v[118:121], v[170:173], v[188:191], v[118:121]
	v_mfma_f32_16x16x32_bf16 v[114:117], v[180:183], v[188:191], v[114:117]
	v_mfma_f32_16x16x32_bf16 v[102:105], v[170:173], v[200:203], v[102:105]
	v_mfma_f32_16x16x32_bf16 v[98:101], v[180:183], v[200:203], v[98:101]
	v_mfma_f32_16x16x32_bf16 v[86:89], v[170:173], v[208:211], v[86:89]
	v_mfma_f32_16x16x32_bf16 v[82:85], v[180:183], v[208:211], v[82:85]
	v_mfma_f32_16x16x32_bf16 v[70:73], v[170:173], v[216:219], v[70:73]
	v_mfma_f32_16x16x32_bf16 v[66:69], v[180:183], v[216:219], v[66:69]
	v_mfma_f32_16x16x32_bf16 v[118:121], v[174:177], v[196:199], v[118:121]
	v_mfma_f32_16x16x32_bf16 v[114:117], v[184:187], v[196:199], v[114:117]
	v_mfma_f32_16x16x32_bf16 v[102:105], v[174:177], v[204:207], v[102:105]
	v_mfma_f32_16x16x32_bf16 v[98:101], v[184:187], v[204:207], v[98:101]
	v_mfma_f32_16x16x32_bf16 v[86:89], v[174:177], v[212:215], v[86:89]
	v_mfma_f32_16x16x32_bf16 v[82:85], v[184:187], v[212:215], v[82:85]
	v_mfma_f32_16x16x32_bf16 v[70:73], v[174:177], v[220:223], v[70:73]
	v_mfma_f32_16x16x32_bf16 v[66:69], v[184:187], v[220:223], v[66:69]
	s_setprio 0
	s_barrier
	s_add_u32 s50, s48, 0x8000
	s_addc_u32 s51, s49, 0
	s_add_i32 s77, s77, s3
	v_lshl_add_u64 v[224:225], s[50:51], 0, v[132:133]
	s_mov_b32 m0, s77
	ds_read_b128 v[188:191], v156 offset:49152
	ds_read_b128 v[196:199], v156 offset:50176
	ds_read_b128 v[200:203], v156 offset:51200
	ds_read_b128 v[204:207], v156 offset:52224
	ds_read_b128 v[208:211], v156 offset:53248
	ds_read_b128 v[212:215], v156 offset:54272
	ds_read_b128 v[216:219], v156 offset:55296
	ds_read_b128 v[220:223], v156 offset:56320
	global_load_lds_dwordx4 v[224:225], off
	s_add_i32 m0, s77, 0x2000
	s_add_u32 s48, s48, 0xc000
	v_lshl_add_u64 v[224:225], s[50:51], 0, v[136:137]
	s_addc_u32 s49, s49, 0
	s_add_i32 s50, s78, s3
	global_load_lds_dwordx4 v[224:225], off
	v_lshl_add_u64 v[224:225], s[48:49], 0, v[132:133]
	s_mov_b32 m0, s50
	s_nop 0
	global_load_lds_dwordx4 v[224:225], off
	v_lshl_add_u64 v[224:225], s[48:49], 0, v[136:137]
	s_add_i32 m0, s50, 0x2000
	s_nop 0
	global_load_lds_dwordx4 v[224:225], off
	s_waitcnt vmcnt(6)
	s_waitcnt lgkmcnt(0)
	s_barrier
	s_setprio 1
	s_waitcnt lgkmcnt(0)
	v_mfma_f32_16x16x32_bf16 v[62:65], v[148:151], v[188:191], v[62:65]
	v_mfma_f32_16x16x32_bf16 v[58:61], v[162:165], v[188:191], v[58:61]
	v_mfma_f32_16x16x32_bf16 v[46:49], v[148:151], v[200:203], v[46:49]
	v_mfma_f32_16x16x32_bf16 v[42:45], v[162:165], v[200:203], v[42:45]
	v_mfma_f32_16x16x32_bf16 v[30:33], v[148:151], v[208:211], v[30:33]
	v_mfma_f32_16x16x32_bf16 v[26:29], v[162:165], v[208:211], v[26:29]
	v_mfma_f32_16x16x32_bf16 v[14:17], v[148:151], v[216:219], v[14:17]
	v_mfma_f32_16x16x32_bf16 v[10:13], v[162:165], v[216:219], v[10:13]
	v_mfma_f32_16x16x32_bf16 v[62:65], v[158:161], v[196:199], v[62:65]
	v_mfma_f32_16x16x32_bf16 v[58:61], v[166:169], v[196:199], v[58:61]
	v_mfma_f32_16x16x32_bf16 v[46:49], v[158:161], v[204:207], v[46:49]
	v_mfma_f32_16x16x32_bf16 v[42:45], v[166:169], v[204:207], v[42:45]
	v_mfma_f32_16x16x32_bf16 v[30:33], v[158:161], v[212:215], v[30:33]
	v_mfma_f32_16x16x32_bf16 v[26:29], v[166:169], v[212:215], v[26:29]
	v_mfma_f32_16x16x32_bf16 v[14:17], v[158:161], v[220:223], v[14:17]
	v_mfma_f32_16x16x32_bf16 v[10:13], v[166:169], v[220:223], v[10:13]
	s_setprio 0
	s_setprio 1
	v_mfma_f32_16x16x32_bf16 v[54:57], v[170:173], v[188:191], v[54:57]
	v_mfma_f32_16x16x32_bf16 v[50:53], v[180:183], v[188:191], v[50:53]
	v_mfma_f32_16x16x32_bf16 v[38:41], v[170:173], v[200:203], v[38:41]
	v_mfma_f32_16x16x32_bf16 v[34:37], v[180:183], v[200:203], v[34:37]
	v_mfma_f32_16x16x32_bf16 v[22:25], v[170:173], v[208:211], v[22:25]
	v_mfma_f32_16x16x32_bf16 v[18:21], v[180:183], v[208:211], v[18:21]
	v_mfma_f32_16x16x32_bf16 v[6:9], v[170:173], v[216:219], v[6:9]
	v_mfma_f32_16x16x32_bf16 v[2:5], v[180:183], v[216:219], v[2:5]
	v_mfma_f32_16x16x32_bf16 v[54:57], v[174:177], v[196:199], v[54:57]
	v_mfma_f32_16x16x32_bf16 v[50:53], v[184:187], v[196:199], v[50:53]
	v_mfma_f32_16x16x32_bf16 v[38:41], v[174:177], v[204:207], v[38:41]
	v_mfma_f32_16x16x32_bf16 v[34:37], v[184:187], v[204:207], v[34:37]
	v_mfma_f32_16x16x32_bf16 v[22:25], v[174:177], v[212:215], v[22:25]
	v_mfma_f32_16x16x32_bf16 v[18:21], v[184:187], v[212:215], v[18:21]
	v_mfma_f32_16x16x32_bf16 v[6:9], v[174:177], v[220:223], v[6:9]
	v_mfma_f32_16x16x32_bf16 v[2:5], v[184:187], v[220:223], v[2:5]
	s_setprio 0
	s_barrier
	s_add_i32 s76, s76, 2
	s_add_u32 s44, s44, 0x10000
	s_addc_u32 s45, s45, 0
	s_add_u32 s74, s74, 0x10000
	s_addc_u32 s75, s75, 0
	s_cmpk_gt_u32 s76, 0xa9
	s_cbranch_scc0 .LBB0_200
	s_and_b64 vcc, exec, s[18:19]
	s_cbranch_vccz .LBB0_203
	s_barrier

; #define PG8_STAGE(bufoff, gbase, voff) do { _Pragma("unroll") for (int _i = 0; _i < 2; ++_i) \
;         __builtin_amdgcn_global_load_lds((const unsigned*)((const char*)(gbase) + (voff)[_i]), (PG8_LAS unsigned*)(lds + (bufoff) + ldsw + _i * 8192), 16, 0, 0); } while (0)
; #define PG8_LDA(dst, b, h) do { _Pragma("unroll") for (int m = 0; m < 4; ++m) _Pragma("unroll") for (int k = 0; k < 2; ++k) dst[m][k] = *(const PG8_LAS bf16x8*)(lds + PG8_SA(b, h) + aoff + m * 2048 + k * 1024); } while (0)
; #define PG8_LDB(dst, b, h) do { _Pragma("unroll") for (int n = 0; n < 2; ++n) _Pragma("unroll") for (int k = 0; k < 2; ++k) dst[n][k] = *(const PG8_LAS bf16x8*)(lds + PG8_SB(b, h) + boff + n * 2048 + k * 1024); } while (0)
; template <class Epi, class Sched, bool ALIGN_EPI = false, bool SP2 = false>
; __device__ __forceinline__ void gemm_phase(PG8_LAS unsigned char* lds, const Gemm g, const Sched& S, const Epi& E) {
;     ...
;         for (; t < tend; t += 2) {
;             const bool last = (t == nt - 2);
;             const char* a1 = cA + (size_t)(t + 1) * kstep;
;             const char* a2 = last ? nA : cA + (size_t)(t + 2) * kstep; const char* b2 = last ? nB : cB + (size_t)(t + 2) * kstep;
;             const char* a3 = a2 + kstep; const char* b3 = b2 + kstep;
;             if (last && has_next) S.a_ready(nxt);
;             if constexpr (SP2) {
;             PG8_LDB(B0, 0, 0); PG8_LDB(B1, 0, 1); PG8_SCHED; PG8_LDA(At, 0, 0); PG8_STAGE(PG8_SA(1, 1), a1 + hstep, voffA);
;             PG8_WAIT_V(8); PG8_WAIT_L(0); PG8_BAR; PG8_MMA(0, 0, At, B0); PG8_MMA(0, 1, At, B1); PG8_BAR; PG8_SCHED;
;             PG8_LDA(At, 0, 1); PG8_STAGE(PG8_SB(0, 0), b2, voffB); PG8_STAGE(PG8_SB(0, 1), b2 + hstep, voffB); PG8_STAGE(PG8_SA(0, 0), a2, voffA);
;             PG8_WAIT_V(8); PG8_WAIT_L(0); PG8_BAR; PG8_MMA(1, 0, At, B0); PG8_MMA(1, 1, At, B1); PG8_BAR; PG8_SCHED;
;             PG8_LDB(B0, 1, 0); PG8_LDB(B1, 1, 1); PG8_SCHED; PG8_LDA(At, 1, 0); PG8_STAGE(PG8_SA(0, 1), a2 + hstep, voffA);
;             PG8_WAIT_V(8); PG8_WAIT_L(0); PG8_BAR; PG8_MMA(0, 0, At, B0); PG8_MMA(0, 1, At, B1); PG8_BAR; PG8_SCHED;
;             PG8_LDA(At, 1, 1); PG8_STAGE(PG8_SB(1, 0), b3, voffB); PG8_STAGE(PG8_SB(1, 1), b3 + hstep, voffB); PG8_STAGE(PG8_SA(1, 0), a3, voffA);
;             PG8_WAIT_V(8); PG8_WAIT_L(0); PG8_BAR; PG8_MMA(1, 0, At, B0); PG8_MMA(1, 1, At, B1); PG8_BAR; PG8_SCHED;
.LBB0_290:
	ds_read_b128 v[146:149], v162
	ds_read_b128 v[150:153], v162 offset:1024
	ds_read_b128 v[154:157], v162 offset:2048
	ds_read_b128 v[168:171], v162 offset:3072
	ds_read_b128 v[172:175], v163
	ds_read_b128 v[180:183], v163 offset:1024
	ds_read_b128 v[184:187], v163 offset:2048
	ds_read_b128 v[188:191], v163 offset:3072
	s_add_u32 s59, s72, 0x4000
	s_addc_u32 s62, s73, 0
	s_cmp_eq_u32 s58, 60
	s_cselect_b32 s78, s19, s59
	s_cselect_b32 s79, s5, s62
	s_cselect_b32 s76, s26, s33
	s_cselect_b32 s77, s17, s56
	s_add_u32 s74, s78, 0x8000
	s_addc_u32 s75, s79, 0
	s_sub_u32 s74, s72, 0x4000
	s_subb_u32 s75, s73, 0
	v_lshl_add_u64 v[158:159], s[74:75], 0, v[130:131]
	s_mov_b32 m0, s51
	s_nop 0
	global_load_lds_dwordx4 v[158:159], off
	v_lshl_add_u64 v[158:159], s[74:75], 0, v[134:135]
	s_mov_b32 m0, s57
	s_nop 0
	global_load_lds_dwordx4 v[158:159], off
	v_lshl_add_u64 v[158:159], s[72:73], 0, v[138:139]
	s_add_i32 m0, s15, 0xc000
	ds_read_b128 v[198:201], v164
	ds_read_b128 v[202:205], v164 offset:1024
	ds_read_b128 v[206:209], v164 offset:2048
	ds_read_b128 v[210:213], v164 offset:3072
	ds_read_b128 v[214:217], v164 offset:4096
	ds_read_b128 v[218:221], v164 offset:5120
	ds_read_b128 v[222:225], v164 offset:6144
	ds_read_b128 v[226:229], v164 offset:7168
	global_load_lds_dwordx4 v[158:159], off
	v_lshl_add_u64 v[158:159], s[72:73], 0, v[140:141]
	s_add_i32 m0, s15, 0xe000
	s_nop 0
	global_load_lds_dwordx4 v[158:159], off
	s_waitcnt vmcnt(8)
	s_waitcnt lgkmcnt(0)
	s_barrier
	s_setprio 1
	s_waitcnt lgkmcnt(0)
	v_mfma_f32_16x16x32_bf16 v[126:129], v[146:149], v[198:201], v[126:129]
	v_mfma_f32_16x16x32_bf16 v[122:125], v[154:157], v[198:201], v[122:125]
	v_mfma_f32_16x16x32_bf16 v[110:113], v[146:149], v[206:209], v[110:113]
	v_mfma_f32_16x16x32_bf16 v[106:109], v[154:157], v[206:209], v[106:109]
	v_mfma_f32_16x16x32_bf16 v[94:97], v[146:149], v[214:217], v[94:97]
	v_mfma_f32_16x16x32_bf16 v[90:93], v[154:157], v[214:217], v[90:93]
	v_mfma_f32_16x16x32_bf16 v[78:81], v[146:149], v[222:225], v[78:81]
	v_mfma_f32_16x16x32_bf16 v[74:77], v[154:157], v[222:225], v[74:77]
	v_mfma_f32_16x16x32_bf16 v[126:129], v[150:153], v[202:205], v[126:129]
	v_mfma_f32_16x16x32_bf16 v[122:125], v[168:171], v[202:205], v[122:125]
	v_mfma_f32_16x16x32_bf16 v[110:113], v[150:153], v[210:213], v[110:113]
	v_mfma_f32_16x16x32_bf16 v[106:109], v[168:171], v[210:213], v[106:109]
	v_mfma_f32_16x16x32_bf16 v[94:97], v[150:153], v[218:221], v[94:97]
	v_mfma_f32_16x16x32_bf16 v[90:93], v[168:171], v[218:221], v[90:93]
	v_mfma_f32_16x16x32_bf16 v[78:81], v[150:153], v[226:229], v[78:81]
	v_mfma_f32_16x16x32_bf16 v[74:77], v[168:171], v[226:229], v[74:77]
	s_setprio 0
	s_setprio 1
	v_mfma_f32_16x16x32_bf16 v[118:121], v[172:175], v[198:201], v[118:121]
	v_mfma_f32_16x16x32_bf16 v[114:117], v[184:187], v[198:201], v[114:117]
	v_mfma_f32_16x16x32_bf16 v[102:105], v[172:175], v[206:209], v[102:105]
	v_mfma_f32_16x16x32_bf16 v[98:101], v[184:187], v[206:209], v[98:101]
	v_mfma_f32_16x16x32_bf16 v[86:89], v[172:175], v[214:217], v[86:89]
	v_mfma_f32_16x16x32_bf16 v[82:85], v[184:187], v[214:217], v[82:85]
	v_mfma_f32_16x16x32_bf16 v[70:73], v[172:175], v[222:225], v[70:73]
	v_mfma_f32_16x16x32_bf16 v[66:69], v[184:187], v[222:225], v[66:69]
	v_mfma_f32_16x16x32_bf16 v[118:121], v[180:183], v[202:205], v[118:121]
	v_mfma_f32_16x16x32_bf16 v[114:117], v[188:191], v[202:205], v[114:117]
	v_mfma_f32_16x16x32_bf16 v[102:105], v[180:183], v[210:213], v[102:105]
	v_mfma_f32_16x16x32_bf16 v[98:101], v[188:191], v[210:213], v[98:101]
	v_mfma_f32_16x16x32_bf16 v[86:89], v[180:183], v[218:221], v[86:89]
	v_mfma_f32_16x16x32_bf16 v[82:85], v[188:191], v[218:221], v[82:85]
	v_mfma_f32_16x16x32_bf16 v[70:73], v[180:183], v[226:229], v[70:73]
	v_mfma_f32_16x16x32_bf16 v[66:69], v[188:191], v[226:229], v[66:69]
	s_setprio 0
	s_barrier
	s_add_i32 s59, s81, s3
	v_lshl_add_u64 v[158:159], s[76:77], 0, v[132:133]
	s_mov_b32 m0, s59
	ds_read_b128 v[198:201], v164 offset:16384
	ds_read_b128 v[202:205], v164 offset:17408
	ds_read_b128 v[206:209], v164 offset:18432
	ds_read_b128 v[210:213], v164 offset:19456
	ds_read_b128 v[214:217], v164 offset:20480
	ds_read_b128 v[218:221], v164 offset:21504
	ds_read_b128 v[222:225], v164 offset:22528
	ds_read_b128 v[226:229], v164 offset:23552
	global_load_lds_dwordx4 v[158:159], off
	s_add_i32 m0, s59, 0x2000
	s_add_u32 s62, s76, 0x4000
	v_lshl_add_u64 v[158:159], s[76:77], 0, v[136:137]
	s_addc_u32 s63, s77, 0
	s_add_i32 s59, s82, s3
	global_load_lds_dwordx4 v[158:159], off
	v_lshl_add_u64 v[158:159], s[62:63], 0, v[132:133]
	s_mov_b32 m0, s59
	s_nop 0
	global_load_lds_dwordx4 v[158:159], off
	v_lshl_add_u64 v[158:159], s[62:63], 0, v[136:137]
	s_add_i32 m0, s59, 0x2000
	s_nop 0
	global_load_lds_dwordx4 v[158:159], off
	s_waitcnt vmcnt(6)
	s_waitcnt lgkmcnt(0)
	s_barrier
; #define PG8_STAGE(bufoff, gbase, voff) do { _Pragma("unroll") for (int _i = 0; _i < 2; ++_i) \
;         __builtin_amdgcn_global_load_lds((const unsigned*)((const char*)(gbase) + (voff)[_i]), (PG8_LAS unsigned*)(lds + (bufoff) + ldsw + _i * 8192), 16, 0, 0); } while (0)
; #define PG8_LDA(dst, b, h) do { _Pragma("unroll") for (int m = 0; m < 4; ++m) _Pragma("unroll") for (int k = 0; k < 2; ++k) dst[m][k] = *(const PG8_LAS bf16x8*)(lds + PG8_SA(b, h) + aoff + m * 2048 + k * 1024); } while (0)
; #define PG8_LDB(dst, b, h) do { _Pragma("unroll") for (int n = 0; n < 2; ++n) _Pragma("unroll") for (int k = 0; k < 2; ++k) dst[n][k] = *(const PG8_LAS bf16x8*)(lds + PG8_SB(b, h) + boff + n * 2048 + k * 1024); } while (0)
; #define PG8_MMA(ai, bj, At, Bt) do { __builtin_amdgcn_s_setprio(1); _Pragma("unroll") for (int m = 0; m < 4; ++m) _Pragma("unroll") for (int n = 0; n < 2; ++n) _Pragma("unroll") for (int k = 0; k < 2; ++k) \
;         acc[ai][bj][m][n] = __builtin_amdgcn_mfma_f32_16x16x32_bf16(Bt[n][k], At[m][k], acc[ai][bj][m][n], 0, 0, 0); __builtin_amdgcn_s_setprio(0); } while (0)
; #define PG8_WAIT_V(n) asm volatile("s_waitcnt vmcnt(" #n ")" ::: "memory")
; #define PG8_WAIT_L(n) asm volatile("s_waitcnt lgkmcnt(" #n ")" ::: "memory")
; #define PG8_BAR __builtin_amdgcn_s_barrier()
; #define PG8_SCHED __builtin_amdgcn_sched_barrier(0)
; template <class Epi, class Sched, bool ALIGN_EPI = false, bool SP2 = false>
; __device__ __forceinline__ void gemm_phase(PG8_LAS unsigned char* lds, const Gemm g, const Sched& S, const Epi& E) {
;     ...
;             PG8_LDB(B0, 0, 0); PG8_LDB(B1, 0, 1); PG8_SCHED; PG8_LDA(At, 0, 0); PG8_STAGE(PG8_SA(1, 1), a1 + hstep, voffA);
;             PG8_WAIT_V(8); PG8_WAIT_L(0); PG8_BAR; PG8_MMA(0, 0, At, B0); PG8_MMA(0, 1, At, B1); PG8_BAR; PG8_SCHED;
;             PG8_LDA(At, 0, 1); PG8_STAGE(PG8_SB(0, 0), b2, voffB); PG8_STAGE(PG8_SB(0, 1), b2 + hstep, voffB); PG8_STAGE(PG8_SA(0, 0), a2, voffA);
;             PG8_WAIT_V(8); PG8_WAIT_L(0); PG8_BAR; PG8_MMA(1, 0, At, B0); PG8_MMA(1, 1, At, B1); PG8_BAR; PG8_SCHED;
;             PG8_LDB(B0, 1, 0); PG8_LDB(B1, 1, 1); PG8_SCHED; PG8_LDA(At, 1, 0); PG8_STAGE(PG8_SA(0, 1), a2 + hstep, voffA);
;             PG8_WAIT_V(8); PG8_WAIT_L(0); PG8_BAR; PG8_MMA(0, 0, At, B0); PG8_MMA(0, 1, At, B1); PG8_BAR; PG8_SCHED;
	s_setprio 1
	s_waitcnt lgkmcnt(0)
	v_mfma_f32_16x16x32_bf16 v[62:65], v[146:149], v[198:201], v[62:65]
	v_mfma_f32_16x16x32_bf16 v[58:61], v[154:157], v[198:201], v[58:61]
	v_mfma_f32_16x16x32_bf16 v[46:49], v[146:149], v[206:209], v[46:49]
	v_mfma_f32_16x16x32_bf16 v[42:45], v[154:157], v[206:209], v[42:45]
	v_mfma_f32_16x16x32_bf16 v[30:33], v[146:149], v[214:217], v[30:33]
	v_mfma_f32_16x16x32_bf16 v[26:29], v[154:157], v[214:217], v[26:29]
	v_mfma_f32_16x16x32_bf16 v[14:17], v[146:149], v[222:225], v[14:17]
	v_mfma_f32_16x16x32_bf16 v[10:13], v[154:157], v[222:225], v[10:13]
	v_mfma_f32_16x16x32_bf16 v[62:65], v[150:153], v[202:205], v[62:65]
	v_mfma_f32_16x16x32_bf16 v[58:61], v[168:171], v[202:205], v[58:61]
	v_mfma_f32_16x16x32_bf16 v[46:49], v[150:153], v[210:213], v[46:49]
	v_mfma_f32_16x16x32_bf16 v[42:45], v[168:171], v[210:213], v[42:45]
	v_mfma_f32_16x16x32_bf16 v[30:33], v[150:153], v[218:221], v[30:33]
	v_mfma_f32_16x16x32_bf16 v[26:29], v[168:171], v[218:221], v[26:29]
	v_mfma_f32_16x16x32_bf16 v[14:17], v[150:153], v[226:229], v[14:17]
	v_mfma_f32_16x16x32_bf16 v[10:13], v[168:171], v[226:229], v[10:13]
	s_setprio 0
	s_setprio 1
	v_mfma_f32_16x16x32_bf16 v[54:57], v[172:175], v[198:201], v[54:57]
	v_mfma_f32_16x16x32_bf16 v[50:53], v[184:187], v[198:201], v[50:53]
	v_mfma_f32_16x16x32_bf16 v[38:41], v[172:175], v[206:209], v[38:41]
	v_mfma_f32_16x16x32_bf16 v[34:37], v[184:187], v[206:209], v[34:37]
	v_mfma_f32_16x16x32_bf16 v[22:25], v[172:175], v[214:217], v[22:25]
	v_mfma_f32_16x16x32_bf16 v[18:21], v[184:187], v[214:217], v[18:21]
	v_mfma_f32_16x16x32_bf16 v[6:9], v[172:175], v[222:225], v[6:9]
	v_mfma_f32_16x16x32_bf16 v[2:5], v[184:187], v[222:225], v[2:5]
	v_mfma_f32_16x16x32_bf16 v[54:57], v[180:183], v[202:205], v[54:57]
	v_mfma_f32_16x16x32_bf16 v[50:53], v[188:191], v[202:205], v[50:53]
	v_mfma_f32_16x16x32_bf16 v[38:41], v[180:183], v[210:213], v[38:41]
	v_mfma_f32_16x16x32_bf16 v[34:37], v[188:191], v[210:213], v[34:37]
	v_mfma_f32_16x16x32_bf16 v[22:25], v[180:183], v[218:221], v[22:25]
	v_mfma_f32_16x16x32_bf16 v[18:21], v[188:191], v[218:221], v[18:21]
	v_mfma_f32_16x16x32_bf16 v[6:9], v[180:183], v[226:229], v[6:9]
	v_mfma_f32_16x16x32_bf16 v[2:5], v[188:191], v[226:229], v[2:5]
	s_setprio 0
	s_barrier
	s_add_i32 s59, 0, 0x18000
	v_add_u32_e32 v158, s59, v160
	s_add_i32 s64, 0, 0x1c000
	ds_read_b128 v[146:149], v158
	ds_read_b128 v[150:153], v158 offset:1024
	ds_read_b128 v[154:157], v158 offset:2048
	ds_read_b128 v[168:171], v158 offset:3072
	v_add_u32_e32 v158, s64, v160
	ds_read_b128 v[172:175], v158
	ds_read_b128 v[180:183], v158 offset:1024
	ds_read_b128 v[184:187], v158 offset:2048
	ds_read_b128 v[188:191], v158 offset:3072
	v_lshl_add_u64 v[158:159], s[78:79], 0, v[130:131]
	s_mov_b32 m0, s15
	s_nop 0
	global_load_lds_dwordx4 v[158:159], off
	v_lshl_add_u64 v[158:159], s[78:79], 0, v[134:135]
	s_mov_b32 m0, s27
	s_nop 0
	global_load_lds_dwordx4 v[158:159], off
	s_add_u32 s62, s78, 0x4000
	s_addc_u32 s63, s79, 0
	s_mov_b32 m0, s28
	v_lshl_add_u64 v[158:159], s[62:63], 0, v[130:131]
	ds_read_b128 v[198:201], v164 offset:32768
	ds_read_b128 v[202:205], v164 offset:33792
	ds_read_b128 v[206:209], v164 offset:34816
	ds_read_b128 v[210:213], v164 offset:35840
	ds_read_b128 v[214:217], v164 offset:36864
	ds_read_b128 v[218:221], v164 offset:37888
	ds_read_b128 v[222:225], v164 offset:38912
	ds_read_b128 v[226:229], v164 offset:39936
	global_load_lds_dwordx4 v[158:159], off
	v_lshl_add_u64 v[158:159], s[62:63], 0, v[134:135]
	s_mov_b32 m0, s29
	s_nop 0
	global_load_lds_dwordx4 v[158:159], off
	s_waitcnt vmcnt(8)
	s_waitcnt lgkmcnt(0)
	s_barrier
; #define PG8_STAGE(bufoff, gbase, voff) do { _Pragma("unroll") for (int _i = 0; _i < 2; ++_i) \
;         __builtin_amdgcn_global_load_lds((const unsigned*)((const char*)(gbase) + (voff)[_i]), (PG8_LAS unsigned*)(lds + (bufoff) + ldsw + _i * 8192), 16, 0, 0); } while (0)
; #define PG8_LDA(dst, b, h) do { _Pragma("unroll") for (int m = 0; m < 4; ++m) _Pragma("unroll") for (int k = 0; k < 2; ++k) dst[m][k] = *(const PG8_LAS bf16x8*)(lds + PG8_SA(b, h) + aoff + m * 2048 + k * 1024); } while (0)
; #define PG8_LDB(dst, b, h) do { _Pragma("unroll") for (int n = 0; n < 2; ++n) _Pragma("unroll") for (int k = 0; k < 2; ++k) dst[n][k] = *(const PG8_LAS bf16x8*)(lds + PG8_SB(b, h) + boff + n * 2048 + k * 1024); } while (0)
; #define PG8_MMA(ai, bj, At, Bt) do { __builtin_amdgcn_s_setprio(1); _Pragma("unroll") for (int m = 0; m < 4; ++m) _Pragma("unroll") for (int n = 0; n < 2; ++n) _Pragma("unroll") for (int k = 0; k < 2; ++k) \
;         acc[ai][bj][m][n] = __builtin_amdgcn_mfma_f32_16x16x32_bf16(Bt[n][k], At[m][k], acc[ai][bj][m][n], 0, 0, 0); __builtin_amdgcn_s_setprio(0); } while (0)
; #define PG8_WAIT_V(n) asm volatile("s_waitcnt vmcnt(" #n ")" ::: "memory")
; #define PG8_WAIT_L(n) asm volatile("s_waitcnt lgkmcnt(" #n ")" ::: "memory")
; #define PG8_BAR __builtin_amdgcn_s_barrier()
; #define PG8_SCHED __builtin_amdgcn_sched_barrier(0)
; template <class Epi, class Sched, bool ALIGN_EPI = false, bool SP2 = false>
; __device__ __forceinline__ void gemm_phase(PG8_LAS unsigned char* lds, const Gemm g, const Sched& S, const Epi& E) {
;     ...
;             PG8_LDB(B0, 1, 0); PG8_LDB(B1, 1, 1); PG8_SCHED; PG8_LDA(At, 1, 0); PG8_STAGE(PG8_SA(0, 1), a2 + hstep, voffA);
;             PG8_WAIT_V(8); PG8_WAIT_L(0); PG8_BAR; PG8_MMA(0, 0, At, B0); PG8_MMA(0, 1, At, B1); PG8_BAR; PG8_SCHED;
;             PG8_LDA(At, 1, 1); PG8_STAGE(PG8_SB(1, 0), b3, voffB); PG8_STAGE(PG8_SB(1, 1), b3 + hstep, voffB); PG8_STAGE(PG8_SA(1, 0), a3, voffA);
;             PG8_WAIT_V(8); PG8_WAIT_L(0); PG8_BAR; PG8_MMA(1, 0, At, B0); PG8_MMA(1, 1, At, B1); PG8_BAR; PG8_SCHED;
	s_setprio 1
	s_waitcnt lgkmcnt(0)
	v_mfma_f32_16x16x32_bf16 v[126:129], v[146:149], v[198:201], v[126:129]
	v_mfma_f32_16x16x32_bf16 v[122:125], v[154:157], v[198:201], v[122:125]
	v_mfma_f32_16x16x32_bf16 v[110:113], v[146:149], v[206:209], v[110:113]
	v_mfma_f32_16x16x32_bf16 v[106:109], v[154:157], v[206:209], v[106:109]
	v_mfma_f32_16x16x32_bf16 v[94:97], v[146:149], v[214:217], v[94:97]
	v_mfma_f32_16x16x32_bf16 v[90:93], v[154:157], v[214:217], v[90:93]
	v_mfma_f32_16x16x32_bf16 v[78:81], v[146:149], v[222:225], v[78:81]
	v_mfma_f32_16x16x32_bf16 v[74:77], v[154:157], v[222:225], v[74:77]
	v_mfma_f32_16x16x32_bf16 v[126:129], v[150:153], v[202:205], v[126:129]
	v_mfma_f32_16x16x32_bf16 v[122:125], v[168:171], v[202:205], v[122:125]
	v_mfma_f32_16x16x32_bf16 v[110:113], v[150:153], v[210:213], v[110:113]
	v_mfma_f32_16x16x32_bf16 v[106:109], v[168:171], v[210:213], v[106:109]
	v_mfma_f32_16x16x32_bf16 v[94:97], v[150:153], v[218:221], v[94:97]
	v_mfma_f32_16x16x32_bf16 v[90:93], v[168:171], v[218:221], v[90:93]
	v_mfma_f32_16x16x32_bf16 v[78:81], v[150:153], v[226:229], v[78:81]
	v_mfma_f32_16x16x32_bf16 v[74:77], v[168:171], v[226:229], v[74:77]
	s_setprio 0
	s_setprio 1
	v_mfma_f32_16x16x32_bf16 v[118:121], v[172:175], v[198:201], v[118:121]
	v_mfma_f32_16x16x32_bf16 v[114:117], v[184:187], v[198:201], v[114:117]
	v_mfma_f32_16x16x32_bf16 v[102:105], v[172:175], v[206:209], v[102:105]
	v_mfma_f32_16x16x32_bf16 v[98:101], v[184:187], v[206:209], v[98:101]
	v_mfma_f32_16x16x32_bf16 v[86:89], v[172:175], v[214:217], v[86:89]
	v_mfma_f32_16x16x32_bf16 v[82:85], v[184:187], v[214:217], v[82:85]
	v_mfma_f32_16x16x32_bf16 v[70:73], v[172:175], v[222:225], v[70:73]
	v_mfma_f32_16x16x32_bf16 v[66:69], v[184:187], v[222:225], v[66:69]
	v_mfma_f32_16x16x32_bf16 v[118:121], v[180:183], v[202:205], v[118:121]
	v_mfma_f32_16x16x32_bf16 v[114:117], v[188:191], v[202:205], v[114:117]
	v_mfma_f32_16x16x32_bf16 v[102:105], v[180:183], v[210:213], v[102:105]
	v_mfma_f32_16x16x32_bf16 v[98:101], v[188:191], v[210:213], v[98:101]
	v_mfma_f32_16x16x32_bf16 v[86:89], v[180:183], v[218:221], v[86:89]
	v_mfma_f32_16x16x32_bf16 v[82:85], v[188:191], v[218:221], v[82:85]
	v_mfma_f32_16x16x32_bf16 v[70:73], v[180:183], v[226:229], v[70:73]
	v_mfma_f32_16x16x32_bf16 v[66:69], v[188:191], v[226:229], v[66:69]
	s_setprio 0
	s_barrier
	s_add_u32 s62, s76, 0x8000
	s_addc_u32 s63, s77, 0
	s_add_i32 s59, s59, s3
	v_lshl_add_u64 v[158:159], s[62:63], 0, v[132:133]
	s_mov_b32 m0, s59
	ds_read_b128 v[198:201], v164 offset:49152
	ds_read_b128 v[202:205], v164 offset:50176
	ds_read_b128 v[206:209], v164 offset:51200
	ds_read_b128 v[210:213], v164 offset:52224
	ds_read_b128 v[214:217], v164 offset:53248
	ds_read_b128 v[218:221], v164 offset:54272
	ds_read_b128 v[222:225], v164 offset:55296
	ds_read_b128 v[226:229], v164 offset:56320
	global_load_lds_dwordx4 v[158:159], off
	s_add_i32 m0, s59, 0x2000
	v_lshl_add_u64 v[158:159], s[62:63], 0, v[136:137]
	s_add_u32 s62, s76, 0xc000
	s_addc_u32 s63, s77, 0
	s_add_i32 s59, s64, s3
	global_load_lds_dwordx4 v[158:159], off
	v_lshl_add_u64 v[158:159], s[62:63], 0, v[132:133]
	s_mov_b32 m0, s59
	s_nop 0
	global_load_lds_dwordx4 v[158:159], off
	v_lshl_add_u64 v[158:159], s[62:63], 0, v[136:137]
	s_add_i32 m0, s59, 0x2000
	s_nop 0
	global_load_lds_dwordx4 v[158:159], off
	s_waitcnt vmcnt(6)
	s_waitcnt lgkmcnt(0)
	s_barrier
	s_setprio 1
	s_waitcnt lgkmcnt(0)
	v_mfma_f32_16x16x32_bf16 v[62:65], v[146:149], v[198:201], v[62:65]
	v_mfma_f32_16x16x32_bf16 v[58:61], v[154:157], v[198:201], v[58:61]
	v_mfma_f32_16x16x32_bf16 v[46:49], v[146:149], v[206:209], v[46:49]
	v_mfma_f32_16x16x32_bf16 v[42:45], v[154:157], v[206:209], v[42:45]
	v_mfma_f32_16x16x32_bf16 v[30:33], v[146:149], v[214:217], v[30:33]
	v_mfma_f32_16x16x32_bf16 v[26:29], v[154:157], v[214:217], v[26:29]
	v_mfma_f32_16x16x32_bf16 v[14:17], v[146:149], v[222:225], v[14:17]
	v_mfma_f32_16x16x32_bf16 v[10:13], v[154:157], v[222:225], v[10:13]
	v_mfma_f32_16x16x32_bf16 v[62:65], v[150:153], v[202:205], v[62:65]
	v_mfma_f32_16x16x32_bf16 v[58:61], v[168:171], v[202:205], v[58:61]
	v_mfma_f32_16x16x32_bf16 v[46:49], v[150:153], v[210:213], v[46:49]
	v_mfma_f32_16x16x32_bf16 v[42:45], v[168:171], v[210:213], v[42:45]
	v_mfma_f32_16x16x32_bf16 v[30:33], v[150:153], v[218:221], v[30:33]
	v_mfma_f32_16x16x32_bf16 v[26:29], v[168:171], v[218:221], v[26:29]
	v_mfma_f32_16x16x32_bf16 v[14:17], v[150:153], v[226:229], v[14:17]
	v_mfma_f32_16x16x32_bf16 v[10:13], v[168:171], v[226:229], v[10:13]
	s_setprio 0
	s_setprio 1
	v_mfma_f32_16x16x32_bf16 v[54:57], v[172:175], v[198:201], v[54:57]
	v_mfma_f32_16x16x32_bf16 v[50:53], v[184:187], v[198:201], v[50:53]
	v_mfma_f32_16x16x32_bf16 v[38:41], v[172:175], v[206:209], v[38:41]
	v_mfma_f32_16x16x32_bf16 v[34:37], v[184:187], v[206:209], v[34:37]
	v_mfma_f32_16x16x32_bf16 v[22:25], v[172:175], v[214:217], v[22:25]
	v_mfma_f32_16x16x32_bf16 v[18:21], v[184:187], v[214:217], v[18:21]
	v_mfma_f32_16x16x32_bf16 v[6:9], v[172:175], v[222:225], v[6:9]
	v_mfma_f32_16x16x32_bf16 v[2:5], v[184:187], v[222:225], v[2:5]
	v_mfma_f32_16x16x32_bf16 v[54:57], v[180:183], v[202:205], v[54:57]
	v_mfma_f32_16x16x32_bf16 v[50:53], v[188:191], v[202:205], v[50:53]
	v_mfma_f32_16x16x32_bf16 v[38:41], v[180:183], v[210:213], v[38:41]
	v_mfma_f32_16x16x32_bf16 v[34:37], v[188:191], v[210:213], v[34:37]
	v_mfma_f32_16x16x32_bf16 v[22:25], v[180:183], v[218:221], v[22:25]
	v_mfma_f32_16x16x32_bf16 v[18:21], v[188:191], v[218:221], v[18:21]
	v_mfma_f32_16x16x32_bf16 v[6:9], v[180:183], v[226:229], v[6:9]
	v_mfma_f32_16x16x32_bf16 v[2:5], v[188:191], v[226:229], v[2:5]
	s_setprio 0
	s_barrier
	s_add_i32 s58, s58, 2
	s_add_u32 s72, s72, 0x10000
	s_addc_u32 s73, s73, 0
	s_add_u32 s33, s33, 0x10000
	s_addc_u32 s56, s56, 0
	s_cmp_gt_u32 s58, 61
	s_cbranch_scc0 .LBB0_290
	s_and_b64 vcc, exec, s[12:13]
	s_cbranch_vccz .LBB0_293
	s_barrier

; #define PG8_STAGE(bufoff, gbase, voff) do { _Pragma("unroll") for (int _i = 0; _i < 2; ++_i) \
;         __builtin_amdgcn_global_load_lds((const unsigned*)((const char*)(gbase) + (voff)[_i]), (PG8_LAS unsigned*)(lds + (bufoff) + ldsw + _i * 8192), 16, 0, 0); } while (0)
; #define PG8_LDA(dst, b, h) do { _Pragma("unroll") for (int m = 0; m < 4; ++m) _Pragma("unroll") for (int k = 0; k < 2; ++k) dst[m][k] = *(const PG8_LAS bf16x8*)(lds + PG8_SA(b, h) + aoff + m * 2048 + k * 1024); } while (0)
; #define PG8_LDB(dst, b, h) do { _Pragma("unroll") for (int n = 0; n < 2; ++n) _Pragma("unroll") for (int k = 0; k < 2; ++k) dst[n][k] = *(const PG8_LAS bf16x8*)(lds + PG8_SB(b, h) + boff + n * 2048 + k * 1024); } while (0)
; template <class Epi, class Sched, bool ALIGN_EPI = false, bool SP2 = false>
; __device__ __forceinline__ void gemm_phase(PG8_LAS unsigned char* lds, const Gemm g, const Sched& S, const Epi& E) {
;     ...
;         for (; t < tend; t += 2) {
;             const bool last = (t == nt - 2);
;             const char* a1 = cA + (size_t)(t + 1) * kstep;
;             const char* a2 = last ? nA : cA + (size_t)(t + 2) * kstep; const char* b2 = last ? nB : cB + (size_t)(t + 2) * kstep;
;             const char* a3 = a2 + kstep; const char* b3 = b2 + kstep;
;             if (last && has_next) S.a_ready(nxt);
;             if constexpr (SP2) {
;             PG8_LDB(B0, 0, 0); PG8_LDB(B1, 0, 1); PG8_SCHED; PG8_LDA(At, 0, 0); PG8_STAGE(PG8_SA(1, 1), a1 + hstep, voffA);
;             PG8_WAIT_V(8); PG8_WAIT_L(0); PG8_BAR; PG8_MMA(0, 0, At, B0); PG8_MMA(0, 1, At, B1); PG8_BAR; PG8_SCHED;
;             PG8_LDA(At, 0, 1); PG8_STAGE(PG8_SB(0, 0), b2, voffB); PG8_STAGE(PG8_SB(0, 1), b2 + hstep, voffB); PG8_STAGE(PG8_SA(0, 0), a2, voffA);
;             PG8_WAIT_V(8); PG8_WAIT_L(0); PG8_BAR; PG8_MMA(1, 0, At, B0); PG8_MMA(1, 1, At, B1); PG8_BAR; PG8_SCHED;
;             PG8_LDB(B0, 1, 0); PG8_LDB(B1, 1, 1); PG8_SCHED; PG8_LDA(At, 1, 0); PG8_STAGE(PG8_SA(0, 1), a2 + hstep, voffA);
;             PG8_WAIT_V(8); PG8_WAIT_L(0); PG8_BAR; PG8_MMA(0, 0, At, B0); PG8_MMA(0, 1, At, B1); PG8_BAR; PG8_SCHED;
;             PG8_LDA(At, 1, 1); PG8_STAGE(PG8_SB(1, 0), b3, voffB); PG8_STAGE(PG8_SB(1, 1), b3 + hstep, voffB); PG8_STAGE(PG8_SA(1, 0), a3, voffA);
;             PG8_WAIT_V(8); PG8_WAIT_L(0); PG8_BAR; PG8_MMA(1, 0, At, B0); PG8_MMA(1, 1, At, B1); PG8_BAR; PG8_SCHED;
.LBB0_757:
	ds_read_b128 v[154:157], v149
	ds_read_b128 v[158:161], v149 offset:1024
	ds_read_b128 v[162:165], v149 offset:2048
	ds_read_b128 v[166:169], v149 offset:3072
	ds_read_b128 v[170:173], v150
	ds_read_b128 v[174:177], v150 offset:1024
	ds_read_b128 v[180:183], v150 offset:2048
	ds_read_b128 v[184:187], v150 offset:3072
	s_add_u32 s46, s44, 0x4000
	s_addc_u32 s47, s45, 0
	s_cmp_eq_u32 s70, 60
	s_cselect_b32 s50, s39, s46
	s_cselect_b32 s51, s17, s47
	s_cselect_b32 s48, s41, s68
	s_cselect_b32 s49, s15, s69
	s_add_u32 s46, s50, 0x8000
	s_addc_u32 s47, s51, 0
	s_sub_u32 s46, s44, 0x4000
	s_subb_u32 s47, s45, 0
	v_lshl_add_u64 v[146:147], s[46:47], 0, v[130:131]
	s_mov_b32 m0, s57
	s_nop 0
	global_load_lds_dwordx4 v[146:147], off
	v_lshl_add_u64 v[146:147], s[46:47], 0, v[134:135]
	s_mov_b32 m0, s58
	s_nop 0
	global_load_lds_dwordx4 v[146:147], off
	v_lshl_add_u64 v[146:147], s[44:45], 0, v[138:139]
	s_add_i32 m0, s26, 0xc000
	ds_read_b128 v[188:191], v151
	ds_read_b128 v[198:201], v151 offset:1024
	ds_read_b128 v[202:205], v151 offset:2048
	ds_read_b128 v[206:209], v151 offset:3072
	ds_read_b128 v[210:213], v151 offset:4096
	ds_read_b128 v[214:217], v151 offset:5120
	ds_read_b128 v[218:221], v151 offset:6144
	ds_read_b128 v[222:225], v151 offset:7168
	global_load_lds_dwordx4 v[146:147], off
	v_lshl_add_u64 v[146:147], s[44:45], 0, v[140:141]
	s_add_i32 m0, s26, 0xe000
	s_nop 0
	global_load_lds_dwordx4 v[146:147], off
	s_waitcnt vmcnt(8)
	s_waitcnt lgkmcnt(0)
	s_barrier
	s_setprio 1
	s_waitcnt lgkmcnt(0)
	v_mfma_f32_16x16x32_bf16 v[126:129], v[154:157], v[188:191], v[126:129]
	v_mfma_f32_16x16x32_bf16 v[122:125], v[162:165], v[188:191], v[122:125]
	v_mfma_f32_16x16x32_bf16 v[110:113], v[154:157], v[202:205], v[110:113]
	v_mfma_f32_16x16x32_bf16 v[106:109], v[162:165], v[202:205], v[106:109]
	v_mfma_f32_16x16x32_bf16 v[94:97], v[154:157], v[210:213], v[94:97]
	v_mfma_f32_16x16x32_bf16 v[90:93], v[162:165], v[210:213], v[90:93]
	v_mfma_f32_16x16x32_bf16 v[78:81], v[154:157], v[218:221], v[78:81]
	v_mfma_f32_16x16x32_bf16 v[74:77], v[162:165], v[218:221], v[74:77]
	v_mfma_f32_16x16x32_bf16 v[126:129], v[158:161], v[198:201], v[126:129]
	v_mfma_f32_16x16x32_bf16 v[122:125], v[166:169], v[198:201], v[122:125]
	v_mfma_f32_16x16x32_bf16 v[110:113], v[158:161], v[206:209], v[110:113]
	v_mfma_f32_16x16x32_bf16 v[106:109], v[166:169], v[206:209], v[106:109]
	v_mfma_f32_16x16x32_bf16 v[94:97], v[158:161], v[214:217], v[94:97]
	v_mfma_f32_16x16x32_bf16 v[90:93], v[166:169], v[214:217], v[90:93]
	v_mfma_f32_16x16x32_bf16 v[78:81], v[158:161], v[222:225], v[78:81]
	v_mfma_f32_16x16x32_bf16 v[74:77], v[166:169], v[222:225], v[74:77]
	s_setprio 0
	s_setprio 1
	v_mfma_f32_16x16x32_bf16 v[118:121], v[170:173], v[188:191], v[118:121]
	v_mfma_f32_16x16x32_bf16 v[114:117], v[180:183], v[188:191], v[114:117]
	v_mfma_f32_16x16x32_bf16 v[102:105], v[170:173], v[202:205], v[102:105]
	v_mfma_f32_16x16x32_bf16 v[98:101], v[180:183], v[202:205], v[98:101]
	v_mfma_f32_16x16x32_bf16 v[86:89], v[170:173], v[210:213], v[86:89]
	v_mfma_f32_16x16x32_bf16 v[82:85], v[180:183], v[210:213], v[82:85]
	v_mfma_f32_16x16x32_bf16 v[70:73], v[170:173], v[218:221], v[70:73]
	v_mfma_f32_16x16x32_bf16 v[66:69], v[180:183], v[218:221], v[66:69]
	v_mfma_f32_16x16x32_bf16 v[118:121], v[174:177], v[198:201], v[118:121]
	v_mfma_f32_16x16x32_bf16 v[114:117], v[184:187], v[198:201], v[114:117]
	v_mfma_f32_16x16x32_bf16 v[102:105], v[174:177], v[206:209], v[102:105]
	v_mfma_f32_16x16x32_bf16 v[98:101], v[184:187], v[206:209], v[98:101]
	v_mfma_f32_16x16x32_bf16 v[86:89], v[174:177], v[214:217], v[86:89]
	v_mfma_f32_16x16x32_bf16 v[82:85], v[184:187], v[214:217], v[82:85]
	v_mfma_f32_16x16x32_bf16 v[70:73], v[174:177], v[222:225], v[70:73]
	v_mfma_f32_16x16x32_bf16 v[66:69], v[184:187], v[222:225], v[66:69]
	s_setprio 0
	s_barrier
	s_add_i32 s71, s59, s3
	v_lshl_add_u64 v[146:147], s[48:49], 0, v[132:133]
	s_mov_b32 m0, s71
	ds_read_b128 v[188:191], v151 offset:16384
	ds_read_b128 v[198:201], v151 offset:17408
	ds_read_b128 v[202:205], v151 offset:18432
	ds_read_b128 v[206:209], v151 offset:19456
	ds_read_b128 v[210:213], v151 offset:20480
	ds_read_b128 v[214:217], v151 offset:21504
	ds_read_b128 v[218:221], v151 offset:22528
	ds_read_b128 v[222:225], v151 offset:23552
	global_load_lds_dwordx4 v[146:147], off
	s_add_i32 m0, s71, 0x2000
	s_add_u32 s72, s48, 0x4000
	v_lshl_add_u64 v[146:147], s[48:49], 0, v[136:137]
	s_addc_u32 s73, s49, 0
	s_add_i32 s71, s61, s3
	global_load_lds_dwordx4 v[146:147], off
	v_lshl_add_u64 v[146:147], s[72:73], 0, v[132:133]
	s_mov_b32 m0, s71
	s_nop 0
	global_load_lds_dwordx4 v[146:147], off
	v_lshl_add_u64 v[146:147], s[72:73], 0, v[136:137]
	s_add_i32 m0, s71, 0x2000
	s_nop 0
	global_load_lds_dwordx4 v[146:147], off
	s_waitcnt vmcnt(6)
	s_waitcnt lgkmcnt(0)
	s_barrier
; #define PG8_STAGE(bufoff, gbase, voff) do { _Pragma("unroll") for (int _i = 0; _i < 2; ++_i) \
;         __builtin_amdgcn_global_load_lds((const unsigned*)((const char*)(gbase) + (voff)[_i]), (PG8_LAS unsigned*)(lds + (bufoff) + ldsw + _i * 8192), 16, 0, 0); } while (0)
; #define PG8_LDA(dst, b, h) do { _Pragma("unroll") for (int m = 0; m < 4; ++m) _Pragma("unroll") for (int k = 0; k < 2; ++k) dst[m][k] = *(const PG8_LAS bf16x8*)(lds + PG8_SA(b, h) + aoff + m * 2048 + k * 1024); } while (0)
; #define PG8_LDB(dst, b, h) do { _Pragma("unroll") for (int n = 0; n < 2; ++n) _Pragma("unroll") for (int k = 0; k < 2; ++k) dst[n][k] = *(const PG8_LAS bf16x8*)(lds + PG8_SB(b, h) + boff + n * 2048 + k * 1024); } while (0)
; #define PG8_MMA(ai, bj, At, Bt) do { __builtin_amdgcn_s_setprio(1); _Pragma("unroll") for (int m = 0; m < 4; ++m) _Pragma("unroll") for (int n = 0; n < 2; ++n) _Pragma("unroll") for (int k = 0; k < 2; ++k) \
;         acc[ai][bj][m][n] = __builtin_amdgcn_mfma_f32_16x16x32_bf16(Bt[n][k], At[m][k], acc[ai][bj][m][n], 0, 0, 0); __builtin_amdgcn_s_setprio(0); } while (0)
; #define PG8_WAIT_V(n) asm volatile("s_waitcnt vmcnt(" #n ")" ::: "memory")
; #define PG8_WAIT_L(n) asm volatile("s_waitcnt lgkmcnt(" #n ")" ::: "memory")
; #define PG8_BAR __builtin_amdgcn_s_barrier()
; #define PG8_SCHED __builtin_amdgcn_sched_barrier(0)
; template <class Epi, class Sched, bool ALIGN_EPI = false, bool SP2 = false>
; __device__ __forceinline__ void gemm_phase(PG8_LAS unsigned char* lds, const Gemm g, const Sched& S, const Epi& E) {
;     ...
;             PG8_LDB(B0, 0, 0); PG8_LDB(B1, 0, 1); PG8_SCHED; PG8_LDA(At, 0, 0); PG8_STAGE(PG8_SA(1, 1), a1 + hstep, voffA);
;             PG8_WAIT_V(8); PG8_WAIT_L(0); PG8_BAR; PG8_MMA(0, 0, At, B0); PG8_MMA(0, 1, At, B1); PG8_BAR; PG8_SCHED;
;             PG8_LDA(At, 0, 1); PG8_STAGE(PG8_SB(0, 0), b2, voffB); PG8_STAGE(PG8_SB(0, 1), b2 + hstep, voffB); PG8_STAGE(PG8_SA(0, 0), a2, voffA);
;             PG8_WAIT_V(8); PG8_WAIT_L(0); PG8_BAR; PG8_MMA(1, 0, At, B0); PG8_MMA(1, 1, At, B1); PG8_BAR; PG8_SCHED;
;             PG8_LDB(B0, 1, 0); PG8_LDB(B1, 1, 1); PG8_SCHED; PG8_LDA(At, 1, 0); PG8_STAGE(PG8_SA(0, 1), a2 + hstep, voffA);
;             PG8_WAIT_V(8); PG8_WAIT_L(0); PG8_BAR; PG8_MMA(0, 0, At, B0); PG8_MMA(0, 1, At, B1); PG8_BAR; PG8_SCHED;
	s_setprio 1
	s_waitcnt lgkmcnt(0)
	v_mfma_f32_16x16x32_bf16 v[62:65], v[154:157], v[188:191], v[62:65]
	v_mfma_f32_16x16x32_bf16 v[58:61], v[162:165], v[188:191], v[58:61]
	v_mfma_f32_16x16x32_bf16 v[46:49], v[154:157], v[202:205], v[46:49]
	v_mfma_f32_16x16x32_bf16 v[42:45], v[162:165], v[202:205], v[42:45]
	v_mfma_f32_16x16x32_bf16 v[30:33], v[154:157], v[210:213], v[30:33]
	v_mfma_f32_16x16x32_bf16 v[26:29], v[162:165], v[210:213], v[26:29]
	v_mfma_f32_16x16x32_bf16 v[14:17], v[154:157], v[218:221], v[14:17]
	v_mfma_f32_16x16x32_bf16 v[10:13], v[162:165], v[218:221], v[10:13]
	v_mfma_f32_16x16x32_bf16 v[62:65], v[158:161], v[198:201], v[62:65]
	v_mfma_f32_16x16x32_bf16 v[58:61], v[166:169], v[198:201], v[58:61]
	v_mfma_f32_16x16x32_bf16 v[46:49], v[158:161], v[206:209], v[46:49]
	v_mfma_f32_16x16x32_bf16 v[42:45], v[166:169], v[206:209], v[42:45]
	v_mfma_f32_16x16x32_bf16 v[30:33], v[158:161], v[214:217], v[30:33]
	v_mfma_f32_16x16x32_bf16 v[26:29], v[166:169], v[214:217], v[26:29]
	v_mfma_f32_16x16x32_bf16 v[14:17], v[158:161], v[222:225], v[14:17]
	v_mfma_f32_16x16x32_bf16 v[10:13], v[166:169], v[222:225], v[10:13]
	s_setprio 0
	s_setprio 1
	v_mfma_f32_16x16x32_bf16 v[54:57], v[170:173], v[188:191], v[54:57]
	v_mfma_f32_16x16x32_bf16 v[50:53], v[180:183], v[188:191], v[50:53]
	v_mfma_f32_16x16x32_bf16 v[38:41], v[170:173], v[202:205], v[38:41]
	v_mfma_f32_16x16x32_bf16 v[34:37], v[180:183], v[202:205], v[34:37]
	v_mfma_f32_16x16x32_bf16 v[22:25], v[170:173], v[210:213], v[22:25]
	v_mfma_f32_16x16x32_bf16 v[18:21], v[180:183], v[210:213], v[18:21]
	v_mfma_f32_16x16x32_bf16 v[6:9], v[170:173], v[218:221], v[6:9]
	v_mfma_f32_16x16x32_bf16 v[2:5], v[180:183], v[218:221], v[2:5]
	v_mfma_f32_16x16x32_bf16 v[54:57], v[174:177], v[198:201], v[54:57]
	v_mfma_f32_16x16x32_bf16 v[50:53], v[184:187], v[198:201], v[50:53]
	v_mfma_f32_16x16x32_bf16 v[38:41], v[174:177], v[206:209], v[38:41]
	v_mfma_f32_16x16x32_bf16 v[34:37], v[184:187], v[206:209], v[34:37]
	v_mfma_f32_16x16x32_bf16 v[22:25], v[174:177], v[214:217], v[22:25]
	v_mfma_f32_16x16x32_bf16 v[18:21], v[184:187], v[214:217], v[18:21]
	v_mfma_f32_16x16x32_bf16 v[6:9], v[174:177], v[222:225], v[6:9]
	v_mfma_f32_16x16x32_bf16 v[2:5], v[184:187], v[222:225], v[2:5]
	s_setprio 0
	s_barrier
	s_add_i32 s71, 0, 0x18000
	v_add_u32_e32 v146, s71, v1
	s_add_i32 s72, 0, 0x1c000
	ds_read_b128 v[154:157], v146
	ds_read_b128 v[158:161], v146 offset:1024
	ds_read_b128 v[162:165], v146 offset:2048
	ds_read_b128 v[166:169], v146 offset:3072
	v_add_u32_e32 v146, s72, v1
	ds_read_b128 v[170:173], v146
	ds_read_b128 v[174:177], v146 offset:1024
	ds_read_b128 v[180:183], v146 offset:2048
	ds_read_b128 v[184:187], v146 offset:3072
	v_lshl_add_u64 v[146:147], s[50:51], 0, v[130:131]
	s_mov_b32 m0, s26
	s_nop 0
	global_load_lds_dwordx4 v[146:147], off
	v_lshl_add_u64 v[146:147], s[50:51], 0, v[134:135]
	s_mov_b32 m0, s27
	s_nop 0
	global_load_lds_dwordx4 v[146:147], off
	s_add_u32 s50, s50, 0x4000
	s_addc_u32 s51, s51, 0
	s_mov_b32 m0, s28
	v_lshl_add_u64 v[146:147], s[50:51], 0, v[130:131]
	ds_read_b128 v[188:191], v151 offset:32768
	ds_read_b128 v[198:201], v151 offset:33792
	ds_read_b128 v[202:205], v151 offset:34816
	ds_read_b128 v[206:209], v151 offset:35840
	ds_read_b128 v[210:213], v151 offset:36864
	ds_read_b128 v[214:217], v151 offset:37888
	ds_read_b128 v[218:221], v151 offset:38912
	ds_read_b128 v[222:225], v151 offset:39936
	global_load_lds_dwordx4 v[146:147], off
	v_lshl_add_u64 v[146:147], s[50:51], 0, v[134:135]
	s_mov_b32 m0, s29
	s_nop 0
	global_load_lds_dwordx4 v[146:147], off
	s_waitcnt vmcnt(8)
	s_waitcnt lgkmcnt(0)
	s_barrier
	s_setprio 1
	s_waitcnt lgkmcnt(0)
	v_mfma_f32_16x16x32_bf16 v[126:129], v[154:157], v[188:191], v[126:129]
	v_mfma_f32_16x16x32_bf16 v[122:125], v[162:165], v[188:191], v[122:125]
	v_mfma_f32_16x16x32_bf16 v[110:113], v[154:157], v[202:205], v[110:113]
	v_mfma_f32_16x16x32_bf16 v[106:109], v[162:165], v[202:205], v[106:109]
	v_mfma_f32_16x16x32_bf16 v[94:97], v[154:157], v[210:213], v[94:97]
	v_mfma_f32_16x16x32_bf16 v[90:93], v[162:165], v[210:213], v[90:93]
	v_mfma_f32_16x16x32_bf16 v[78:81], v[154:157], v[218:221], v[78:81]
	v_mfma_f32_16x16x32_bf16 v[74:77], v[162:165], v[218:221], v[74:77]
	v_mfma_f32_16x16x32_bf16 v[126:129], v[158:161], v[198:201], v[126:129]
	v_mfma_f32_16x16x32_bf16 v[122:125], v[166:169], v[198:201], v[122:125]
	v_mfma_f32_16x16x32_bf16 v[110:113], v[158:161], v[206:209], v[110:113]
	v_mfma_f32_16x16x32_bf16 v[106:109], v[166:169], v[206:209], v[106:109]
	v_mfma_f32_16x16x32_bf16 v[94:97], v[158:161], v[214:217], v[94:97]
	v_mfma_f32_16x16x32_bf16 v[90:93], v[166:169], v[214:217], v[90:93]
	v_mfma_f32_16x16x32_bf16 v[78:81], v[158:161], v[222:225], v[78:81]
	v_mfma_f32_16x16x32_bf16 v[74:77], v[166:169], v[222:225], v[74:77]
	s_setprio 0
	s_setprio 1
	v_mfma_f32_16x16x32_bf16 v[118:121], v[170:173], v[188:191], v[118:121]
	v_mfma_f32_16x16x32_bf16 v[114:117], v[180:183], v[188:191], v[114:117]
	v_mfma_f32_16x16x32_bf16 v[102:105], v[170:173], v[202:205], v[102:105]
	v_mfma_f32_16x16x32_bf16 v[98:101], v[180:183], v[202:205], v[98:101]
	v_mfma_f32_16x16x32_bf16 v[86:89], v[170:173], v[210:213], v[86:89]
	v_mfma_f32_16x16x32_bf16 v[82:85], v[180:183], v[210:213], v[82:85]
	v_mfma_f32_16x16x32_bf16 v[70:73], v[170:173], v[218:221], v[70:73]
	v_mfma_f32_16x16x32_bf16 v[66:69], v[180:183], v[218:221], v[66:69]
	v_mfma_f32_16x16x32_bf16 v[118:121], v[174:177], v[198:201], v[118:121]
	v_mfma_f32_16x16x32_bf16 v[114:117], v[184:187], v[198:201], v[114:117]
	v_mfma_f32_16x16x32_bf16 v[102:105], v[174:177], v[206:209], v[102:105]
	v_mfma_f32_16x16x32_bf16 v[98:101], v[184:187], v[206:209], v[98:101]
	v_mfma_f32_16x16x32_bf16 v[86:89], v[174:177], v[214:217], v[86:89]
	v_mfma_f32_16x16x32_bf16 v[82:85], v[184:187], v[214:217], v[82:85]
	v_mfma_f32_16x16x32_bf16 v[70:73], v[174:177], v[222:225], v[70:73]
	v_mfma_f32_16x16x32_bf16 v[66:69], v[184:187], v[222:225], v[66:69]
	s_setprio 0
	s_barrier
; __host__ __device__ __forceinline__ size_t blk(int r, int k, int K) { return (((size_t)((r >> 8) * (K >> 6) + (k >> 6))) << 14) + (size_t)(((r & 255) << 6) + (k & 63)); }
; __device__ __forceinline__ float bflo(unsigned w) { return __uint_as_float(w << 16); }
; __device__ __forceinline__ float bfhi(unsigned w) { return __uint_as_float(w & 0xffff0000u); }
; #define PG8_STAGE(bufoff, gbase, voff) do { _Pragma("unroll") for (int _i = 0; _i < 2; ++_i) \
;         __builtin_amdgcn_global_load_lds((const unsigned*)((const char*)(gbase) + (voff)[_i]), (PG8_LAS unsigned*)(lds + (bufoff) + ldsw + _i * 8192), 16, 0, 0); } while (0)
; #define PG8_LDA(dst, b, h) do { _Pragma("unroll") for (int m = 0; m < 4; ++m) _Pragma("unroll") for (int k = 0; k < 2; ++k) dst[m][k] = *(const PG8_LAS bf16x8*)(lds + PG8_SA(b, h) + aoff + m * 2048 + k * 1024); } while (0)
; #define PG8_WAIT_V(n) asm volatile("s_waitcnt vmcnt(" #n ")" ::: "memory")
; #define PG8_WAIT_L(n) asm volatile("s_waitcnt lgkmcnt(" #n ")" ::: "memory")
;     __device__ __forceinline__ void operator()(const f32x4 (&acc)[2][2][4][2], const Unit& u, int wr, int wc, int fr, int fq) const {
;         const int row0 = u.pm * BM + wr * 64 + fr, col0 = u.pn * BM + wc * 32 + 8 * fq;
; #pragma unroll
;         for (int ai = 0; ai < 2; ++ai)
; #pragma unroll
;             for (int m = 0; m < 4; ++m) { const int row = row0 + ai * HALF + m * 16; const size_t off = (size_t)row * D + col0; float s = 0.f;
; #pragma unroll
;                 for (int bj = 0; bj < 2; ++bj) {
;                     f32x4 v0, v1;
;                     if (MODE == 0) { v0 = *(const f32x4*)(base + off + bj * HALF); v1 = *(const f32x4*)(base + off + bj * HALF + 4); }
;                     else { const u32x4 r = *(const u32x4*)(bb + blk(row, col0 + bj * HALF, D)); v0 = (f32x4){bflo(r.x), bfhi(r.x), bflo(r.y), bfhi(r.y)}; v1 = (f32x4){bflo(r.z), bfhi(r.z), bflo(r.w), bfhi(r.w)}; }
; template <class Epi, class Sched, bool ALIGN_EPI = false, bool SP2 = false>
; __device__ __forceinline__ void gemm_phase(PG8_LAS unsigned char* lds, const Gemm g, const Sched& S, const Epi& E) {
;     ...
;             PG8_LDA(At, 1, 1); PG8_STAGE(PG8_SB(1, 0), b3, voffB); PG8_STAGE(PG8_SB(1, 1), b3 + hstep, voffB); PG8_STAGE(PG8_SA(1, 0), a3, voffA);
;             PG8_WAIT_V(8); PG8_WAIT_L(0); PG8_BAR; PG8_MMA(1, 0, At, B0); PG8_MMA(1, 1, At, B1); PG8_BAR; PG8_SCHED;
	s_add_u32 s50, s48, 0x8000
	s_addc_u32 s51, s49, 0
	s_add_i32 s71, s71, s3
	v_lshl_add_u64 v[146:147], s[50:51], 0, v[132:133]
	s_mov_b32 m0, s71
	ds_read_b128 v[188:191], v151 offset:49152
	ds_read_b128 v[198:201], v151 offset:50176
	ds_read_b128 v[202:205], v151 offset:51200
	ds_read_b128 v[206:209], v151 offset:52224
	ds_read_b128 v[210:213], v151 offset:53248
	ds_read_b128 v[214:217], v151 offset:54272
	ds_read_b128 v[218:221], v151 offset:55296
	ds_read_b128 v[222:225], v151 offset:56320
	global_load_lds_dwordx4 v[146:147], off
	s_add_i32 m0, s71, 0x2000
	s_add_u32 s48, s48, 0xc000
	v_lshl_add_u64 v[146:147], s[50:51], 0, v[136:137]
	s_addc_u32 s49, s49, 0
	s_add_i32 s50, s72, s3
	global_load_lds_dwordx4 v[146:147], off
	v_lshl_add_u64 v[146:147], s[48:49], 0, v[132:133]
	s_mov_b32 m0, s50
	s_nop 0
	global_load_lds_dwordx4 v[146:147], off
	v_lshl_add_u64 v[146:147], s[48:49], 0, v[136:137]
	s_add_i32 m0, s50, 0x2000
	s_nop 0
	global_load_lds_dwordx4 v[146:147], off
	s_waitcnt vmcnt(6)
	s_waitcnt lgkmcnt(0)
	s_barrier
	s_setprio 1
	s_waitcnt lgkmcnt(0)
	v_mfma_f32_16x16x32_bf16 v[62:65], v[154:157], v[188:191], v[62:65]
	v_mfma_f32_16x16x32_bf16 v[58:61], v[162:165], v[188:191], v[58:61]
	v_mfma_f32_16x16x32_bf16 v[46:49], v[154:157], v[202:205], v[46:49]
	v_mfma_f32_16x16x32_bf16 v[42:45], v[162:165], v[202:205], v[42:45]
	v_mfma_f32_16x16x32_bf16 v[30:33], v[154:157], v[210:213], v[30:33]
	v_mfma_f32_16x16x32_bf16 v[26:29], v[162:165], v[210:213], v[26:29]
	v_mfma_f32_16x16x32_bf16 v[14:17], v[154:157], v[218:221], v[14:17]
	v_mfma_f32_16x16x32_bf16 v[10:13], v[162:165], v[218:221], v[10:13]
	v_mfma_f32_16x16x32_bf16 v[62:65], v[158:161], v[198:201], v[62:65]
	v_mfma_f32_16x16x32_bf16 v[58:61], v[166:169], v[198:201], v[58:61]
	v_mfma_f32_16x16x32_bf16 v[46:49], v[158:161], v[206:209], v[46:49]
	v_mfma_f32_16x16x32_bf16 v[42:45], v[166:169], v[206:209], v[42:45]
	v_mfma_f32_16x16x32_bf16 v[30:33], v[158:161], v[214:217], v[30:33]
	v_mfma_f32_16x16x32_bf16 v[26:29], v[166:169], v[214:217], v[26:29]
	v_mfma_f32_16x16x32_bf16 v[14:17], v[158:161], v[222:225], v[14:17]
	v_mfma_f32_16x16x32_bf16 v[10:13], v[166:169], v[222:225], v[10:13]
	s_setprio 0
	s_setprio 1
	v_mfma_f32_16x16x32_bf16 v[54:57], v[170:173], v[188:191], v[54:57]
	v_mfma_f32_16x16x32_bf16 v[50:53], v[180:183], v[188:191], v[50:53]
	v_mfma_f32_16x16x32_bf16 v[38:41], v[170:173], v[202:205], v[38:41]
	v_mfma_f32_16x16x32_bf16 v[34:37], v[180:183], v[202:205], v[34:37]
	v_mfma_f32_16x16x32_bf16 v[22:25], v[170:173], v[210:213], v[22:25]
	v_mfma_f32_16x16x32_bf16 v[18:21], v[180:183], v[210:213], v[18:21]
	v_mfma_f32_16x16x32_bf16 v[6:9], v[170:173], v[218:221], v[6:9]
	v_mfma_f32_16x16x32_bf16 v[2:5], v[180:183], v[218:221], v[2:5]
	v_mfma_f32_16x16x32_bf16 v[54:57], v[174:177], v[198:201], v[54:57]
	v_mfma_f32_16x16x32_bf16 v[50:53], v[184:187], v[198:201], v[50:53]
	v_mfma_f32_16x16x32_bf16 v[38:41], v[174:177], v[206:209], v[38:41]
	v_mfma_f32_16x16x32_bf16 v[34:37], v[184:187], v[206:209], v[34:37]
	v_mfma_f32_16x16x32_bf16 v[22:25], v[174:177], v[214:217], v[22:25]
	v_mfma_f32_16x16x32_bf16 v[18:21], v[184:187], v[214:217], v[18:21]
	v_mfma_f32_16x16x32_bf16 v[6:9], v[174:177], v[222:225], v[6:9]
	v_mfma_f32_16x16x32_bf16 v[2:5], v[184:187], v[222:225], v[2:5]
	s_setprio 0
	s_barrier
	s_add_i32 s70, s70, 2
	s_add_u32 s44, s44, 0x10000
	s_addc_u32 s45, s45, 0
	s_add_u32 s68, s68, 0x10000
	s_addc_u32 s69, s69, 0
	s_cmp_gt_u32 s70, 61
	s_cbranch_scc0 .LBB0_757
	s_and_b64 vcc, exec, s[12:13]
	s_cbranch_vccz .LBB0_760
	s_barrier
.LBB0_760:
	s_lshl_b32 s15, s40, 8
	s_add_i32 s15, s15, s35
	s_lshl_b32 s17, s38, 8
	v_or_b32_e32 v146, s15, v195
	s_or_b32 s17, s17, s56
	s_ashr_i32 s15, s15, 2
	s_and_b32 s40, s15, 0xffffffc0
	s_ashr_i32 s15, s17, 6
	s_add_i32 s38, s40, s15
	v_lshlrev_b32_e32 v147, 6, v146
	s_ashr_i32 s39, s38, 31
	v_and_or_b32 v147, v147, s62, v148
	s_lshl_b64 s[38:39], s[38:39], 14
	v_or_b32_e32 v154, s38, v147
	v_mov_b32_e32 v155, s39
	v_lshlrev_b64 v[158:159], 1, v[154:155]
	v_lshl_add_u64 v[154:155], s[42:43], 0, v[158:159]
	v_lshl_add_u64 v[176:177], s[42:43], 0, v[158:159]
	global_load_dwordx4 v[154:157], v[154:155], off
	s_mov_b32 s98, 0x1000
	s_mov_b32 s99, 0
	s_mov_b32 s100, 0x10000
	s_mov_b32 s101, 0
	v_lshl_add_u64 v[222:223], v[176:177], 0, s[100:101]
	s_mov_b32 s100, 0x3000
	global_load_dwordx4 v[168:171], v[222:223], off
	global_load_dwordx4 v[172:175], v[176:177], off offset:2048
	global_load_dwordx4 v[180:183], v[222:223], off offset:2048
	v_lshl_add_u64 v[176:177], v[176:177], 0, s[98:99]
	v_lshl_add_u64 v[222:223], v[222:223], 0, s[98:99]
	global_load_dwordx4 v[184:187], v[176:177], off
	global_load_dwordx4 v[188:191], v[222:223], off
	global_load_dwordx4 v[198:201], v[176:177], off offset:2048
	global_load_dwordx4 v[202:205], v[222:223], off offset:2048
	v_lshl_add_u64 v[176:177], v[176:177], 0, s[100:101]
	v_lshl_add_u64 v[222:223], v[222:223], 0, s[100:101]
	global_load_dwordx4 v[206:209], v[176:177], off
	global_load_dwordx4 v[210:213], v[222:223], off
	global_load_dwordx4 v[214:217], v[176:177], off offset:2048
	global_load_dwordx4 v[218:221], v[222:223], off offset:2048
	s_or_b32 s17, s15, 2
	s_add_i32 s40, s40, s17
	s_ashr_i32 s41, s40, 31
	s_lshl_b64 s[40:41], s[40:41], 14
	v_or_b32_e32 v160, s40, v147
	v_mov_b32_e32 v161, s41
	v_lshlrev_b64 v[160:161], 1, v[160:161]
	v_lshl_add_u64 v[158:159], s[18:19], 0, v[158:159]
	v_lshl_add_u64 v[162:163], s[42:43], 0, v[160:161]
	v_xor_b32_e32 v147, 32, v152
	s_waitcnt vmcnt(0)
; __host__ __device__ __forceinline__ size_t blk(int r, int k, int K) { return (((size_t)((r >> 8) * (K >> 6) + (k >> 6))) << 14) + (size_t)(((r & 255) << 6) + (k & 63)); }
; __device__ __forceinline__ float bflo(unsigned w) { return __uint_as_float(w << 16); }
; __device__ __forceinline__ float bfhi(unsigned w) { return __uint_as_float(w & 0xffff0000u); }
; __device__ __forceinline__ unsigned pk2(float lo, float hi) { f32x2 v = {lo, hi}; bf16x2_t b = __builtin_convertvector(v, bf16x2_t); return __builtin_bit_cast(unsigned, b); }
;     __device__ __forceinline__ void operator()(const f32x4 (&acc)[2][2][4][2], const Unit& u, int wr, int wc, int fr, int fq) const {
;     ...
;             for (int m = 0; m < 4; ++m) { const int row = row0 + ai * HALF + m * 16; const size_t off = (size_t)row * D + col0; float s = 0.f;
; #pragma unroll
;                 for (int bj = 0; bj < 2; ++bj) {
;                     f32x4 v0, v1;
;                     if (MODE == 0) { v0 = *(const f32x4*)(base + off + bj * HALF); v1 = *(const f32x4*)(base + off + bj * HALF + 4); }
;                     else { const u32x4 r = *(const u32x4*)(bb + blk(row, col0 + bj * HALF, D)); v0 = (f32x4){bflo(r.x), bfhi(r.x), bflo(r.y), bfhi(r.y)}; v1 = (f32x4){bflo(r.z), bfhi(r.z), bflo(r.w), bfhi(r.w)}; }
;                     v0 += acc[ai][bj][m][0] * alpha; v1 += acc[ai][bj][m][1] * alpha;
;                     if (MODE == 2) { *(f32x4*)(out + off + bj * HALF) = v0; *(f32x4*)(out + off + bj * HALF + 4) = v1; }
;                     else {
;                         s += (v0[0] * v0[0] + v0[1] * v0[1]) + (v0[2] * v0[2] + v0[3] * v0[3]) + (v1[0] * v1[0] + v1[1] * v1[1]) + (v1[2] * v1[2] + v1[3] * v1[3]);
;                         u32x4 w; w.x = pk2(v0[0], v0[1]); w.y = pk2(v0[2], v0[3]); w.z = pk2(v1[0], v1[1]); w.w = pk2(v1[2], v1[3]); *(u32x4*)(xb + blk(row, col0 + bj * HALF, D)) = w; } }
;                 if (MODE != 2) { s += __shfl_xor(s, 16); s += __shfl_xor(s, 32); if (fq == 0) unsafeAtomicAdd(ssq + row, s); } }
	v_lshlrev_b32_e32 v164, 16, v154
	v_and_b32_e32 v165, 0xffff0000, v154
	v_lshlrev_b32_e32 v154, 16, v155
	v_and_b32_e32 v155, 0xffff0000, v155
	v_lshlrev_b32_e32 v166, 16, v156
	v_and_b32_e32 v167, 0xffff0000, v156
	v_lshlrev_b32_e32 v156, 16, v157
	v_and_b32_e32 v157, 0xffff0000, v157
	v_pk_add_f32 v[128:129], v[128:129], v[154:155]
	v_pk_add_f32 v[154:155], v[126:127], v[164:165]
	v_pk_add_f32 v[156:157], v[124:125], v[156:157]
	v_pk_add_f32 v[164:165], v[122:123], v[166:167]
	v_cvt_pk_bf16_f32 v122, v154, v155
	v_cvt_pk_bf16_f32 v123, v128, v129
	v_cvt_pk_bf16_f32 v124, v164, v165
	v_cvt_pk_bf16_f32 v125, v156, v157
	global_store_dwordx4 v[158:159], v[122:125], off
	s_nop 0
	v_mul_f32_e32 v153, v155, v155
	v_mul_f32_e32 v129, v129, v129
	v_mul_f32_e32 v155, v165, v165
	v_fmac_f32_e32 v153, v154, v154
	v_fmac_f32_e32 v129, v128, v128
	v_mul_f32_e32 v157, v157, v157
	v_fmac_f32_e32 v155, v164, v164
	v_add_f32_e32 v128, v153, v129
	v_fmac_f32_e32 v157, v156, v156
	v_add_f32_e32 v128, v155, v128
	v_add_f32_e32 v153, v157, v128
	v_and_b32_e32 v123, 64, v152
	v_xor_b32_e32 v122, 16, v152
	v_add_u32_e32 v123, 64, v123
	v_cmp_lt_i32_e32 vcc, v122, v123
	v_mov_b32_e32 v124, v168
	v_mov_b32_e32 v125, v169
	v_mov_b32_e32 v126, v170
	v_mov_b32_e32 v127, v171
	v_lshlrev_b32_e32 v128, 16, v124
	v_and_b32_e32 v129, 0xffff0000, v124
	v_lshlrev_b32_e32 v124, 16, v125
	v_and_b32_e32 v125, 0xffff0000, v125
	v_lshlrev_b32_e32 v154, 16, v126
	v_and_b32_e32 v155, 0xffff0000, v126
	v_lshlrev_b32_e32 v126, 16, v127
	v_and_b32_e32 v127, 0xffff0000, v127
	v_pk_add_f32 v[120:121], v[120:121], v[124:125]
	v_pk_add_f32 v[118:119], v[118:119], v[128:129]
	v_pk_add_f32 v[124:125], v[116:117], v[126:127]
	v_pk_add_f32 v[126:127], v[114:115], v[154:155]
	v_mul_f32_e32 v114, v119, v119
	v_mul_f32_e32 v115, v121, v121
	v_mul_f32_e32 v116, v127, v127
	v_fmac_f32_e32 v114, v118, v118
	v_fmac_f32_e32 v115, v120, v120
	v_mul_f32_e32 v117, v125, v125
	v_fmac_f32_e32 v116, v126, v126
	v_add_f32_e32 v114, v114, v115
	v_fmac_f32_e32 v117, v124, v124
	v_add_f32_e32 v114, v116, v114
	v_cndmask_b32_e32 v122, v152, v122, vcc
	v_add_f32_e32 v114, v117, v114
	v_lshlrev_b32_e32 v122, 2, v122
	v_add_f32_e32 v114, v153, v114
	ds_bpermute_b32 v115, v122, v114
	v_cmp_lt_i32_e32 vcc, v147, v123
	v_cvt_pk_bf16_f32 v118, v118, v119
	v_cvt_pk_bf16_f32 v119, v120, v121
	v_cndmask_b32_e32 v116, v152, v147, vcc
	v_lshlrev_b32_e32 v116, 2, v116
	s_waitcnt lgkmcnt(0)
	v_add_f32_e32 v114, v114, v115
	ds_bpermute_b32 v115, v116, v114
	v_cvt_pk_bf16_f32 v120, v126, v127
	v_cvt_pk_bf16_f32 v121, v124, v125
	v_lshl_add_u64 v[124:125], s[18:19], 0, v[160:161]
	global_store_dwordx4 v[124:125], v[118:121], off
	s_and_saveexec_b64 s[44:45], s[0:1]
	s_cbranch_execz .LBB0_762
	v_ashrrev_i32_e32 v147, 31, v146
	v_lshl_add_u64 v[118:119], v[146:147], 2, s[10:11]
	s_waitcnt lgkmcnt(0)
	v_add_f32_e32 v114, v114, v115
	global_atomic_add_f32 v[118:119], v114, off
.LBB0_762:
	s_or_b64 exec, exec, s[44:45]
	v_or_b32_e32 v114, 16, v146
	s_waitcnt lgkmcnt(0)
	v_lshlrev_b32_e32 v115, 6, v114
	v_and_or_b32 v115, v115, s63, v148
	v_or_b32_e32 v118, s38, v115
	v_mov_b32_e32 v119, s39
	v_lshlrev_b64 v[124:125], 1, v[118:119]
	v_lshl_add_u64 v[118:119], s[42:43], 0, v[124:125]
	s_nop 0
	v_mov_b32_e32 v127, s41
	v_or_b32_e32 v126, s40, v115
	v_lshlrev_b64 v[126:127], 1, v[126:127]
	v_lshl_add_u64 v[124:125], s[18:19], 0, v[124:125]
	v_lshl_add_u64 v[128:129], s[42:43], 0, v[126:127]
	v_mov_b32_e32 v118, v172
	v_mov_b32_e32 v119, v173
	v_mov_b32_e32 v120, v174
	v_mov_b32_e32 v121, v175
	v_lshlrev_b32_e32 v154, 16, v118
	v_and_b32_e32 v155, 0xffff0000, v118
	v_lshlrev_b32_e32 v118, 16, v119
	v_and_b32_e32 v119, 0xffff0000, v119
	v_lshlrev_b32_e32 v156, 16, v120
	v_and_b32_e32 v157, 0xffff0000, v120
	v_lshlrev_b32_e32 v120, 16, v121
	v_and_b32_e32 v121, 0xffff0000, v121
	v_pk_add_f32 v[112:113], v[112:113], v[118:119]
	v_pk_add_f32 v[110:111], v[110:111], v[154:155]
	v_pk_add_f32 v[118:119], v[108:109], v[120:121]
	v_pk_add_f32 v[120:121], v[106:107], v[156:157]
	v_cvt_pk_bf16_f32 v106, v110, v111
	v_cvt_pk_bf16_f32 v107, v112, v113
	v_cvt_pk_bf16_f32 v108, v120, v121
	v_cvt_pk_bf16_f32 v109, v118, v119
	global_store_dwordx4 v[124:125], v[106:109], off
	s_nop 0
	v_mul_f32_e32 v111, v111, v111
	v_mul_f32_e32 v113, v113, v113
	v_mul_f32_e32 v115, v121, v121
	v_fmac_f32_e32 v111, v110, v110
	v_fmac_f32_e32 v113, v112, v112
	v_mul_f32_e32 v117, v119, v119
	v_fmac_f32_e32 v115, v120, v120
	v_add_f32_e32 v110, v111, v113
	v_fmac_f32_e32 v117, v118, v118
	v_add_f32_e32 v110, v115, v110
	v_add_f32_e32 v115, v117, v110
	v_mov_b32_e32 v106, v180
	v_mov_b32_e32 v107, v181
	v_mov_b32_e32 v108, v182
	v_mov_b32_e32 v109, v183
	v_lshlrev_b32_e32 v110, 16, v106
	v_and_b32_e32 v111, 0xffff0000, v106
	v_lshlrev_b32_e32 v106, 16, v107
	v_and_b32_e32 v107, 0xffff0000, v107
	v_lshlrev_b32_e32 v112, 16, v108
	v_and_b32_e32 v113, 0xffff0000, v108
	v_lshlrev_b32_e32 v108, 16, v109
	v_and_b32_e32 v109, 0xffff0000, v109
	v_pk_add_f32 v[104:105], v[104:105], v[106:107]
	v_pk_add_f32 v[102:103], v[102:103], v[110:111]
	v_pk_add_f32 v[106:107], v[100:101], v[108:109]
	v_pk_add_f32 v[108:109], v[98:99], v[112:113]
	v_mul_f32_e32 v98, v103, v103
	v_mul_f32_e32 v99, v105, v105
	v_mul_f32_e32 v100, v109, v109
	v_fmac_f32_e32 v98, v102, v102
	v_fmac_f32_e32 v99, v104, v104
	v_mul_f32_e32 v101, v107, v107
	v_fmac_f32_e32 v100, v108, v108
	v_add_f32_e32 v98, v98, v99
	v_add_f32_e32 v98, v100, v98
	v_fmac_f32_e32 v101, v106, v106
	v_add_f32_e32 v98, v101, v98
	v_add_f32_e32 v98, v115, v98
	ds_bpermute_b32 v99, v122, v98
	v_cvt_pk_bf16_f32 v100, v102, v103
	v_cvt_pk_bf16_f32 v101, v104, v105
	v_cvt_pk_bf16_f32 v102, v108, v109
	v_cvt_pk_bf16_f32 v103, v106, v107
	s_waitcnt lgkmcnt(0)
	v_add_f32_e32 v98, v98, v99
	ds_bpermute_b32 v99, v116, v98
	v_lshl_add_u64 v[104:105], s[18:19], 0, v[126:127]
	global_store_dwordx4 v[104:105], v[100:103], off
	s_and_saveexec_b64 s[44:45], s[0:1]
	s_cbranch_execz .LBB0_764
	v_ashrrev_i32_e32 v115, 31, v114
	v_lshl_add_u64 v[100:101], v[114:115], 2, s[10:11]
	s_waitcnt lgkmcnt(0)
	v_add_f32_e32 v98, v98, v99
	global_atomic_add_f32 v[100:101], v98, off
; __host__ __device__ __forceinline__ size_t blk(int r, int k, int K) { return (((size_t)((r >> 8) * (K >> 6) + (k >> 6))) << 14) + (size_t)(((r & 255) << 6) + (k & 63)); }
; __device__ __forceinline__ float bflo(unsigned w) { return __uint_as_float(w << 16); }
; __device__ __forceinline__ float bfhi(unsigned w) { return __uint_as_float(w & 0xffff0000u); }
; __device__ __forceinline__ unsigned pk2(float lo, float hi) { f32x2 v = {lo, hi}; bf16x2_t b = __builtin_convertvector(v, bf16x2_t); return __builtin_bit_cast(unsigned, b); }
;     __device__ __forceinline__ void operator()(const f32x4 (&acc)[2][2][4][2], const Unit& u, int wr, int wc, int fr, int fq) const {
;     ...
;             for (int m = 0; m < 4; ++m) { const int row = row0 + ai * HALF + m * 16; const size_t off = (size_t)row * D + col0; float s = 0.f;
; #pragma unroll
;                 for (int bj = 0; bj < 2; ++bj) {
;                     f32x4 v0, v1;
;                     if (MODE == 0) { v0 = *(const f32x4*)(base + off + bj * HALF); v1 = *(const f32x4*)(base + off + bj * HALF + 4); }
;                     else { const u32x4 r = *(const u32x4*)(bb + blk(row, col0 + bj * HALF, D)); v0 = (f32x4){bflo(r.x), bfhi(r.x), bflo(r.y), bfhi(r.y)}; v1 = (f32x4){bflo(r.z), bfhi(r.z), bflo(r.w), bfhi(r.w)}; }
;                     v0 += acc[ai][bj][m][0] * alpha; v1 += acc[ai][bj][m][1] * alpha;
;                     if (MODE == 2) { *(f32x4*)(out + off + bj * HALF) = v0; *(f32x4*)(out + off + bj * HALF + 4) = v1; }
;                     else {
;                         s += (v0[0] * v0[0] + v0[1] * v0[1]) + (v0[2] * v0[2] + v0[3] * v0[3]) + (v1[0] * v1[0] + v1[1] * v1[1]) + (v1[2] * v1[2] + v1[3] * v1[3]);
;                         u32x4 w; w.x = pk2(v0[0], v0[1]); w.y = pk2(v0[2], v0[3]); w.z = pk2(v1[0], v1[1]); w.w = pk2(v1[2], v1[3]); *(u32x4*)(xb + blk(row, col0 + bj * HALF, D)) = w; } }
;                 if (MODE != 2) { s += __shfl_xor(s, 16); s += __shfl_xor(s, 32); if (fq == 0) unsafeAtomicAdd(ssq + row, s); } }
.LBB0_764:
	s_or_b64 exec, exec, s[44:45]
	v_or_b32_e32 v98, 32, v146
	s_waitcnt lgkmcnt(0)
	v_lshlrev_b32_e32 v99, 6, v98
	v_and_or_b32 v99, v99, s64, v148
	v_or_b32_e32 v100, s38, v99
	v_mov_b32_e32 v101, s39
	v_lshlrev_b64 v[104:105], 1, v[100:101]
	v_lshl_add_u64 v[100:101], s[42:43], 0, v[104:105]
	s_nop 0
	v_mov_b32_e32 v107, s41
	v_or_b32_e32 v106, s40, v99
	v_lshlrev_b64 v[106:107], 1, v[106:107]
	v_lshl_add_u64 v[104:105], s[18:19], 0, v[104:105]
	v_lshl_add_u64 v[108:109], s[42:43], 0, v[106:107]
	v_mov_b32_e32 v100, v184
	v_mov_b32_e32 v101, v185
	v_mov_b32_e32 v102, v186
	v_mov_b32_e32 v103, v187
	v_lshlrev_b32_e32 v110, 16, v100
	v_and_b32_e32 v111, 0xffff0000, v100
	v_lshlrev_b32_e32 v100, 16, v101
	v_and_b32_e32 v101, 0xffff0000, v101
	v_lshlrev_b32_e32 v112, 16, v102
	v_and_b32_e32 v113, 0xffff0000, v102
	v_lshlrev_b32_e32 v102, 16, v103
	v_and_b32_e32 v103, 0xffff0000, v103
	v_pk_add_f32 v[96:97], v[96:97], v[100:101]
	v_pk_add_f32 v[94:95], v[94:95], v[110:111]
	v_pk_add_f32 v[100:101], v[92:93], v[102:103]
	v_pk_add_f32 v[102:103], v[90:91], v[112:113]
	v_cvt_pk_bf16_f32 v90, v94, v95
	v_cvt_pk_bf16_f32 v91, v96, v97
	v_cvt_pk_bf16_f32 v92, v102, v103
	v_cvt_pk_bf16_f32 v93, v100, v101
	global_store_dwordx4 v[104:105], v[90:93], off
	s_nop 0
	v_mul_f32_e32 v95, v95, v95
	v_mul_f32_e32 v97, v97, v97
	v_mul_f32_e32 v99, v103, v103
	v_fmac_f32_e32 v95, v94, v94
	v_fmac_f32_e32 v97, v96, v96
	v_mul_f32_e32 v101, v101, v101
	v_fmac_f32_e32 v99, v102, v102
	v_add_f32_e32 v94, v95, v97
	v_fmac_f32_e32 v101, v100, v100
	v_add_f32_e32 v94, v99, v94
	v_add_f32_e32 v99, v101, v94
	v_mov_b32_e32 v90, v188
	v_mov_b32_e32 v91, v189
	v_mov_b32_e32 v92, v190
	v_mov_b32_e32 v93, v191
	v_lshl_add_u64 v[176:177], v[176:177], 0, s[98:99]
	v_lshl_add_u64 v[222:223], v[222:223], 0, s[98:99]
	global_load_dwordx4 v[168:171], v[176:177], off
	global_load_dwordx4 v[172:175], v[222:223], off
	global_load_dwordx4 v[180:183], v[176:177], off offset:2048
	global_load_dwordx4 v[184:187], v[222:223], off offset:2048
	v_lshlrev_b32_e32 v94, 16, v90
	v_and_b32_e32 v95, 0xffff0000, v90
	v_lshlrev_b32_e32 v90, 16, v91
	v_and_b32_e32 v91, 0xffff0000, v91
	v_lshlrev_b32_e32 v96, 16, v92
	v_and_b32_e32 v97, 0xffff0000, v92
	v_lshlrev_b32_e32 v92, 16, v93
	v_and_b32_e32 v93, 0xffff0000, v93
	v_pk_add_f32 v[88:89], v[88:89], v[90:91]
	v_pk_add_f32 v[86:87], v[86:87], v[94:95]
	v_pk_add_f32 v[90:91], v[84:85], v[92:93]
	v_pk_add_f32 v[92:93], v[82:83], v[96:97]
	v_mul_f32_e32 v82, v87, v87
	v_mul_f32_e32 v83, v89, v89
	v_mul_f32_e32 v84, v93, v93
	v_fmac_f32_e32 v82, v86, v86
	v_fmac_f32_e32 v83, v88, v88
	v_mul_f32_e32 v85, v91, v91
	v_fmac_f32_e32 v84, v92, v92
	v_add_f32_e32 v82, v82, v83
	v_add_f32_e32 v82, v84, v82
	v_fmac_f32_e32 v85, v90, v90
	v_add_f32_e32 v82, v85, v82
	v_add_f32_e32 v82, v99, v82
	ds_bpermute_b32 v83, v122, v82
	v_cvt_pk_bf16_f32 v84, v86, v87
	v_cvt_pk_bf16_f32 v85, v88, v89
	v_cvt_pk_bf16_f32 v86, v92, v93
	v_cvt_pk_bf16_f32 v87, v90, v91
	s_waitcnt lgkmcnt(0)
	v_add_f32_e32 v82, v82, v83
	ds_bpermute_b32 v83, v116, v82
	v_lshl_add_u64 v[88:89], s[18:19], 0, v[106:107]
	global_store_dwordx4 v[88:89], v[84:87], off
	s_and_saveexec_b64 s[44:45], s[0:1]
	s_cbranch_execz .LBB0_766
	v_ashrrev_i32_e32 v99, 31, v98
	v_lshl_add_u64 v[84:85], v[98:99], 2, s[10:11]
	s_waitcnt lgkmcnt(0)
	v_add_f32_e32 v82, v82, v83
	global_atomic_add_f32 v[84:85], v82, off
.LBB0_766:
	s_or_b64 exec, exec, s[44:45]
	v_or_b32_e32 v82, 48, v146
	s_waitcnt lgkmcnt(0)
	v_lshlrev_b32_e32 v83, 6, v82
	v_and_or_b32 v83, v83, s65, v148
	v_or_b32_e32 v84, s38, v83
	v_mov_b32_e32 v85, s39
	v_lshlrev_b64 v[88:89], 1, v[84:85]
	v_lshl_add_u64 v[84:85], s[42:43], 0, v[88:89]
	s_nop 0
	v_mov_b32_e32 v91, s41
	v_or_b32_e32 v90, s40, v83
	v_lshlrev_b64 v[90:91], 1, v[90:91]
	v_lshl_add_u64 v[88:89], s[18:19], 0, v[88:89]
	v_lshl_add_u64 v[92:93], s[42:43], 0, v[90:91]
	v_mov_b32_e32 v84, v198
	v_mov_b32_e32 v85, v199
	v_mov_b32_e32 v86, v200
	v_mov_b32_e32 v87, v201
	v_lshlrev_b32_e32 v94, 16, v84
	v_and_b32_e32 v95, 0xffff0000, v84
	v_lshlrev_b32_e32 v84, 16, v85
	v_and_b32_e32 v85, 0xffff0000, v85
	v_lshlrev_b32_e32 v96, 16, v86
	v_and_b32_e32 v97, 0xffff0000, v86
	v_lshlrev_b32_e32 v86, 16, v87
	v_and_b32_e32 v87, 0xffff0000, v87
	v_pk_add_f32 v[80:81], v[80:81], v[84:85]
	v_pk_add_f32 v[78:79], v[78:79], v[94:95]
	v_pk_add_f32 v[84:85], v[76:77], v[86:87]
	v_pk_add_f32 v[86:87], v[74:75], v[96:97]
	v_cvt_pk_bf16_f32 v74, v78, v79
	v_cvt_pk_bf16_f32 v75, v80, v81
	v_cvt_pk_bf16_f32 v76, v86, v87
	v_cvt_pk_bf16_f32 v77, v84, v85
	global_store_dwordx4 v[88:89], v[74:77], off
	s_nop 0
	v_mul_f32_e32 v79, v79, v79
	v_mul_f32_e32 v81, v81, v81
	v_mul_f32_e32 v83, v87, v87
	v_fmac_f32_e32 v79, v78, v78
	v_fmac_f32_e32 v81, v80, v80
	v_mul_f32_e32 v85, v85, v85
	v_fmac_f32_e32 v83, v86, v86
	v_add_f32_e32 v78, v79, v81
	v_fmac_f32_e32 v85, v84, v84
	v_add_f32_e32 v78, v83, v78
	v_add_f32_e32 v83, v85, v78
	v_mov_b32_e32 v74, v202
	v_mov_b32_e32 v75, v203
	v_mov_b32_e32 v76, v204
	v_mov_b32_e32 v77, v205
	v_lshlrev_b32_e32 v78, 16, v74
	v_and_b32_e32 v79, 0xffff0000, v74
	v_lshlrev_b32_e32 v74, 16, v75
	v_and_b32_e32 v75, 0xffff0000, v75
	v_lshlrev_b32_e32 v80, 16, v76
	v_and_b32_e32 v81, 0xffff0000, v76
	v_lshlrev_b32_e32 v76, 16, v77
	v_and_b32_e32 v77, 0xffff0000, v77
	v_pk_add_f32 v[72:73], v[72:73], v[74:75]
	v_pk_add_f32 v[70:71], v[70:71], v[78:79]
	v_pk_add_f32 v[74:75], v[68:69], v[76:77]
	v_pk_add_f32 v[76:77], v[66:67], v[80:81]
	v_mul_f32_e32 v66, v71, v71
	v_mul_f32_e32 v67, v73, v73
	v_mul_f32_e32 v68, v77, v77
	v_fmac_f32_e32 v66, v70, v70
	v_fmac_f32_e32 v67, v72, v72
	v_mul_f32_e32 v69, v75, v75
	v_fmac_f32_e32 v68, v76, v76
	v_add_f32_e32 v66, v66, v67
	v_add_f32_e32 v66, v68, v66
	v_fmac_f32_e32 v69, v74, v74
	v_add_f32_e32 v66, v69, v66
	v_add_f32_e32 v66, v83, v66
	ds_bpermute_b32 v67, v122, v66
	v_cvt_pk_bf16_f32 v68, v70, v71
	v_cvt_pk_bf16_f32 v69, v72, v73
	v_cvt_pk_bf16_f32 v70, v76, v77
	v_cvt_pk_bf16_f32 v71, v74, v75
	s_waitcnt lgkmcnt(0)
	v_add_f32_e32 v66, v66, v67
	ds_bpermute_b32 v67, v116, v66
	v_lshl_add_u64 v[72:73], s[18:19], 0, v[90:91]
	global_store_dwordx4 v[72:73], v[68:71], off
	s_and_saveexec_b64 s[38:39], s[0:1]
	s_cbranch_execz .LBB0_768
	v_ashrrev_i32_e32 v83, 31, v82
	v_lshl_add_u64 v[68:69], v[82:83], 2, s[10:11]
	s_waitcnt lgkmcnt(0)
	v_add_f32_e32 v66, v66, v67
	global_atomic_add_f32 v[68:69], v66, off
; __host__ __device__ __forceinline__ size_t blk(int r, int k, int K) { return (((size_t)((r >> 8) * (K >> 6) + (k >> 6))) << 14) + (size_t)(((r & 255) << 6) + (k & 63)); }
; __device__ __forceinline__ float bflo(unsigned w) { return __uint_as_float(w << 16); }
; __device__ __forceinline__ float bfhi(unsigned w) { return __uint_as_float(w & 0xffff0000u); }
; __device__ __forceinline__ unsigned pk2(float lo, float hi) { f32x2 v = {lo, hi}; bf16x2_t b = __builtin_convertvector(v, bf16x2_t); return __builtin_bit_cast(unsigned, b); }
;     __device__ __forceinline__ void operator()(const f32x4 (&acc)[2][2][4][2], const Unit& u, int wr, int wc, int fr, int fq) const {
;     ...
;             for (int m = 0; m < 4; ++m) { const int row = row0 + ai * HALF + m * 16; const size_t off = (size_t)row * D + col0; float s = 0.f;
; #pragma unroll
;                 for (int bj = 0; bj < 2; ++bj) {
;                     f32x4 v0, v1;
;                     if (MODE == 0) { v0 = *(const f32x4*)(base + off + bj * HALF); v1 = *(const f32x4*)(base + off + bj * HALF + 4); }
;                     else { const u32x4 r = *(const u32x4*)(bb + blk(row, col0 + bj * HALF, D)); v0 = (f32x4){bflo(r.x), bfhi(r.x), bflo(r.y), bfhi(r.y)}; v1 = (f32x4){bflo(r.z), bfhi(r.z), bflo(r.w), bfhi(r.w)}; }
;                     v0 += acc[ai][bj][m][0] * alpha; v1 += acc[ai][bj][m][1] * alpha;
;                     if (MODE == 2) { *(f32x4*)(out + off + bj * HALF) = v0; *(f32x4*)(out + off + bj * HALF + 4) = v1; }
;                     else {
;                         s += (v0[0] * v0[0] + v0[1] * v0[1]) + (v0[2] * v0[2] + v0[3] * v0[3]) + (v1[0] * v1[0] + v1[1] * v1[1]) + (v1[2] * v1[2] + v1[3] * v1[3]);
;                         u32x4 w; w.x = pk2(v0[0], v0[1]); w.y = pk2(v0[2], v0[3]); w.z = pk2(v1[0], v1[1]); w.w = pk2(v1[2], v1[3]); *(u32x4*)(xb + blk(row, col0 + bj * HALF, D)) = w; } }
;                 if (MODE != 2) { s += __shfl_xor(s, 16); s += __shfl_xor(s, 32); if (fq == 0) unsafeAtomicAdd(ssq + row, s); } }
.LBB0_768:
	s_or_b64 exec, exec, s[38:39]
	v_add_u32_e32 v70, 0x80, v146
	v_ashrrev_i32_e32 v66, 2, v70
	v_and_b32_e32 v71, 0xffffffc0, v66
	v_lshlrev_b32_e32 v66, 6, v70
	v_and_or_b32 v78, v66, s62, v148
	v_add_u32_e32 v66, s15, v71
	s_waitcnt lgkmcnt(0)
	v_ashrrev_i32_e32 v67, 31, v66
	v_lshlrev_b64 v[66:67], 14, v[66:67]
	v_or_b32_e32 v68, v66, v78
	v_mov_b32_e32 v69, v67
	v_lshlrev_b64 v[76:77], 1, v[68:69]
	v_lshl_add_u64 v[68:69], s[42:43], 0, v[76:77]
	s_nop 0
	v_add_u32_e32 v68, s17, v71
	v_ashrrev_i32_e32 v69, 31, v68
	v_lshlrev_b64 v[68:69], 14, v[68:69]
	v_or_b32_e32 v78, v68, v78
	v_mov_b32_e32 v79, v69
	v_lshlrev_b64 v[78:79], 1, v[78:79]
	v_lshl_add_u64 v[76:77], s[18:19], 0, v[76:77]
	v_lshl_add_u64 v[80:81], s[42:43], 0, v[78:79]
	v_mov_b32_e32 v72, v206
	v_mov_b32_e32 v73, v207
	v_mov_b32_e32 v74, v208
	v_mov_b32_e32 v75, v209
	v_lshlrev_b32_e32 v82, 16, v72
	v_and_b32_e32 v83, 0xffff0000, v72
	v_lshlrev_b32_e32 v72, 16, v73
	v_and_b32_e32 v73, 0xffff0000, v73
	v_lshlrev_b32_e32 v84, 16, v74
	v_and_b32_e32 v85, 0xffff0000, v74
	v_lshlrev_b32_e32 v74, 16, v75
	v_and_b32_e32 v75, 0xffff0000, v75
	v_pk_add_f32 v[64:65], v[64:65], v[72:73]
	v_pk_add_f32 v[62:63], v[62:63], v[82:83]
	v_pk_add_f32 v[72:73], v[60:61], v[74:75]
	v_pk_add_f32 v[74:75], v[58:59], v[84:85]
	v_cvt_pk_bf16_f32 v58, v62, v63
	v_cvt_pk_bf16_f32 v59, v64, v65
	v_cvt_pk_bf16_f32 v60, v74, v75
	v_cvt_pk_bf16_f32 v61, v72, v73
	global_store_dwordx4 v[76:77], v[58:61], off
	s_nop 0
	v_mul_f32_e32 v63, v63, v63
	v_mul_f32_e32 v65, v65, v65
	v_mul_f32_e32 v71, v75, v75
	v_fmac_f32_e32 v63, v62, v62
	v_fmac_f32_e32 v65, v64, v64
	v_mul_f32_e32 v73, v73, v73
	v_fmac_f32_e32 v71, v74, v74
	v_add_f32_e32 v62, v63, v65
	v_fmac_f32_e32 v73, v72, v72
	v_add_f32_e32 v62, v71, v62
	v_add_f32_e32 v71, v73, v62
	v_mov_b32_e32 v58, v210
	v_mov_b32_e32 v59, v211
	v_mov_b32_e32 v60, v212
	v_mov_b32_e32 v61, v213
	v_lshlrev_b32_e32 v62, 16, v58
	v_and_b32_e32 v63, 0xffff0000, v58
	v_lshlrev_b32_e32 v58, 16, v59
	v_and_b32_e32 v59, 0xffff0000, v59
	v_lshlrev_b32_e32 v64, 16, v60
	v_and_b32_e32 v65, 0xffff0000, v60
	v_lshlrev_b32_e32 v60, 16, v61
	v_and_b32_e32 v61, 0xffff0000, v61
	v_pk_add_f32 v[56:57], v[56:57], v[58:59]
	v_pk_add_f32 v[54:55], v[54:55], v[62:63]
	v_pk_add_f32 v[58:59], v[52:53], v[60:61]
	v_pk_add_f32 v[60:61], v[50:51], v[64:65]
	v_mul_f32_e32 v50, v55, v55
	v_mul_f32_e32 v51, v57, v57
	v_mul_f32_e32 v52, v61, v61
	v_fmac_f32_e32 v50, v54, v54
	v_fmac_f32_e32 v51, v56, v56
	v_mul_f32_e32 v53, v59, v59
	v_fmac_f32_e32 v52, v60, v60
	v_add_f32_e32 v50, v50, v51
	v_add_f32_e32 v50, v52, v50
	v_fmac_f32_e32 v53, v58, v58
	v_add_f32_e32 v50, v53, v50
	v_add_f32_e32 v50, v71, v50
	ds_bpermute_b32 v51, v122, v50
	v_cvt_pk_bf16_f32 v52, v54, v55
	v_cvt_pk_bf16_f32 v53, v56, v57
	v_cvt_pk_bf16_f32 v54, v60, v61
	v_cvt_pk_bf16_f32 v55, v58, v59
	s_waitcnt lgkmcnt(0)
	v_add_f32_e32 v50, v50, v51
	ds_bpermute_b32 v51, v116, v50
	v_lshl_add_u64 v[56:57], s[18:19], 0, v[78:79]
	global_store_dwordx4 v[56:57], v[52:55], off
	s_and_saveexec_b64 s[38:39], s[0:1]
	s_cbranch_execz .LBB0_770
	v_ashrrev_i32_e32 v71, 31, v70
	v_lshl_add_u64 v[52:53], v[70:71], 2, s[10:11]
	s_waitcnt lgkmcnt(0)
	v_add_f32_e32 v50, v50, v51
	global_atomic_add_f32 v[52:53], v50, off
.LBB0_770:
	s_or_b64 exec, exec, s[38:39]
	v_add_u32_e32 v50, 0x90, v146
	s_waitcnt lgkmcnt(0)
	v_lshlrev_b32_e32 v51, 6, v50
	v_and_or_b32 v51, v51, s63, v148
	v_or_b32_e32 v52, v66, v51
	v_mov_b32_e32 v53, v67
	v_lshlrev_b64 v[56:57], 1, v[52:53]
	v_lshl_add_u64 v[52:53], s[42:43], 0, v[56:57]
	s_nop 0
	v_mov_b32_e32 v59, v69
	v_or_b32_e32 v58, v68, v51
	v_lshlrev_b64 v[58:59], 1, v[58:59]
	v_lshl_add_u64 v[56:57], s[18:19], 0, v[56:57]
	v_lshl_add_u64 v[60:61], s[42:43], 0, v[58:59]
	v_mov_b32_e32 v52, v214
	v_mov_b32_e32 v53, v215
	v_mov_b32_e32 v54, v216
	v_mov_b32_e32 v55, v217
	v_lshlrev_b32_e32 v62, 16, v52
	v_and_b32_e32 v63, 0xffff0000, v52
	v_lshlrev_b32_e32 v52, 16, v53
	v_and_b32_e32 v53, 0xffff0000, v53
	v_lshlrev_b32_e32 v64, 16, v54
	v_and_b32_e32 v65, 0xffff0000, v54
	v_lshlrev_b32_e32 v54, 16, v55
	v_and_b32_e32 v55, 0xffff0000, v55
	v_pk_add_f32 v[48:49], v[48:49], v[52:53]
	v_pk_add_f32 v[46:47], v[46:47], v[62:63]
	v_pk_add_f32 v[52:53], v[44:45], v[54:55]
	v_pk_add_f32 v[54:55], v[42:43], v[64:65]
	v_cvt_pk_bf16_f32 v42, v46, v47
	v_cvt_pk_bf16_f32 v43, v48, v49
	v_cvt_pk_bf16_f32 v44, v54, v55
	v_cvt_pk_bf16_f32 v45, v52, v53
	global_store_dwordx4 v[56:57], v[42:45], off
	s_nop 0
	v_mul_f32_e32 v47, v47, v47
	v_mul_f32_e32 v49, v49, v49
	v_mul_f32_e32 v51, v55, v55
	v_fmac_f32_e32 v47, v46, v46
	v_fmac_f32_e32 v49, v48, v48
	v_mul_f32_e32 v53, v53, v53
	v_fmac_f32_e32 v51, v54, v54
	v_add_f32_e32 v46, v47, v49
	v_fmac_f32_e32 v53, v52, v52
	v_add_f32_e32 v46, v51, v46
	v_add_f32_e32 v51, v53, v46
	v_mov_b32_e32 v42, v218
	v_mov_b32_e32 v43, v219
	v_mov_b32_e32 v44, v220
	v_mov_b32_e32 v45, v221
	v_lshlrev_b32_e32 v46, 16, v42
	v_and_b32_e32 v47, 0xffff0000, v42
	v_lshlrev_b32_e32 v42, 16, v43
	v_and_b32_e32 v43, 0xffff0000, v43
	v_lshlrev_b32_e32 v48, 16, v44
	v_and_b32_e32 v49, 0xffff0000, v44
	v_lshlrev_b32_e32 v44, 16, v45
	v_and_b32_e32 v45, 0xffff0000, v45
	v_pk_add_f32 v[40:41], v[40:41], v[42:43]
	v_pk_add_f32 v[38:39], v[38:39], v[46:47]
	v_pk_add_f32 v[42:43], v[36:37], v[44:45]
	v_pk_add_f32 v[44:45], v[34:35], v[48:49]
	v_mul_f32_e32 v34, v39, v39
	v_mul_f32_e32 v35, v41, v41
	v_mul_f32_e32 v36, v45, v45
	v_fmac_f32_e32 v34, v38, v38
	v_fmac_f32_e32 v35, v40, v40
	v_mul_f32_e32 v37, v43, v43
	v_fmac_f32_e32 v36, v44, v44
	v_add_f32_e32 v34, v34, v35
	v_add_f32_e32 v34, v36, v34
	v_fmac_f32_e32 v37, v42, v42
	v_add_f32_e32 v34, v37, v34
	v_add_f32_e32 v34, v51, v34
	ds_bpermute_b32 v35, v122, v34
	v_cvt_pk_bf16_f32 v36, v38, v39
	v_cvt_pk_bf16_f32 v37, v40, v41
	v_cvt_pk_bf16_f32 v38, v44, v45
	v_cvt_pk_bf16_f32 v39, v42, v43
	s_waitcnt lgkmcnt(0)
	v_add_f32_e32 v34, v34, v35
	ds_bpermute_b32 v35, v116, v34
	v_lshl_add_u64 v[40:41], s[18:19], 0, v[58:59]
	global_store_dwordx4 v[40:41], v[36:39], off
	s_and_saveexec_b64 s[38:39], s[0:1]
	s_cbranch_execz .LBB0_772
	v_ashrrev_i32_e32 v51, 31, v50
	v_lshl_add_u64 v[36:37], v[50:51], 2, s[10:11]
	s_waitcnt lgkmcnt(0)
	v_add_f32_e32 v34, v34, v35
	global_atomic_add_f32 v[36:37], v34, off
; __host__ __device__ __forceinline__ size_t blk(int r, int k, int K) { return (((size_t)((r >> 8) * (K >> 6) + (k >> 6))) << 14) + (size_t)(((r & 255) << 6) + (k & 63)); }
; __device__ __forceinline__ float bflo(unsigned w) { return __uint_as_float(w << 16); }
; __device__ __forceinline__ float bfhi(unsigned w) { return __uint_as_float(w & 0xffff0000u); }
; __device__ __forceinline__ unsigned pk2(float lo, float hi) { f32x2 v = {lo, hi}; bf16x2_t b = __builtin_convertvector(v, bf16x2_t); return __builtin_bit_cast(unsigned, b); }
;     __device__ __forceinline__ void operator()(const f32x4 (&acc)[2][2][4][2], const Unit& u, int wr, int wc, int fr, int fq) const {
;     ...
;             for (int m = 0; m < 4; ++m) { const int row = row0 + ai * HALF + m * 16; const size_t off = (size_t)row * D + col0; float s = 0.f;
; #pragma unroll
;                 for (int bj = 0; bj < 2; ++bj) {
;                     f32x4 v0, v1;
;                     if (MODE == 0) { v0 = *(const f32x4*)(base + off + bj * HALF); v1 = *(const f32x4*)(base + off + bj * HALF + 4); }
;                     else { const u32x4 r = *(const u32x4*)(bb + blk(row, col0 + bj * HALF, D)); v0 = (f32x4){bflo(r.x), bfhi(r.x), bflo(r.y), bfhi(r.y)}; v1 = (f32x4){bflo(r.z), bfhi(r.z), bflo(r.w), bfhi(r.w)}; }
;                     v0 += acc[ai][bj][m][0] * alpha; v1 += acc[ai][bj][m][1] * alpha;
;                     if (MODE == 2) { *(f32x4*)(out + off + bj * HALF) = v0; *(f32x4*)(out + off + bj * HALF + 4) = v1; }
;                     else {
;                         s += (v0[0] * v0[0] + v0[1] * v0[1]) + (v0[2] * v0[2] + v0[3] * v0[3]) + (v1[0] * v1[0] + v1[1] * v1[1]) + (v1[2] * v1[2] + v1[3] * v1[3]);
;                         u32x4 w; w.x = pk2(v0[0], v0[1]); w.y = pk2(v0[2], v0[3]); w.z = pk2(v1[0], v1[1]); w.w = pk2(v1[2], v1[3]); *(u32x4*)(xb + blk(row, col0 + bj * HALF, D)) = w; } }
;                 if (MODE != 2) { s += __shfl_xor(s, 16); s += __shfl_xor(s, 32); if (fq == 0) unsafeAtomicAdd(ssq + row, s); } }
.LBB0_772:
	s_or_b64 exec, exec, s[38:39]
	v_add_u32_e32 v34, 0xa0, v146
	s_waitcnt lgkmcnt(0)
	v_lshlrev_b32_e32 v35, 6, v34
	v_and_or_b32 v35, v35, s64, v148
	v_or_b32_e32 v36, v66, v35
	v_mov_b32_e32 v37, v67
	v_lshlrev_b64 v[40:41], 1, v[36:37]
	v_lshl_add_u64 v[36:37], s[42:43], 0, v[40:41]
	s_nop 0
	v_mov_b32_e32 v43, v69
	v_or_b32_e32 v42, v68, v35
	v_lshlrev_b64 v[42:43], 1, v[42:43]
	v_lshl_add_u64 v[40:41], s[18:19], 0, v[40:41]
	v_lshl_add_u64 v[44:45], s[42:43], 0, v[42:43]
	s_waitcnt vmcnt(10)
	v_mov_b32_e32 v36, v168
	v_mov_b32_e32 v37, v169
	v_mov_b32_e32 v38, v170
	v_mov_b32_e32 v39, v171
	v_lshlrev_b32_e32 v46, 16, v36
	v_and_b32_e32 v47, 0xffff0000, v36
	v_lshlrev_b32_e32 v36, 16, v37
	v_and_b32_e32 v37, 0xffff0000, v37
	v_lshlrev_b32_e32 v48, 16, v38
	v_and_b32_e32 v49, 0xffff0000, v38
	v_lshlrev_b32_e32 v38, 16, v39
	v_and_b32_e32 v39, 0xffff0000, v39
	v_pk_add_f32 v[32:33], v[32:33], v[36:37]
	v_pk_add_f32 v[30:31], v[30:31], v[46:47]
	v_pk_add_f32 v[36:37], v[28:29], v[38:39]
	v_pk_add_f32 v[38:39], v[26:27], v[48:49]
	v_cvt_pk_bf16_f32 v26, v30, v31
	v_cvt_pk_bf16_f32 v27, v32, v33
	v_cvt_pk_bf16_f32 v28, v38, v39
	v_cvt_pk_bf16_f32 v29, v36, v37
	global_store_dwordx4 v[40:41], v[26:29], off
	s_nop 0
	v_mul_f32_e32 v31, v31, v31
	v_mul_f32_e32 v33, v33, v33
	v_mul_f32_e32 v35, v39, v39
	v_fmac_f32_e32 v31, v30, v30
	v_fmac_f32_e32 v33, v32, v32
	v_mul_f32_e32 v37, v37, v37
	v_fmac_f32_e32 v35, v38, v38
	v_add_f32_e32 v30, v31, v33
	v_fmac_f32_e32 v37, v36, v36
	v_add_f32_e32 v30, v35, v30
	v_add_f32_e32 v35, v37, v30
	v_mov_b32_e32 v26, v172
	v_mov_b32_e32 v27, v173
	v_mov_b32_e32 v28, v174
	v_mov_b32_e32 v29, v175
	v_lshlrev_b32_e32 v30, 16, v26
	v_and_b32_e32 v31, 0xffff0000, v26
	v_lshlrev_b32_e32 v26, 16, v27
	v_and_b32_e32 v27, 0xffff0000, v27
	v_lshlrev_b32_e32 v32, 16, v28
	v_and_b32_e32 v33, 0xffff0000, v28
	v_lshlrev_b32_e32 v28, 16, v29
	v_and_b32_e32 v29, 0xffff0000, v29
	v_pk_add_f32 v[24:25], v[24:25], v[26:27]
	v_pk_add_f32 v[22:23], v[22:23], v[30:31]
	v_pk_add_f32 v[26:27], v[20:21], v[28:29]
	v_pk_add_f32 v[28:29], v[18:19], v[32:33]
	v_mul_f32_e32 v18, v23, v23
	v_mul_f32_e32 v19, v25, v25
	v_mul_f32_e32 v20, v29, v29
	v_fmac_f32_e32 v18, v22, v22
	v_fmac_f32_e32 v19, v24, v24
	v_mul_f32_e32 v21, v27, v27
	v_fmac_f32_e32 v20, v28, v28
	v_add_f32_e32 v18, v18, v19
	v_add_f32_e32 v18, v20, v18
	v_fmac_f32_e32 v21, v26, v26
	v_add_f32_e32 v18, v21, v18
	v_add_f32_e32 v18, v35, v18
	ds_bpermute_b32 v19, v122, v18
	v_cvt_pk_bf16_f32 v20, v22, v23
	v_cvt_pk_bf16_f32 v21, v24, v25
	v_cvt_pk_bf16_f32 v22, v28, v29
	v_cvt_pk_bf16_f32 v23, v26, v27
	s_waitcnt lgkmcnt(0)
	v_add_f32_e32 v18, v18, v19
	ds_bpermute_b32 v19, v116, v18
	v_lshl_add_u64 v[24:25], s[18:19], 0, v[42:43]
	global_store_dwordx4 v[24:25], v[20:23], off
	s_and_saveexec_b64 s[38:39], s[0:1]
	s_cbranch_execz .LBB0_774
	v_ashrrev_i32_e32 v35, 31, v34
	v_lshl_add_u64 v[20:21], v[34:35], 2, s[10:11]
	s_waitcnt lgkmcnt(0)
	v_add_f32_e32 v18, v18, v19
	global_atomic_add_f32 v[20:21], v18, off
.LBB0_774:
	s_or_b64 exec, exec, s[38:39]
	v_add_u32_e32 v18, 0xb0, v146
	s_waitcnt lgkmcnt(0)
	v_lshlrev_b32_e32 v19, 6, v18
	v_and_or_b32 v19, v19, s65, v148
	v_or_b32_e32 v66, v66, v19
	v_lshlrev_b64 v[24:25], 1, v[66:67]
	v_lshl_add_u64 v[20:21], s[42:43], 0, v[24:25]
	s_nop 0
	v_or_b32_e32 v68, v68, v19
	v_lshlrev_b64 v[26:27], 1, v[68:69]
	v_lshl_add_u64 v[24:25], s[18:19], 0, v[24:25]
	v_lshl_add_u64 v[28:29], s[42:43], 0, v[26:27]
	v_mov_b32_e32 v20, v180
	v_mov_b32_e32 v21, v181
	v_mov_b32_e32 v22, v182
	v_mov_b32_e32 v23, v183
	v_lshlrev_b32_e32 v30, 16, v20
	v_and_b32_e32 v31, 0xffff0000, v20
	v_lshlrev_b32_e32 v20, 16, v21
	v_and_b32_e32 v21, 0xffff0000, v21
	v_lshlrev_b32_e32 v32, 16, v22
	v_and_b32_e32 v33, 0xffff0000, v22
	v_lshlrev_b32_e32 v22, 16, v23
	v_and_b32_e32 v23, 0xffff0000, v23
	v_pk_add_f32 v[16:17], v[16:17], v[20:21]
	v_pk_add_f32 v[14:15], v[14:15], v[30:31]
	v_pk_add_f32 v[20:21], v[12:13], v[22:23]
	v_pk_add_f32 v[22:23], v[10:11], v[32:33]
	v_cvt_pk_bf16_f32 v10, v14, v15
	v_cvt_pk_bf16_f32 v11, v16, v17
	v_cvt_pk_bf16_f32 v12, v22, v23
	v_cvt_pk_bf16_f32 v13, v20, v21
	global_store_dwordx4 v[24:25], v[10:13], off
	s_nop 0
	v_mul_f32_e32 v15, v15, v15
	v_mul_f32_e32 v17, v17, v17
	v_mul_f32_e32 v19, v23, v23
	v_fmac_f32_e32 v15, v14, v14
	v_fmac_f32_e32 v17, v16, v16
	v_mul_f32_e32 v21, v21, v21
	v_fmac_f32_e32 v19, v22, v22
	v_add_f32_e32 v14, v15, v17
	v_fmac_f32_e32 v21, v20, v20
	v_add_f32_e32 v14, v19, v14
	v_add_f32_e32 v19, v21, v14
	v_mov_b32_e32 v10, v184
	v_mov_b32_e32 v11, v185
	v_mov_b32_e32 v12, v186
	v_mov_b32_e32 v13, v187
	v_lshlrev_b32_e32 v14, 16, v10
	v_and_b32_e32 v15, 0xffff0000, v10
	v_lshlrev_b32_e32 v10, 16, v11
	v_and_b32_e32 v11, 0xffff0000, v11
	v_lshlrev_b32_e32 v16, 16, v12
	v_and_b32_e32 v17, 0xffff0000, v12
	v_lshlrev_b32_e32 v12, 16, v13
	v_and_b32_e32 v13, 0xffff0000, v13
	v_pk_add_f32 v[8:9], v[8:9], v[10:11]
	v_pk_add_f32 v[6:7], v[6:7], v[14:15]
	v_pk_add_f32 v[10:11], v[4:5], v[12:13]
	v_pk_add_f32 v[12:13], v[2:3], v[16:17]
	v_mul_f32_e32 v2, v7, v7
	v_mul_f32_e32 v3, v9, v9
	v_mul_f32_e32 v4, v13, v13
	v_fmac_f32_e32 v2, v6, v6
	v_fmac_f32_e32 v3, v8, v8
	v_mul_f32_e32 v5, v11, v11
	v_fmac_f32_e32 v4, v12, v12
	v_add_f32_e32 v2, v2, v3
	v_add_f32_e32 v2, v4, v2
	v_fmac_f32_e32 v5, v10, v10
	v_add_f32_e32 v2, v5, v2
	v_add_f32_e32 v2, v19, v2
	ds_bpermute_b32 v3, v122, v2
	v_cvt_pk_bf16_f32 v4, v6, v7
	v_cvt_pk_bf16_f32 v5, v8, v9
	v_cvt_pk_bf16_f32 v6, v12, v13
	v_cvt_pk_bf16_f32 v7, v10, v11
	s_waitcnt lgkmcnt(0)
	v_add_f32_e32 v2, v2, v3
	ds_bpermute_b32 v3, v116, v2
	v_lshl_add_u64 v[8:9], s[18:19], 0, v[26:27]
	global_store_dwordx4 v[8:9], v[4:7], off
	s_and_saveexec_b64 s[38:39], s[0:1]
	s_cbranch_execz .LBB0_776
	v_ashrrev_i32_e32 v19, 31, v18
	v_lshl_add_u64 v[4:5], v[18:19], 2, s[10:11]
	s_waitcnt lgkmcnt(0)
	v_add_f32_e32 v2, v2, v3
	global_atomic_add_f32 v[4:5], v2, off

; #define PG8_STAGE(bufoff, gbase, voff) do { _Pragma("unroll") for (int _i = 0; _i < 2; ++_i) \
;         __builtin_amdgcn_global_load_lds((const unsigned*)((const char*)(gbase) + (voff)[_i]), (PG8_LAS unsigned*)(lds + (bufoff) + ldsw + _i * 8192), 16, 0, 0); } while (0)
; #define PG8_LDA(dst, b, h) do { _Pragma("unroll") for (int m = 0; m < 4; ++m) _Pragma("unroll") for (int k = 0; k < 2; ++k) dst[m][k] = *(const PG8_LAS bf16x8*)(lds + PG8_SA(b, h) + aoff + m * 2048 + k * 1024); } while (0)
; #define PG8_LDB(dst, b, h) do { _Pragma("unroll") for (int n = 0; n < 2; ++n) _Pragma("unroll") for (int k = 0; k < 2; ++k) dst[n][k] = *(const PG8_LAS bf16x8*)(lds + PG8_SB(b, h) + boff + n * 2048 + k * 1024); } while (0)
; template <class Epi, class Sched, bool ALIGN_EPI = false, bool SP2 = false>
; __device__ __forceinline__ void gemm_phase(PG8_LAS unsigned char* lds, const Gemm g, const Sched& S, const Epi& E) {
;     ...
;         for (; t < tend; t += 2) {
;             const bool last = (t == nt - 2);
;             const char* a1 = cA + (size_t)(t + 1) * kstep;
;             const char* a2 = last ? nA : cA + (size_t)(t + 2) * kstep; const char* b2 = last ? nB : cB + (size_t)(t + 2) * kstep;
;             const char* a3 = a2 + kstep; const char* b3 = b2 + kstep;
;             if (last && has_next) S.a_ready(nxt);
;             if constexpr (SP2) {
;             PG8_LDB(B0, 0, 0); PG8_LDB(B1, 0, 1); PG8_SCHED; PG8_LDA(At, 0, 0); PG8_STAGE(PG8_SA(1, 1), a1 + hstep, voffA);
;             PG8_WAIT_V(8); PG8_WAIT_L(0); PG8_BAR; PG8_MMA(0, 0, At, B0); PG8_MMA(0, 1, At, B1); PG8_BAR; PG8_SCHED;
;             PG8_LDA(At, 0, 1); PG8_STAGE(PG8_SB(0, 0), b2, voffB); PG8_STAGE(PG8_SB(0, 1), b2 + hstep, voffB); PG8_STAGE(PG8_SA(0, 0), a2, voffA);
;             PG8_WAIT_V(8); PG8_WAIT_L(0); PG8_BAR; PG8_MMA(1, 0, At, B0); PG8_MMA(1, 1, At, B1); PG8_BAR; PG8_SCHED;
;             PG8_LDB(B0, 1, 0); PG8_LDB(B1, 1, 1); PG8_SCHED; PG8_LDA(At, 1, 0); PG8_STAGE(PG8_SA(0, 1), a2 + hstep, voffA);
;             PG8_WAIT_V(8); PG8_WAIT_L(0); PG8_BAR; PG8_MMA(0, 0, At, B0); PG8_MMA(0, 1, At, B1); PG8_BAR; PG8_SCHED;
;             PG8_LDA(At, 1, 1); PG8_STAGE(PG8_SB(1, 0), b3, voffB); PG8_STAGE(PG8_SB(1, 1), b3 + hstep, voffB); PG8_STAGE(PG8_SA(1, 0), a3, voffA);
;             PG8_WAIT_V(8); PG8_WAIT_L(0); PG8_BAR; PG8_MMA(1, 0, At, B0); PG8_MMA(1, 1, At, B1); PG8_BAR; PG8_SCHED;
.LBB0_840:
	ds_read_b128 v[148:151], v153
	ds_read_b128 v[158:161], v153 offset:1024
	ds_read_b128 v[162:165], v153 offset:2048
	ds_read_b128 v[166:169], v153 offset:3072
	ds_read_b128 v[170:173], v154
	ds_read_b128 v[174:177], v154 offset:1024
	ds_read_b128 v[180:183], v154 offset:2048
	ds_read_b128 v[184:187], v154 offset:3072
	s_add_u32 s42, s40, 0x4000
	s_addc_u32 s43, s41, 0
	s_cmp_eq_u32 s69, 60
	s_cselect_b32 s46, s65, s42
	s_cselect_b32 s47, s23, s43
	s_cselect_b32 s44, s66, s67
	s_cselect_b32 s45, s17, s68
	s_add_u32 s42, s46, 0x8000
	s_addc_u32 s43, s47, 0
	s_sub_u32 s42, s40, 0x4000
	s_subb_u32 s43, s41, 0
	v_lshl_add_u64 v[226:227], s[42:43], 0, v[130:131]
	s_mov_b32 m0, s50
	s_nop 0
	global_load_lds_dwordx4 v[226:227], off
	v_lshl_add_u64 v[226:227], s[42:43], 0, v[134:135]
	s_mov_b32 m0, s51
	s_nop 0
	global_load_lds_dwordx4 v[226:227], off
	v_lshl_add_u64 v[226:227], s[40:41], 0, v[140:141]
	s_add_i32 m0, s28, 0xc000
	ds_read_b128 v[188:191], v155
	ds_read_b128 v[198:201], v155 offset:1024
	ds_read_b128 v[202:205], v155 offset:2048
	ds_read_b128 v[206:209], v155 offset:3072
	ds_read_b128 v[210:213], v155 offset:4096
	ds_read_b128 v[214:217], v155 offset:5120
	ds_read_b128 v[218:221], v155 offset:6144
	ds_read_b128 v[222:225], v155 offset:7168
	global_load_lds_dwordx4 v[226:227], off
	v_lshl_add_u64 v[226:227], s[40:41], 0, v[142:143]
	s_add_i32 m0, s28, 0xe000
	s_nop 0
	global_load_lds_dwordx4 v[226:227], off
	s_waitcnt vmcnt(8)
	s_waitcnt lgkmcnt(0)
	s_barrier
	s_setprio 1
	s_waitcnt lgkmcnt(0)
	v_mfma_f32_16x16x32_bf16 v[126:129], v[148:151], v[188:191], v[126:129]
	v_mfma_f32_16x16x32_bf16 v[122:125], v[162:165], v[188:191], v[122:125]
	v_mfma_f32_16x16x32_bf16 v[110:113], v[148:151], v[202:205], v[110:113]
	v_mfma_f32_16x16x32_bf16 v[106:109], v[162:165], v[202:205], v[106:109]
	v_mfma_f32_16x16x32_bf16 v[94:97], v[148:151], v[210:213], v[94:97]
	v_mfma_f32_16x16x32_bf16 v[90:93], v[162:165], v[210:213], v[90:93]
	v_mfma_f32_16x16x32_bf16 v[78:81], v[148:151], v[218:221], v[78:81]
	v_mfma_f32_16x16x32_bf16 v[74:77], v[162:165], v[218:221], v[74:77]
	v_mfma_f32_16x16x32_bf16 v[126:129], v[158:161], v[198:201], v[126:129]
	v_mfma_f32_16x16x32_bf16 v[122:125], v[166:169], v[198:201], v[122:125]
	v_mfma_f32_16x16x32_bf16 v[110:113], v[158:161], v[206:209], v[110:113]
	v_mfma_f32_16x16x32_bf16 v[106:109], v[166:169], v[206:209], v[106:109]
	v_mfma_f32_16x16x32_bf16 v[94:97], v[158:161], v[214:217], v[94:97]
	v_mfma_f32_16x16x32_bf16 v[90:93], v[166:169], v[214:217], v[90:93]
	v_mfma_f32_16x16x32_bf16 v[78:81], v[158:161], v[222:225], v[78:81]
	v_mfma_f32_16x16x32_bf16 v[74:77], v[166:169], v[222:225], v[74:77]
	s_setprio 0
	s_setprio 1
	v_mfma_f32_16x16x32_bf16 v[118:121], v[170:173], v[188:191], v[118:121]
	v_mfma_f32_16x16x32_bf16 v[114:117], v[180:183], v[188:191], v[114:117]
	v_mfma_f32_16x16x32_bf16 v[102:105], v[170:173], v[202:205], v[102:105]
	v_mfma_f32_16x16x32_bf16 v[98:101], v[180:183], v[202:205], v[98:101]
	v_mfma_f32_16x16x32_bf16 v[86:89], v[170:173], v[210:213], v[86:89]
	v_mfma_f32_16x16x32_bf16 v[82:85], v[180:183], v[210:213], v[82:85]
	v_mfma_f32_16x16x32_bf16 v[70:73], v[170:173], v[218:221], v[70:73]
	v_mfma_f32_16x16x32_bf16 v[66:69], v[180:183], v[218:221], v[66:69]
	v_mfma_f32_16x16x32_bf16 v[118:121], v[174:177], v[198:201], v[118:121]
	v_mfma_f32_16x16x32_bf16 v[114:117], v[184:187], v[198:201], v[114:117]
	v_mfma_f32_16x16x32_bf16 v[102:105], v[174:177], v[206:209], v[102:105]
	v_mfma_f32_16x16x32_bf16 v[98:101], v[184:187], v[206:209], v[98:101]
	v_mfma_f32_16x16x32_bf16 v[86:89], v[174:177], v[214:217], v[86:89]
	v_mfma_f32_16x16x32_bf16 v[82:85], v[184:187], v[214:217], v[82:85]
	v_mfma_f32_16x16x32_bf16 v[70:73], v[174:177], v[222:225], v[70:73]
	v_mfma_f32_16x16x32_bf16 v[66:69], v[184:187], v[222:225], v[66:69]
	s_setprio 0
	s_barrier
	s_add_i32 s70, s56, s3
	v_lshl_add_u64 v[226:227], s[44:45], 0, v[132:133]
	s_mov_b32 m0, s70
	ds_read_b128 v[188:191], v155 offset:16384
	ds_read_b128 v[198:201], v155 offset:17408
	ds_read_b128 v[202:205], v155 offset:18432
	ds_read_b128 v[206:209], v155 offset:19456
	ds_read_b128 v[210:213], v155 offset:20480
	ds_read_b128 v[214:217], v155 offset:21504
	ds_read_b128 v[218:221], v155 offset:22528
	ds_read_b128 v[222:225], v155 offset:23552
	global_load_lds_dwordx4 v[226:227], off
	s_add_i32 m0, s70, 0x2000
	s_add_u32 s70, s44, 0x4000
	v_lshl_add_u64 v[226:227], s[44:45], 0, v[136:137]
	s_addc_u32 s71, s45, 0
	s_add_i32 s72, s57, s3
	global_load_lds_dwordx4 v[226:227], off
	v_lshl_add_u64 v[226:227], s[70:71], 0, v[132:133]
	s_mov_b32 m0, s72
	s_nop 0
	global_load_lds_dwordx4 v[226:227], off
	v_lshl_add_u64 v[226:227], s[70:71], 0, v[136:137]
	s_add_i32 m0, s72, 0x2000
	s_nop 0
	global_load_lds_dwordx4 v[226:227], off
	s_waitcnt vmcnt(6)
	s_waitcnt lgkmcnt(0)
	s_barrier
; #define PG8_STAGE(bufoff, gbase, voff) do { _Pragma("unroll") for (int _i = 0; _i < 2; ++_i) \
;         __builtin_amdgcn_global_load_lds((const unsigned*)((const char*)(gbase) + (voff)[_i]), (PG8_LAS unsigned*)(lds + (bufoff) + ldsw + _i * 8192), 16, 0, 0); } while (0)
; #define PG8_LDA(dst, b, h) do { _Pragma("unroll") for (int m = 0; m < 4; ++m) _Pragma("unroll") for (int k = 0; k < 2; ++k) dst[m][k] = *(const PG8_LAS bf16x8*)(lds + PG8_SA(b, h) + aoff + m * 2048 + k * 1024); } while (0)
; #define PG8_LDB(dst, b, h) do { _Pragma("unroll") for (int n = 0; n < 2; ++n) _Pragma("unroll") for (int k = 0; k < 2; ++k) dst[n][k] = *(const PG8_LAS bf16x8*)(lds + PG8_SB(b, h) + boff + n * 2048 + k * 1024); } while (0)
; #define PG8_MMA(ai, bj, At, Bt) do { __builtin_amdgcn_s_setprio(1); _Pragma("unroll") for (int m = 0; m < 4; ++m) _Pragma("unroll") for (int n = 0; n < 2; ++n) _Pragma("unroll") for (int k = 0; k < 2; ++k) \
;         acc[ai][bj][m][n] = __builtin_amdgcn_mfma_f32_16x16x32_bf16(Bt[n][k], At[m][k], acc[ai][bj][m][n], 0, 0, 0); __builtin_amdgcn_s_setprio(0); } while (0)
; #define PG8_WAIT_V(n) asm volatile("s_waitcnt vmcnt(" #n ")" ::: "memory")
; #define PG8_WAIT_L(n) asm volatile("s_waitcnt lgkmcnt(" #n ")" ::: "memory")
; #define PG8_BAR __builtin_amdgcn_s_barrier()
; #define PG8_SCHED __builtin_amdgcn_sched_barrier(0)
; template <class Epi, class Sched, bool ALIGN_EPI = false, bool SP2 = false>
; __device__ __forceinline__ void gemm_phase(PG8_LAS unsigned char* lds, const Gemm g, const Sched& S, const Epi& E) {
;     ...
;             PG8_LDB(B0, 0, 0); PG8_LDB(B1, 0, 1); PG8_SCHED; PG8_LDA(At, 0, 0); PG8_STAGE(PG8_SA(1, 1), a1 + hstep, voffA);
;             PG8_WAIT_V(8); PG8_WAIT_L(0); PG8_BAR; PG8_MMA(0, 0, At, B0); PG8_MMA(0, 1, At, B1); PG8_BAR; PG8_SCHED;
;             PG8_LDA(At, 0, 1); PG8_STAGE(PG8_SB(0, 0), b2, voffB); PG8_STAGE(PG8_SB(0, 1), b2 + hstep, voffB); PG8_STAGE(PG8_SA(0, 0), a2, voffA);
;             PG8_WAIT_V(8); PG8_WAIT_L(0); PG8_BAR; PG8_MMA(1, 0, At, B0); PG8_MMA(1, 1, At, B1); PG8_BAR; PG8_SCHED;
;             PG8_LDB(B0, 1, 0); PG8_LDB(B1, 1, 1); PG8_SCHED; PG8_LDA(At, 1, 0); PG8_STAGE(PG8_SA(0, 1), a2 + hstep, voffA);
;             PG8_WAIT_V(8); PG8_WAIT_L(0); PG8_BAR; PG8_MMA(0, 0, At, B0); PG8_MMA(0, 1, At, B1); PG8_BAR; PG8_SCHED;
	s_setprio 1
	s_waitcnt lgkmcnt(0)
	v_mfma_f32_16x16x32_bf16 v[62:65], v[148:151], v[188:191], v[62:65]
	v_mfma_f32_16x16x32_bf16 v[58:61], v[162:165], v[188:191], v[58:61]
	v_mfma_f32_16x16x32_bf16 v[46:49], v[148:151], v[202:205], v[46:49]
	v_mfma_f32_16x16x32_bf16 v[42:45], v[162:165], v[202:205], v[42:45]
	v_mfma_f32_16x16x32_bf16 v[30:33], v[148:151], v[210:213], v[30:33]
	v_mfma_f32_16x16x32_bf16 v[26:29], v[162:165], v[210:213], v[26:29]
	v_mfma_f32_16x16x32_bf16 v[14:17], v[148:151], v[218:221], v[14:17]
	v_mfma_f32_16x16x32_bf16 v[10:13], v[162:165], v[218:221], v[10:13]
	v_mfma_f32_16x16x32_bf16 v[62:65], v[158:161], v[198:201], v[62:65]
	v_mfma_f32_16x16x32_bf16 v[58:61], v[166:169], v[198:201], v[58:61]
	v_mfma_f32_16x16x32_bf16 v[46:49], v[158:161], v[206:209], v[46:49]
	v_mfma_f32_16x16x32_bf16 v[42:45], v[166:169], v[206:209], v[42:45]
	v_mfma_f32_16x16x32_bf16 v[30:33], v[158:161], v[214:217], v[30:33]
	v_mfma_f32_16x16x32_bf16 v[26:29], v[166:169], v[214:217], v[26:29]
	v_mfma_f32_16x16x32_bf16 v[14:17], v[158:161], v[222:225], v[14:17]
	v_mfma_f32_16x16x32_bf16 v[10:13], v[166:169], v[222:225], v[10:13]
	s_setprio 0
	s_setprio 1
	v_mfma_f32_16x16x32_bf16 v[54:57], v[170:173], v[188:191], v[54:57]
	v_mfma_f32_16x16x32_bf16 v[50:53], v[180:183], v[188:191], v[50:53]
	v_mfma_f32_16x16x32_bf16 v[38:41], v[170:173], v[202:205], v[38:41]
	v_mfma_f32_16x16x32_bf16 v[34:37], v[180:183], v[202:205], v[34:37]
	v_mfma_f32_16x16x32_bf16 v[22:25], v[170:173], v[210:213], v[22:25]
	v_mfma_f32_16x16x32_bf16 v[18:21], v[180:183], v[210:213], v[18:21]
	v_mfma_f32_16x16x32_bf16 v[6:9], v[170:173], v[218:221], v[6:9]
	v_mfma_f32_16x16x32_bf16 v[2:5], v[180:183], v[218:221], v[2:5]
	v_mfma_f32_16x16x32_bf16 v[54:57], v[174:177], v[198:201], v[54:57]
	v_mfma_f32_16x16x32_bf16 v[50:53], v[184:187], v[198:201], v[50:53]
	v_mfma_f32_16x16x32_bf16 v[38:41], v[174:177], v[206:209], v[38:41]
	v_mfma_f32_16x16x32_bf16 v[34:37], v[184:187], v[206:209], v[34:37]
	v_mfma_f32_16x16x32_bf16 v[22:25], v[174:177], v[214:217], v[22:25]
	v_mfma_f32_16x16x32_bf16 v[18:21], v[184:187], v[214:217], v[18:21]
	v_mfma_f32_16x16x32_bf16 v[6:9], v[174:177], v[222:225], v[6:9]
	v_mfma_f32_16x16x32_bf16 v[2:5], v[184:187], v[222:225], v[2:5]
	s_setprio 0
	s_barrier
	s_add_i32 s70, 0, 0x18000
	v_add_u32_e32 v138, s70, v1
	s_add_i32 s71, 0, 0x1c000
	ds_read_b128 v[148:151], v138
	ds_read_b128 v[158:161], v138 offset:1024
	ds_read_b128 v[162:165], v138 offset:2048
	ds_read_b128 v[166:169], v138 offset:3072
	v_add_u32_e32 v138, s71, v1
	ds_read_b128 v[170:173], v138
	ds_read_b128 v[174:177], v138 offset:1024
	ds_read_b128 v[180:183], v138 offset:2048
	ds_read_b128 v[184:187], v138 offset:3072
	v_lshl_add_u64 v[226:227], s[46:47], 0, v[130:131]
	s_mov_b32 m0, s28
	s_nop 0
	global_load_lds_dwordx4 v[226:227], off
	v_lshl_add_u64 v[226:227], s[46:47], 0, v[134:135]
	s_mov_b32 m0, s29
	s_nop 0
	global_load_lds_dwordx4 v[226:227], off
	s_add_u32 s46, s46, 0x4000
	s_addc_u32 s47, s47, 0
	s_mov_b32 m0, s30
	v_lshl_add_u64 v[226:227], s[46:47], 0, v[130:131]
	ds_read_b128 v[188:191], v155 offset:32768
	ds_read_b128 v[198:201], v155 offset:33792
	ds_read_b128 v[202:205], v155 offset:34816
	ds_read_b128 v[206:209], v155 offset:35840
	ds_read_b128 v[210:213], v155 offset:36864
	ds_read_b128 v[214:217], v155 offset:37888
	ds_read_b128 v[218:221], v155 offset:38912
	ds_read_b128 v[222:225], v155 offset:39936
	global_load_lds_dwordx4 v[226:227], off
	v_lshl_add_u64 v[226:227], s[46:47], 0, v[134:135]
	s_mov_b32 m0, s31
	s_nop 0
	global_load_lds_dwordx4 v[226:227], off
	s_waitcnt vmcnt(8)
	s_waitcnt lgkmcnt(0)
	s_barrier
; #define PG8_STAGE(bufoff, gbase, voff) do { _Pragma("unroll") for (int _i = 0; _i < 2; ++_i) \
;         __builtin_amdgcn_global_load_lds((const unsigned*)((const char*)(gbase) + (voff)[_i]), (PG8_LAS unsigned*)(lds + (bufoff) + ldsw + _i * 8192), 16, 0, 0); } while (0)
; #define PG8_LDA(dst, b, h) do { _Pragma("unroll") for (int m = 0; m < 4; ++m) _Pragma("unroll") for (int k = 0; k < 2; ++k) dst[m][k] = *(const PG8_LAS bf16x8*)(lds + PG8_SA(b, h) + aoff + m * 2048 + k * 1024); } while (0)
; #define PG8_LDB(dst, b, h) do { _Pragma("unroll") for (int n = 0; n < 2; ++n) _Pragma("unroll") for (int k = 0; k < 2; ++k) dst[n][k] = *(const PG8_LAS bf16x8*)(lds + PG8_SB(b, h) + boff + n * 2048 + k * 1024); } while (0)
; #define PG8_MMA(ai, bj, At, Bt) do { __builtin_amdgcn_s_setprio(1); _Pragma("unroll") for (int m = 0; m < 4; ++m) _Pragma("unroll") for (int n = 0; n < 2; ++n) _Pragma("unroll") for (int k = 0; k < 2; ++k) \
;         acc[ai][bj][m][n] = __builtin_amdgcn_mfma_f32_16x16x32_bf16(Bt[n][k], At[m][k], acc[ai][bj][m][n], 0, 0, 0); __builtin_amdgcn_s_setprio(0); } while (0)
; #define PG8_BAR __builtin_amdgcn_s_barrier()
; template <class Epi, class Sched, bool ALIGN_EPI = false, bool SP2 = false>
; __device__ __forceinline__ void gemm_phase(PG8_LAS unsigned char* lds, const Gemm g, const Sched& S, const Epi& E) {
;     ...
;             if constexpr (SP2) {
;             PG8_LDB(B0, 0, 0); PG8_LDB(B1, 0, 1); PG8_SCHED; PG8_LDA(At, 0, 0); PG8_STAGE(PG8_SA(1, 1), a1 + hstep, voffA);
;             PG8_WAIT_V(8); PG8_WAIT_L(0); PG8_BAR; PG8_MMA(0, 0, At, B0); PG8_MMA(0, 1, At, B1); PG8_BAR; PG8_SCHED;
;             PG8_LDA(At, 0, 1); PG8_STAGE(PG8_SB(0, 0), b2, voffB); PG8_STAGE(PG8_SB(0, 1), b2 + hstep, voffB); PG8_STAGE(PG8_SA(0, 0), a2, voffA);
;             PG8_WAIT_V(8); PG8_WAIT_L(0); PG8_BAR; PG8_MMA(1, 0, At, B0); PG8_MMA(1, 1, At, B1); PG8_BAR; PG8_SCHED;
;             PG8_LDB(B0, 1, 0); PG8_LDB(B1, 1, 1); PG8_SCHED; PG8_LDA(At, 1, 0); PG8_STAGE(PG8_SA(0, 1), a2 + hstep, voffA);
;             PG8_WAIT_V(8); PG8_WAIT_L(0); PG8_BAR; PG8_MMA(0, 0, At, B0); PG8_MMA(0, 1, At, B1); PG8_BAR; PG8_SCHED;
;             PG8_LDA(At, 1, 1); PG8_STAGE(PG8_SB(1, 0), b3, voffB); PG8_STAGE(PG8_SB(1, 1), b3 + hstep, voffB); PG8_STAGE(PG8_SA(1, 0), a3, voffA);
;             PG8_WAIT_V(8); PG8_WAIT_L(0); PG8_BAR; PG8_MMA(1, 0, At, B0); PG8_MMA(1, 1, At, B1); PG8_BAR; PG8_SCHED;
	s_setprio 1
	s_waitcnt lgkmcnt(0)
	v_mfma_f32_16x16x32_bf16 v[126:129], v[148:151], v[188:191], v[126:129]
	v_mfma_f32_16x16x32_bf16 v[122:125], v[162:165], v[188:191], v[122:125]
	v_mfma_f32_16x16x32_bf16 v[110:113], v[148:151], v[202:205], v[110:113]
	v_mfma_f32_16x16x32_bf16 v[106:109], v[162:165], v[202:205], v[106:109]
	v_mfma_f32_16x16x32_bf16 v[94:97], v[148:151], v[210:213], v[94:97]
	v_mfma_f32_16x16x32_bf16 v[90:93], v[162:165], v[210:213], v[90:93]
	v_mfma_f32_16x16x32_bf16 v[78:81], v[148:151], v[218:221], v[78:81]
	v_mfma_f32_16x16x32_bf16 v[74:77], v[162:165], v[218:221], v[74:77]
	v_mfma_f32_16x16x32_bf16 v[126:129], v[158:161], v[198:201], v[126:129]
	v_mfma_f32_16x16x32_bf16 v[122:125], v[166:169], v[198:201], v[122:125]
	v_mfma_f32_16x16x32_bf16 v[110:113], v[158:161], v[206:209], v[110:113]
	v_mfma_f32_16x16x32_bf16 v[106:109], v[166:169], v[206:209], v[106:109]
	v_mfma_f32_16x16x32_bf16 v[94:97], v[158:161], v[214:217], v[94:97]
	v_mfma_f32_16x16x32_bf16 v[90:93], v[166:169], v[214:217], v[90:93]
	v_mfma_f32_16x16x32_bf16 v[78:81], v[158:161], v[222:225], v[78:81]
	v_mfma_f32_16x16x32_bf16 v[74:77], v[166:169], v[222:225], v[74:77]
	s_setprio 0
	s_setprio 1
	v_mfma_f32_16x16x32_bf16 v[118:121], v[170:173], v[188:191], v[118:121]
	v_mfma_f32_16x16x32_bf16 v[114:117], v[180:183], v[188:191], v[114:117]
	v_mfma_f32_16x16x32_bf16 v[102:105], v[170:173], v[202:205], v[102:105]
	v_mfma_f32_16x16x32_bf16 v[98:101], v[180:183], v[202:205], v[98:101]
	v_mfma_f32_16x16x32_bf16 v[86:89], v[170:173], v[210:213], v[86:89]
	v_mfma_f32_16x16x32_bf16 v[82:85], v[180:183], v[210:213], v[82:85]
	v_mfma_f32_16x16x32_bf16 v[70:73], v[170:173], v[218:221], v[70:73]
	v_mfma_f32_16x16x32_bf16 v[66:69], v[180:183], v[218:221], v[66:69]
	v_mfma_f32_16x16x32_bf16 v[118:121], v[174:177], v[198:201], v[118:121]
	v_mfma_f32_16x16x32_bf16 v[114:117], v[184:187], v[198:201], v[114:117]
	v_mfma_f32_16x16x32_bf16 v[102:105], v[174:177], v[206:209], v[102:105]
	v_mfma_f32_16x16x32_bf16 v[98:101], v[184:187], v[206:209], v[98:101]
	v_mfma_f32_16x16x32_bf16 v[86:89], v[174:177], v[214:217], v[86:89]
	v_mfma_f32_16x16x32_bf16 v[82:85], v[184:187], v[214:217], v[82:85]
	v_mfma_f32_16x16x32_bf16 v[70:73], v[174:177], v[222:225], v[70:73]
	v_mfma_f32_16x16x32_bf16 v[66:69], v[184:187], v[222:225], v[66:69]
	s_setprio 0
	s_barrier
	s_add_u32 s46, s44, 0x8000
	s_addc_u32 s47, s45, 0
	s_add_i32 s70, s70, s3
	v_lshl_add_u64 v[226:227], s[46:47], 0, v[132:133]
	s_mov_b32 m0, s70
	ds_read_b128 v[188:191], v155 offset:49152
	ds_read_b128 v[198:201], v155 offset:50176
	ds_read_b128 v[202:205], v155 offset:51200
	ds_read_b128 v[206:209], v155 offset:52224
	ds_read_b128 v[210:213], v155 offset:53248
	ds_read_b128 v[214:217], v155 offset:54272
	ds_read_b128 v[218:221], v155 offset:55296
	ds_read_b128 v[222:225], v155 offset:56320
	global_load_lds_dwordx4 v[226:227], off
	s_add_i32 m0, s70, 0x2000
	s_add_u32 s44, s44, 0xc000
	v_lshl_add_u64 v[226:227], s[46:47], 0, v[136:137]
	s_addc_u32 s45, s45, 0
	s_add_i32 s46, s71, s3
	global_load_lds_dwordx4 v[226:227], off
	v_lshl_add_u64 v[226:227], s[44:45], 0, v[132:133]
	s_mov_b32 m0, s46
	s_nop 0
	global_load_lds_dwordx4 v[226:227], off
	v_lshl_add_u64 v[226:227], s[44:45], 0, v[136:137]
	s_add_i32 m0, s46, 0x2000
	s_nop 0
	global_load_lds_dwordx4 v[226:227], off
	s_waitcnt vmcnt(6)
	s_waitcnt lgkmcnt(0)
	s_barrier
	s_setprio 1
	s_waitcnt lgkmcnt(0)
	v_mfma_f32_16x16x32_bf16 v[62:65], v[148:151], v[188:191], v[62:65]
	v_mfma_f32_16x16x32_bf16 v[58:61], v[162:165], v[188:191], v[58:61]
	v_mfma_f32_16x16x32_bf16 v[46:49], v[148:151], v[202:205], v[46:49]
	v_mfma_f32_16x16x32_bf16 v[42:45], v[162:165], v[202:205], v[42:45]
	v_mfma_f32_16x16x32_bf16 v[30:33], v[148:151], v[210:213], v[30:33]
	v_mfma_f32_16x16x32_bf16 v[26:29], v[162:165], v[210:213], v[26:29]
	v_mfma_f32_16x16x32_bf16 v[14:17], v[148:151], v[218:221], v[14:17]
	v_mfma_f32_16x16x32_bf16 v[10:13], v[162:165], v[218:221], v[10:13]
	v_mfma_f32_16x16x32_bf16 v[62:65], v[158:161], v[198:201], v[62:65]
	v_mfma_f32_16x16x32_bf16 v[58:61], v[166:169], v[198:201], v[58:61]
	v_mfma_f32_16x16x32_bf16 v[46:49], v[158:161], v[206:209], v[46:49]
	v_mfma_f32_16x16x32_bf16 v[42:45], v[166:169], v[206:209], v[42:45]
	v_mfma_f32_16x16x32_bf16 v[30:33], v[158:161], v[214:217], v[30:33]
	v_mfma_f32_16x16x32_bf16 v[26:29], v[166:169], v[214:217], v[26:29]
	v_mfma_f32_16x16x32_bf16 v[14:17], v[158:161], v[222:225], v[14:17]
	v_mfma_f32_16x16x32_bf16 v[10:13], v[166:169], v[222:225], v[10:13]
	s_setprio 0
	s_setprio 1
	v_mfma_f32_16x16x32_bf16 v[54:57], v[170:173], v[188:191], v[54:57]
	v_mfma_f32_16x16x32_bf16 v[50:53], v[180:183], v[188:191], v[50:53]
	v_mfma_f32_16x16x32_bf16 v[38:41], v[170:173], v[202:205], v[38:41]
	v_mfma_f32_16x16x32_bf16 v[34:37], v[180:183], v[202:205], v[34:37]
	v_mfma_f32_16x16x32_bf16 v[22:25], v[170:173], v[210:213], v[22:25]
	v_mfma_f32_16x16x32_bf16 v[18:21], v[180:183], v[210:213], v[18:21]
	v_mfma_f32_16x16x32_bf16 v[6:9], v[170:173], v[218:221], v[6:9]
	v_mfma_f32_16x16x32_bf16 v[2:5], v[180:183], v[218:221], v[2:5]
	v_mfma_f32_16x16x32_bf16 v[54:57], v[174:177], v[198:201], v[54:57]
	v_mfma_f32_16x16x32_bf16 v[50:53], v[184:187], v[198:201], v[50:53]
	v_mfma_f32_16x16x32_bf16 v[38:41], v[174:177], v[206:209], v[38:41]
	v_mfma_f32_16x16x32_bf16 v[34:37], v[184:187], v[206:209], v[34:37]
	v_mfma_f32_16x16x32_bf16 v[22:25], v[174:177], v[214:217], v[22:25]
	v_mfma_f32_16x16x32_bf16 v[18:21], v[184:187], v[214:217], v[18:21]
	v_mfma_f32_16x16x32_bf16 v[6:9], v[174:177], v[222:225], v[6:9]
	v_mfma_f32_16x16x32_bf16 v[2:5], v[184:187], v[222:225], v[2:5]
	s_setprio 0
	s_barrier
	s_add_i32 s69, s69, 2
	s_add_u32 s40, s40, 0x10000
	s_addc_u32 s41, s41, 0
	s_add_u32 s67, s67, 0x10000
	s_addc_u32 s68, s68, 0
	s_cmp_gt_u32 s69, 61
	s_cbranch_scc0 .LBB0_840
	s_and_b64 vcc, exec, s[14:15]
	s_cbranch_vccz .LBB0_843
	s_barrier

; #define PG8_STAGE(bufoff, gbase, voff) do { _Pragma("unroll") for (int _i = 0; _i < 2; ++_i) \
;         __builtin_amdgcn_global_load_lds((const unsigned*)((const char*)(gbase) + (voff)[_i]), (PG8_LAS unsigned*)(lds + (bufoff) + ldsw + _i * 8192), 16, 0, 0); } while (0)
; #define PG8_LDA(dst, b, h) do { _Pragma("unroll") for (int m = 0; m < 4; ++m) _Pragma("unroll") for (int k = 0; k < 2; ++k) dst[m][k] = *(const PG8_LAS bf16x8*)(lds + PG8_SA(b, h) + aoff + m * 2048 + k * 1024); } while (0)
; #define PG8_LDB(dst, b, h) do { _Pragma("unroll") for (int n = 0; n < 2; ++n) _Pragma("unroll") for (int k = 0; k < 2; ++k) dst[n][k] = *(const PG8_LAS bf16x8*)(lds + PG8_SB(b, h) + boff + n * 2048 + k * 1024); } while (0)
; template <class Epi, class Sched, bool ALIGN_EPI = false, bool SP2 = false>
; __device__ __forceinline__ void gemm_phase(PG8_LAS unsigned char* lds, const Gemm g, const Sched& S, const Epi& E) {
;     ...
;         for (; t < tend; t += 2) {
;             const bool last = (t == nt - 2);
;             const char* a1 = cA + (size_t)(t + 1) * kstep;
;             const char* a2 = last ? nA : cA + (size_t)(t + 2) * kstep; const char* b2 = last ? nB : cB + (size_t)(t + 2) * kstep;
;             const char* a3 = a2 + kstep; const char* b3 = b2 + kstep;
;             if (last && has_next) S.a_ready(nxt);
;             if constexpr (SP2) {
;             PG8_LDB(B0, 0, 0); PG8_LDB(B1, 0, 1); PG8_SCHED; PG8_LDA(At, 0, 0); PG8_STAGE(PG8_SA(1, 1), a1 + hstep, voffA);
;             PG8_WAIT_V(8); PG8_WAIT_L(0); PG8_BAR; PG8_MMA(0, 0, At, B0); PG8_MMA(0, 1, At, B1); PG8_BAR; PG8_SCHED;
;             PG8_LDA(At, 0, 1); PG8_STAGE(PG8_SB(0, 0), b2, voffB); PG8_STAGE(PG8_SB(0, 1), b2 + hstep, voffB); PG8_STAGE(PG8_SA(0, 0), a2, voffA);
;             PG8_WAIT_V(8); PG8_WAIT_L(0); PG8_BAR; PG8_MMA(1, 0, At, B0); PG8_MMA(1, 1, At, B1); PG8_BAR; PG8_SCHED;
;             PG8_LDB(B0, 1, 0); PG8_LDB(B1, 1, 1); PG8_SCHED; PG8_LDA(At, 1, 0); PG8_STAGE(PG8_SA(0, 1), a2 + hstep, voffA);
;             PG8_WAIT_V(8); PG8_WAIT_L(0); PG8_BAR; PG8_MMA(0, 0, At, B0); PG8_MMA(0, 1, At, B1); PG8_BAR; PG8_SCHED;
;             PG8_LDA(At, 1, 1); PG8_STAGE(PG8_SB(1, 0), b3, voffB); PG8_STAGE(PG8_SB(1, 1), b3 + hstep, voffB); PG8_STAGE(PG8_SA(1, 0), a3, voffA);
;             PG8_WAIT_V(8); PG8_WAIT_L(0); PG8_BAR; PG8_MMA(1, 0, At, B0); PG8_MMA(1, 1, At, B1); PG8_BAR; PG8_SCHED;
.LBB0_939:
	s_or_b32 s24, s59, 1
	s_lshl_b64 s[62:63], s[24:25], 15
	s_add_i32 s24, s59, 2
	ds_read_b128 v[156:159], v193
	ds_read_b128 v[160:163], v193 offset:1024
	ds_read_b128 v[196:199], v193 offset:2048
	ds_read_b128 v[200:203], v193 offset:3072
	ds_read_b128 v[204:207], v194
	ds_read_b128 v[208:211], v194 offset:1024
	ds_read_b128 v[212:215], v194 offset:2048
	ds_read_b128 v[216:219], v194 offset:3072
	s_lshl_b64 s[8:9], s[24:25], 15
	s_add_u32 s44, s6, s8
	s_addc_u32 s45, s7, s9
	s_cmpk_eq_i32 s59, 0xaa
	s_cselect_b32 s46, s58, s44
	s_cselect_b32 s47, s56, s45
	s_cselect_b32 s44, 0, s8
	s_cselect_b32 s45, 0, s9
	s_add_u32 s8, s46, 0x8000
	s_addc_u32 s9, s47, 0
	s_add_u32 s44, s14, s44
	s_addc_u32 s45, s15, s45
	s_add_u32 s62, s6, s62
	s_addc_u32 s63, s7, s63
	s_add_u32 s62, s62, 0x4000
	s_addc_u32 s63, s63, 0
	s_sub_u32 s8, s62, 0x4000
	s_subb_u32 s9, s63, 0
	v_lshl_add_u64 v[164:165], s[8:9], 0, v[130:131]
	s_mov_b32 m0, s51
	s_nop 0
	global_load_lds_dwordx4 v[164:165], off
	v_lshl_add_u64 v[164:165], s[8:9], 0, v[134:135]
	s_mov_b32 m0, s57
	s_nop 0
	global_load_lds_dwordx4 v[164:165], off
	v_lshl_add_u64 v[164:165], s[62:63], 0, v[130:131]
	s_add_i32 m0, s30, 0xc000
	ds_read_b128 v[220:223], v186
	ds_read_b128 v[224:227], v186 offset:1024
	ds_read_b128 v[228:231], v186 offset:2048
	ds_read_b128 v[232:235], v186 offset:3072
	ds_read_b128 v[236:239], v186 offset:4096
	ds_read_b128 v[240:243], v186 offset:5120
	ds_read_b128 v[244:247], v186 offset:6144
	ds_read_b128 v[248:251], v186 offset:7168
	global_load_lds_dwordx4 v[164:165], off
	v_lshl_add_u64 v[164:165], s[62:63], 0, v[134:135]
	s_add_i32 m0, s30, 0xe000
	s_nop 0
	global_load_lds_dwordx4 v[164:165], off
	s_waitcnt vmcnt(8)
	s_waitcnt lgkmcnt(0)
	s_barrier
	s_setprio 1
	s_waitcnt lgkmcnt(0)
	v_mfma_f32_16x16x32_bf16 v[126:129], v[156:159], v[220:223], v[126:129]
	v_mfma_f32_16x16x32_bf16 v[122:125], v[196:199], v[220:223], v[122:125]
	v_mfma_f32_16x16x32_bf16 v[110:113], v[156:159], v[228:231], v[110:113]
	v_mfma_f32_16x16x32_bf16 v[106:109], v[196:199], v[228:231], v[106:109]
	v_mfma_f32_16x16x32_bf16 v[94:97], v[156:159], v[236:239], v[94:97]
	v_mfma_f32_16x16x32_bf16 v[90:93], v[196:199], v[236:239], v[90:93]
	v_mfma_f32_16x16x32_bf16 v[78:81], v[156:159], v[244:247], v[78:81]
	v_mfma_f32_16x16x32_bf16 v[74:77], v[196:199], v[244:247], v[74:77]
	v_mfma_f32_16x16x32_bf16 v[126:129], v[160:163], v[224:227], v[126:129]
	v_mfma_f32_16x16x32_bf16 v[122:125], v[200:203], v[224:227], v[122:125]
	v_mfma_f32_16x16x32_bf16 v[110:113], v[160:163], v[232:235], v[110:113]
	v_mfma_f32_16x16x32_bf16 v[106:109], v[200:203], v[232:235], v[106:109]
	v_mfma_f32_16x16x32_bf16 v[94:97], v[160:163], v[240:243], v[94:97]
	v_mfma_f32_16x16x32_bf16 v[90:93], v[200:203], v[240:243], v[90:93]
	v_mfma_f32_16x16x32_bf16 v[78:81], v[160:163], v[248:251], v[78:81]
	v_mfma_f32_16x16x32_bf16 v[74:77], v[200:203], v[248:251], v[74:77]
	s_setprio 0
	s_setprio 1
	v_mfma_f32_16x16x32_bf16 v[118:121], v[204:207], v[220:223], v[118:121]
	v_mfma_f32_16x16x32_bf16 v[114:117], v[212:215], v[220:223], v[114:117]
	v_mfma_f32_16x16x32_bf16 v[102:105], v[204:207], v[228:231], v[102:105]
	v_mfma_f32_16x16x32_bf16 v[98:101], v[212:215], v[228:231], v[98:101]
	v_mfma_f32_16x16x32_bf16 v[86:89], v[204:207], v[236:239], v[86:89]
	v_mfma_f32_16x16x32_bf16 v[82:85], v[212:215], v[236:239], v[82:85]
	v_mfma_f32_16x16x32_bf16 v[70:73], v[204:207], v[244:247], v[70:73]
	v_mfma_f32_16x16x32_bf16 v[66:69], v[212:215], v[244:247], v[66:69]
	v_mfma_f32_16x16x32_bf16 v[118:121], v[208:211], v[224:227], v[118:121]
	v_mfma_f32_16x16x32_bf16 v[114:117], v[216:219], v[224:227], v[114:117]
	v_mfma_f32_16x16x32_bf16 v[102:105], v[208:211], v[232:235], v[102:105]
	v_mfma_f32_16x16x32_bf16 v[98:101], v[216:219], v[232:235], v[98:101]
	v_mfma_f32_16x16x32_bf16 v[86:89], v[208:211], v[240:243], v[86:89]
	v_mfma_f32_16x16x32_bf16 v[82:85], v[216:219], v[240:243], v[82:85]
	v_mfma_f32_16x16x32_bf16 v[70:73], v[208:211], v[248:251], v[70:73]
	v_mfma_f32_16x16x32_bf16 v[66:69], v[216:219], v[248:251], v[66:69]
	s_setprio 0
	s_barrier
	s_add_i32 s62, s67, s29
	v_lshl_add_u64 v[164:165], s[44:45], 0, v[132:133]
	s_mov_b32 m0, s62
	ds_read_b128 v[220:223], v186 offset:16384
	ds_read_b128 v[224:227], v186 offset:17408
	ds_read_b128 v[228:231], v186 offset:18432
	ds_read_b128 v[232:235], v186 offset:19456
	ds_read_b128 v[236:239], v186 offset:20480
	ds_read_b128 v[240:243], v186 offset:21504
	ds_read_b128 v[244:247], v186 offset:22528
	ds_read_b128 v[248:251], v186 offset:23552
	global_load_lds_dwordx4 v[164:165], off
	s_add_i32 m0, s62, 0x2000
	s_add_u32 s62, s44, 0x4000
	v_lshl_add_u64 v[164:165], s[44:45], 0, v[136:137]
	s_addc_u32 s63, s45, 0
	s_add_i32 s72, s68, s29
	global_load_lds_dwordx4 v[164:165], off
	v_lshl_add_u64 v[164:165], s[62:63], 0, v[132:133]
	s_mov_b32 m0, s72
	s_nop 0
	global_load_lds_dwordx4 v[164:165], off
	v_lshl_add_u64 v[164:165], s[62:63], 0, v[136:137]
	s_add_i32 m0, s72, 0x2000
	s_nop 0
	global_load_lds_dwordx4 v[164:165], off
	s_waitcnt vmcnt(6)
	s_waitcnt lgkmcnt(0)
	s_barrier
; #define PG8_STAGE(bufoff, gbase, voff) do { _Pragma("unroll") for (int _i = 0; _i < 2; ++_i) \
;         __builtin_amdgcn_global_load_lds((const unsigned*)((const char*)(gbase) + (voff)[_i]), (PG8_LAS unsigned*)(lds + (bufoff) + ldsw + _i * 8192), 16, 0, 0); } while (0)
; #define PG8_LDA(dst, b, h) do { _Pragma("unroll") for (int m = 0; m < 4; ++m) _Pragma("unroll") for (int k = 0; k < 2; ++k) dst[m][k] = *(const PG8_LAS bf16x8*)(lds + PG8_SA(b, h) + aoff + m * 2048 + k * 1024); } while (0)
; #define PG8_LDB(dst, b, h) do { _Pragma("unroll") for (int n = 0; n < 2; ++n) _Pragma("unroll") for (int k = 0; k < 2; ++k) dst[n][k] = *(const PG8_LAS bf16x8*)(lds + PG8_SB(b, h) + boff + n * 2048 + k * 1024); } while (0)
; #define PG8_MMA(ai, bj, At, Bt) do { __builtin_amdgcn_s_setprio(1); _Pragma("unroll") for (int m = 0; m < 4; ++m) _Pragma("unroll") for (int n = 0; n < 2; ++n) _Pragma("unroll") for (int k = 0; k < 2; ++k) \
;         acc[ai][bj][m][n] = __builtin_amdgcn_mfma_f32_16x16x32_bf16(Bt[n][k], At[m][k], acc[ai][bj][m][n], 0, 0, 0); __builtin_amdgcn_s_setprio(0); } while (0)
; #define PG8_WAIT_V(n) asm volatile("s_waitcnt vmcnt(" #n ")" ::: "memory")
; #define PG8_WAIT_L(n) asm volatile("s_waitcnt lgkmcnt(" #n ")" ::: "memory")
; #define PG8_BAR __builtin_amdgcn_s_barrier()
; #define PG8_SCHED __builtin_amdgcn_sched_barrier(0)
; template <class Epi, class Sched, bool ALIGN_EPI = false, bool SP2 = false>
; __device__ __forceinline__ void gemm_phase(PG8_LAS unsigned char* lds, const Gemm g, const Sched& S, const Epi& E) {
;     ...
;             PG8_WAIT_V(8); PG8_WAIT_L(0); PG8_BAR; PG8_MMA(1, 0, At, B0); PG8_MMA(1, 1, At, B1); PG8_BAR; PG8_SCHED;
;             PG8_LDB(B0, 1, 0); PG8_LDB(B1, 1, 1); PG8_SCHED; PG8_LDA(At, 1, 0); PG8_STAGE(PG8_SA(0, 1), a2 + hstep, voffA);
	s_setprio 1
	s_waitcnt lgkmcnt(0)
	v_mfma_f32_16x16x32_bf16 v[62:65], v[156:159], v[220:223], v[62:65]
	v_mfma_f32_16x16x32_bf16 v[58:61], v[196:199], v[220:223], v[58:61]
	v_mfma_f32_16x16x32_bf16 v[46:49], v[156:159], v[228:231], v[46:49]
	v_mfma_f32_16x16x32_bf16 v[42:45], v[196:199], v[228:231], v[42:45]
	v_mfma_f32_16x16x32_bf16 v[30:33], v[156:159], v[236:239], v[30:33]
	v_mfma_f32_16x16x32_bf16 v[26:29], v[196:199], v[236:239], v[26:29]
	v_mfma_f32_16x16x32_bf16 v[14:17], v[156:159], v[244:247], v[14:17]
	v_mfma_f32_16x16x32_bf16 v[10:13], v[196:199], v[244:247], v[10:13]
	v_mfma_f32_16x16x32_bf16 v[62:65], v[160:163], v[224:227], v[62:65]
	v_mfma_f32_16x16x32_bf16 v[58:61], v[200:203], v[224:227], v[58:61]
	v_mfma_f32_16x16x32_bf16 v[46:49], v[160:163], v[232:235], v[46:49]
	v_mfma_f32_16x16x32_bf16 v[42:45], v[200:203], v[232:235], v[42:45]
	v_mfma_f32_16x16x32_bf16 v[30:33], v[160:163], v[240:243], v[30:33]
	v_mfma_f32_16x16x32_bf16 v[26:29], v[200:203], v[240:243], v[26:29]
	v_mfma_f32_16x16x32_bf16 v[14:17], v[160:163], v[248:251], v[14:17]
	v_mfma_f32_16x16x32_bf16 v[10:13], v[200:203], v[248:251], v[10:13]
	s_setprio 0
	s_setprio 1
	v_mfma_f32_16x16x32_bf16 v[54:57], v[204:207], v[220:223], v[54:57]
	v_mfma_f32_16x16x32_bf16 v[50:53], v[212:215], v[220:223], v[50:53]
	v_mfma_f32_16x16x32_bf16 v[38:41], v[204:207], v[228:231], v[38:41]
	v_mfma_f32_16x16x32_bf16 v[34:37], v[212:215], v[228:231], v[34:37]
	v_mfma_f32_16x16x32_bf16 v[22:25], v[204:207], v[236:239], v[22:25]
	v_mfma_f32_16x16x32_bf16 v[18:21], v[212:215], v[236:239], v[18:21]
	v_mfma_f32_16x16x32_bf16 v[6:9], v[204:207], v[244:247], v[6:9]
	v_mfma_f32_16x16x32_bf16 v[2:5], v[212:215], v[244:247], v[2:5]
	v_mfma_f32_16x16x32_bf16 v[54:57], v[208:211], v[224:227], v[54:57]
	v_mfma_f32_16x16x32_bf16 v[50:53], v[216:219], v[224:227], v[50:53]
	v_mfma_f32_16x16x32_bf16 v[38:41], v[208:211], v[232:235], v[38:41]
	v_mfma_f32_16x16x32_bf16 v[34:37], v[216:219], v[232:235], v[34:37]
	v_mfma_f32_16x16x32_bf16 v[22:25], v[208:211], v[240:243], v[22:25]
	v_mfma_f32_16x16x32_bf16 v[18:21], v[216:219], v[240:243], v[18:21]
	v_mfma_f32_16x16x32_bf16 v[6:9], v[208:211], v[248:251], v[6:9]
	v_mfma_f32_16x16x32_bf16 v[2:5], v[216:219], v[248:251], v[2:5]
	s_setprio 0
	s_barrier
	s_add_i32 s62, 0, 0x18000
	v_add_u32_e32 v145, s62, v166
	s_add_i32 s63, 0, 0x1c000
	ds_read_b128 v[156:159], v145
	ds_read_b128 v[160:163], v145 offset:1024
	ds_read_b128 v[196:199], v145 offset:2048
	ds_read_b128 v[200:203], v145 offset:3072
	v_add_u32_e32 v145, s63, v166
	ds_read_b128 v[204:207], v145
	ds_read_b128 v[208:211], v145 offset:1024
	ds_read_b128 v[212:215], v145 offset:2048
	ds_read_b128 v[216:219], v145 offset:3072
	v_lshl_add_u64 v[164:165], s[46:47], 0, v[130:131]
	s_mov_b32 m0, s30
	s_nop 0
	global_load_lds_dwordx4 v[164:165], off
	v_lshl_add_u64 v[164:165], s[46:47], 0, v[134:135]
	s_mov_b32 m0, s31
	s_nop 0
	global_load_lds_dwordx4 v[164:165], off
	s_add_u32 s46, s46, 0x4000
	s_addc_u32 s47, s47, 0
	s_mov_b32 m0, s35
	v_lshl_add_u64 v[164:165], s[46:47], 0, v[130:131]
	ds_read_b128 v[220:223], v186 offset:32768
	ds_read_b128 v[224:227], v186 offset:33792
	ds_read_b128 v[228:231], v186 offset:34816
	ds_read_b128 v[232:235], v186 offset:35840
	ds_read_b128 v[236:239], v186 offset:36864
	ds_read_b128 v[240:243], v186 offset:37888
	ds_read_b128 v[244:247], v186 offset:38912
	ds_read_b128 v[248:251], v186 offset:39936
	global_load_lds_dwordx4 v[164:165], off
	v_lshl_add_u64 v[164:165], s[46:47], 0, v[134:135]
	s_mov_b32 m0, s48
	s_nop 0
	global_load_lds_dwordx4 v[164:165], off
	s_waitcnt vmcnt(8)
	s_waitcnt lgkmcnt(0)
	s_barrier
; #define PG8_STAGE(bufoff, gbase, voff) do { _Pragma("unroll") for (int _i = 0; _i < 2; ++_i) \
;         __builtin_amdgcn_global_load_lds((const unsigned*)((const char*)(gbase) + (voff)[_i]), (PG8_LAS unsigned*)(lds + (bufoff) + ldsw + _i * 8192), 16, 0, 0); } while (0)
; #define PG8_LDA(dst, b, h) do { _Pragma("unroll") for (int m = 0; m < 4; ++m) _Pragma("unroll") for (int k = 0; k < 2; ++k) dst[m][k] = *(const PG8_LAS bf16x8*)(lds + PG8_SA(b, h) + aoff + m * 2048 + k * 1024); } while (0)
; #define PG8_MMA(ai, bj, At, Bt) do { __builtin_amdgcn_s_setprio(1); _Pragma("unroll") for (int m = 0; m < 4; ++m) _Pragma("unroll") for (int n = 0; n < 2; ++n) _Pragma("unroll") for (int k = 0; k < 2; ++k) \
;         acc[ai][bj][m][n] = __builtin_amdgcn_mfma_f32_16x16x32_bf16(Bt[n][k], At[m][k], acc[ai][bj][m][n], 0, 0, 0); __builtin_amdgcn_s_setprio(0); } while (0)
; #define PG8_WAIT_V(n) asm volatile("s_waitcnt vmcnt(" #n ")" ::: "memory")
; #define PG8_WAIT_L(n) asm volatile("s_waitcnt lgkmcnt(" #n ")" ::: "memory")
; #define PG8_BAR __builtin_amdgcn_s_barrier()
; #define PG8_SCHED __builtin_amdgcn_sched_barrier(0)
; template <class Epi, class Sched, bool ALIGN_EPI = false, bool SP2 = false>
; __device__ __forceinline__ void gemm_phase(PG8_LAS unsigned char* lds, const Gemm g, const Sched& S, const Epi& E) {
;     ...
;             PG8_WAIT_V(8); PG8_WAIT_L(0); PG8_BAR; PG8_MMA(0, 0, At, B0); PG8_MMA(0, 1, At, B1); PG8_BAR; PG8_SCHED;
;             PG8_LDA(At, 1, 1); PG8_STAGE(PG8_SB(1, 0), b3, voffB); PG8_STAGE(PG8_SB(1, 1), b3 + hstep, voffB); PG8_STAGE(PG8_SA(1, 0), a3, voffA);
;             PG8_WAIT_V(8); PG8_WAIT_L(0); PG8_BAR; PG8_MMA(1, 0, At, B0); PG8_MMA(1, 1, At, B1); PG8_BAR; PG8_SCHED;
;     ...
;         if constexpr (ALIGN_EPI) { if (wr == 0) PG8_BAR; }
	s_setprio 1
	s_waitcnt lgkmcnt(0)
	v_mfma_f32_16x16x32_bf16 v[126:129], v[156:159], v[220:223], v[126:129]
	v_mfma_f32_16x16x32_bf16 v[122:125], v[196:199], v[220:223], v[122:125]
	v_mfma_f32_16x16x32_bf16 v[110:113], v[156:159], v[228:231], v[110:113]
	v_mfma_f32_16x16x32_bf16 v[106:109], v[196:199], v[228:231], v[106:109]
	v_mfma_f32_16x16x32_bf16 v[94:97], v[156:159], v[236:239], v[94:97]
	v_mfma_f32_16x16x32_bf16 v[90:93], v[196:199], v[236:239], v[90:93]
	v_mfma_f32_16x16x32_bf16 v[78:81], v[156:159], v[244:247], v[78:81]
	v_mfma_f32_16x16x32_bf16 v[74:77], v[196:199], v[244:247], v[74:77]
	v_mfma_f32_16x16x32_bf16 v[126:129], v[160:163], v[224:227], v[126:129]
	v_mfma_f32_16x16x32_bf16 v[122:125], v[200:203], v[224:227], v[122:125]
	v_mfma_f32_16x16x32_bf16 v[110:113], v[160:163], v[232:235], v[110:113]
	v_mfma_f32_16x16x32_bf16 v[106:109], v[200:203], v[232:235], v[106:109]
	v_mfma_f32_16x16x32_bf16 v[94:97], v[160:163], v[240:243], v[94:97]
	v_mfma_f32_16x16x32_bf16 v[90:93], v[200:203], v[240:243], v[90:93]
	v_mfma_f32_16x16x32_bf16 v[78:81], v[160:163], v[248:251], v[78:81]
	v_mfma_f32_16x16x32_bf16 v[74:77], v[200:203], v[248:251], v[74:77]
	s_setprio 0
	s_setprio 1
	v_mfma_f32_16x16x32_bf16 v[118:121], v[204:207], v[220:223], v[118:121]
	v_mfma_f32_16x16x32_bf16 v[114:117], v[212:215], v[220:223], v[114:117]
	v_mfma_f32_16x16x32_bf16 v[102:105], v[204:207], v[228:231], v[102:105]
	v_mfma_f32_16x16x32_bf16 v[98:101], v[212:215], v[228:231], v[98:101]
	v_mfma_f32_16x16x32_bf16 v[86:89], v[204:207], v[236:239], v[86:89]
	v_mfma_f32_16x16x32_bf16 v[82:85], v[212:215], v[236:239], v[82:85]
	v_mfma_f32_16x16x32_bf16 v[70:73], v[204:207], v[244:247], v[70:73]
	v_mfma_f32_16x16x32_bf16 v[66:69], v[212:215], v[244:247], v[66:69]
	v_mfma_f32_16x16x32_bf16 v[118:121], v[208:211], v[224:227], v[118:121]
	v_mfma_f32_16x16x32_bf16 v[114:117], v[216:219], v[224:227], v[114:117]
	v_mfma_f32_16x16x32_bf16 v[102:105], v[208:211], v[232:235], v[102:105]
	v_mfma_f32_16x16x32_bf16 v[98:101], v[216:219], v[232:235], v[98:101]
	v_mfma_f32_16x16x32_bf16 v[86:89], v[208:211], v[240:243], v[86:89]
	v_mfma_f32_16x16x32_bf16 v[82:85], v[216:219], v[240:243], v[82:85]
	v_mfma_f32_16x16x32_bf16 v[70:73], v[208:211], v[248:251], v[70:73]
	v_mfma_f32_16x16x32_bf16 v[66:69], v[216:219], v[248:251], v[66:69]
	s_setprio 0
	s_barrier
	s_add_u32 s46, s44, 0x8000
	s_addc_u32 s47, s45, 0
	s_add_i32 s62, s62, s29
	v_lshl_add_u64 v[164:165], s[46:47], 0, v[132:133]
	s_mov_b32 m0, s62
	ds_read_b128 v[220:223], v186 offset:49152
	ds_read_b128 v[224:227], v186 offset:50176
	ds_read_b128 v[228:231], v186 offset:51200
	ds_read_b128 v[232:235], v186 offset:52224
	ds_read_b128 v[236:239], v186 offset:53248
	ds_read_b128 v[240:243], v186 offset:54272
	ds_read_b128 v[244:247], v186 offset:55296
	ds_read_b128 v[248:251], v186 offset:56320
	global_load_lds_dwordx4 v[164:165], off
	s_add_i32 m0, s62, 0x2000
	s_add_u32 s44, s44, 0xc000
	v_lshl_add_u64 v[164:165], s[46:47], 0, v[136:137]
	s_addc_u32 s45, s45, 0
	s_add_i32 s46, s63, s29
	global_load_lds_dwordx4 v[164:165], off
	v_lshl_add_u64 v[164:165], s[44:45], 0, v[132:133]
	s_mov_b32 m0, s46
	s_nop 0
	global_load_lds_dwordx4 v[164:165], off
	v_lshl_add_u64 v[164:165], s[44:45], 0, v[136:137]
	s_add_i32 m0, s46, 0x2000
	s_nop 0
	global_load_lds_dwordx4 v[164:165], off
	s_waitcnt vmcnt(6)
	s_waitcnt lgkmcnt(0)
	s_barrier
	s_setprio 1
	s_waitcnt lgkmcnt(0)
	v_mfma_f32_16x16x32_bf16 v[62:65], v[156:159], v[220:223], v[62:65]
	v_mfma_f32_16x16x32_bf16 v[58:61], v[196:199], v[220:223], v[58:61]
	v_mfma_f32_16x16x32_bf16 v[46:49], v[156:159], v[228:231], v[46:49]
	v_mfma_f32_16x16x32_bf16 v[42:45], v[196:199], v[228:231], v[42:45]
	v_mfma_f32_16x16x32_bf16 v[30:33], v[156:159], v[236:239], v[30:33]
	v_mfma_f32_16x16x32_bf16 v[26:29], v[196:199], v[236:239], v[26:29]
	v_mfma_f32_16x16x32_bf16 v[14:17], v[156:159], v[244:247], v[14:17]
	v_mfma_f32_16x16x32_bf16 v[10:13], v[196:199], v[244:247], v[10:13]
	v_mfma_f32_16x16x32_bf16 v[62:65], v[160:163], v[224:227], v[62:65]
	v_mfma_f32_16x16x32_bf16 v[58:61], v[200:203], v[224:227], v[58:61]
	v_mfma_f32_16x16x32_bf16 v[46:49], v[160:163], v[232:235], v[46:49]
	v_mfma_f32_16x16x32_bf16 v[42:45], v[200:203], v[232:235], v[42:45]
	v_mfma_f32_16x16x32_bf16 v[30:33], v[160:163], v[240:243], v[30:33]
	v_mfma_f32_16x16x32_bf16 v[26:29], v[200:203], v[240:243], v[26:29]
	v_mfma_f32_16x16x32_bf16 v[14:17], v[160:163], v[248:251], v[14:17]
	v_mfma_f32_16x16x32_bf16 v[10:13], v[200:203], v[248:251], v[10:13]
	s_setprio 0
	s_setprio 1
	v_mfma_f32_16x16x32_bf16 v[54:57], v[204:207], v[220:223], v[54:57]
	v_mfma_f32_16x16x32_bf16 v[50:53], v[212:215], v[220:223], v[50:53]
	v_mfma_f32_16x16x32_bf16 v[38:41], v[204:207], v[228:231], v[38:41]
	v_mfma_f32_16x16x32_bf16 v[34:37], v[212:215], v[228:231], v[34:37]
	v_mfma_f32_16x16x32_bf16 v[22:25], v[204:207], v[236:239], v[22:25]
	v_mfma_f32_16x16x32_bf16 v[18:21], v[212:215], v[236:239], v[18:21]
	v_mfma_f32_16x16x32_bf16 v[6:9], v[204:207], v[244:247], v[6:9]
	v_mfma_f32_16x16x32_bf16 v[2:5], v[212:215], v[244:247], v[2:5]
	v_mfma_f32_16x16x32_bf16 v[54:57], v[208:211], v[224:227], v[54:57]
	v_mfma_f32_16x16x32_bf16 v[50:53], v[216:219], v[224:227], v[50:53]
	v_mfma_f32_16x16x32_bf16 v[38:41], v[208:211], v[232:235], v[38:41]
	v_mfma_f32_16x16x32_bf16 v[34:37], v[216:219], v[232:235], v[34:37]
	v_mfma_f32_16x16x32_bf16 v[22:25], v[208:211], v[240:243], v[22:25]
	v_mfma_f32_16x16x32_bf16 v[18:21], v[216:219], v[240:243], v[18:21]
	v_mfma_f32_16x16x32_bf16 v[6:9], v[208:211], v[248:251], v[6:9]
	v_mfma_f32_16x16x32_bf16 v[2:5], v[216:219], v[248:251], v[2:5]
	s_setprio 0
	s_barrier
	s_cmpk_gt_u32 s59, 0xa9
	s_mov_b32 s59, s24
	s_cbranch_scc0 .LBB0_939
	s_and_b64 vcc, exec, s[38:39]
	s_cbranch_vccz .LBB0_942
	s_barrier

; __global__ void __launch_bounds__(NTHR, 2) mk_fwd(Args args) {
	.amdhsa_kernel _Z6mk_fwd4Args
		.amdhsa_group_segment_fixed_size 0
		.amdhsa_private_segment_fixed_size 0
		.amdhsa_kernarg_size 432
		.amdhsa_user_sgpr_count 2
		.amdhsa_user_sgpr_dispatch_ptr 0
		.amdhsa_user_sgpr_queue_ptr 0
		.amdhsa_user_sgpr_kernarg_segment_ptr 1
		.amdhsa_user_sgpr_dispatch_id 0
		.amdhsa_user_sgpr_kernarg_preload_length 0
		.amdhsa_user_sgpr_kernarg_preload_offset 0
		.amdhsa_user_sgpr_private_segment_size 0
		.amdhsa_uses_dynamic_stack 0
		.amdhsa_enable_private_segment 0
		.amdhsa_system_sgpr_workgroup_id_x 1
		.amdhsa_system_sgpr_workgroup_id_y 0
		.amdhsa_system_sgpr_workgroup_id_z 0
		.amdhsa_system_sgpr_workgroup_info 0
		.amdhsa_system_vgpr_workitem_id 0
		.amdhsa_next_free_vgpr 256
		.amdhsa_next_free_sgpr 102
		.amdhsa_accum_offset 256
		.amdhsa_reserve_vcc 1
		.amdhsa_float_round_mode_32 0
		.amdhsa_float_round_mode_16_64 0
		.amdhsa_float_denorm_mode_32 3
		.amdhsa_float_denorm_mode_16_64 3
		.amdhsa_dx10_clamp 1
		.amdhsa_ieee_mode 1
		.amdhsa_fp16_overflow 0
		.amdhsa_tg_split 0
		.amdhsa_exception_fp_ieee_invalid_op 0
		.amdhsa_exception_fp_denorm_src 0
		.amdhsa_exception_fp_ieee_div_zero 0
		.amdhsa_exception_fp_ieee_overflow 0
		.amdhsa_exception_fp_ieee_underflow 0
		.amdhsa_exception_fp_ieee_inexact 0
		.amdhsa_exception_int_div_zero 0
	.end_amdhsa_kernel

; __global__ void __launch_bounds__(NTHR, 2) mk_fwd(Args args) {
amdhsa.kernels:
  - .agpr_count:     0
    .args:
      - .offset:         0
        .size:           176
        .value_kind:     by_value
      - .offset:         176
        .size:           4
        .value_kind:     hidden_block_count_x
      - .offset:         180
        .size:           4
        .value_kind:     hidden_block_count_y
      - .offset:         184
        .size:           4
        .value_kind:     hidden_block_count_z
      - .offset:         188
        .size:           2
        .value_kind:     hidden_group_size_x
      - .offset:         190
        .size:           2
        .value_kind:     hidden_group_size_y
      - .offset:         192
        .size:           2
        .value_kind:     hidden_group_size_z
      - .offset:         194
        .size:           2
        .value_kind:     hidden_remainder_x
      - .offset:         196
        .size:           2
        .value_kind:     hidden_remainder_y
      - .offset:         198
        .size:           2
        .value_kind:     hidden_remainder_z
      - .offset:         216
        .size:           8
        .value_kind:     hidden_global_offset_x
      - .offset:         224
        .size:           8
        .value_kind:     hidden_global_offset_y
      - .offset:         232
        .size:           8
        .value_kind:     hidden_global_offset_z
      - .offset:         240
        .size:           2
        .value_kind:     hidden_grid_dims
      - .offset:         296
        .size:           4
        .value_kind:     hidden_dynamic_lds_size
    .group_segment_fixed_size: 0
    .kernarg_segment_align: 8
    .kernarg_segment_size: 432
    .language:       OpenCL C
    .language_version:
      - 2
      - 0
    .max_flat_workgroup_size: 512
    .name:           _Z6mk_fwd4Args
    .private_segment_fixed_size: 0
    .sgpr_count:     108
    .sgpr_spill_count: 27
    .symbol:         _Z6mk_fwd4Args.kd
    .uniform_work_group_size: 1
    .uses_dynamic_stack: false
    .vgpr_count:     256
    .vgpr_spill_count: 0
    .wavefront_size: 64
